# UP GEMM: hand-written bf16-staged LDS epilogue plus next-tile k-tile-0 LDS-DMA loads issued before the epilogue; OUT/DOWN epilogues rewritten with up-front residual prefetch and DPP row sums
# speedup vs baseline: 1.0281x; 1.0090x over previous
; template <int MODE>
; DI void phase_gemm(const Params& p, int l, char* smem) {
;     ...
;   if (MODE == MODE_PROJ) { A = (const bf16_t*)(p.ws + OFF_XB); W = (const bf16_t*)(p.ws + OFF_WIN) + (size_t)l * NPROJ * DM; K = DM; NT = 11; }
;   else if (MODE == MODE_OUT) { A = (const bf16_t*)(p.ws + OFF_MIX); W = (const bf16_t*)(p.ws + OFF_WOUT) + (size_t)l * DM * DM; K = DM; NT = 4; }
;   else if (MODE == MODE_UP) { A = (const bf16_t*)(p.ws + OFF_XB); W = (const bf16_t*)(p.ws + OFF_WUP) + (size_t)l * DFF * DM; K = DM; NT = 16; }
;   else { A = (const bf16_t*)(p.ws + OFF_U); W = (const bf16_t*)(p.ws + OFF_WDN) + (size_t)l * DM * DFF; K = DFF; NT = 4; }
; __global__ void __launch_bounds__(512, 2) mega(Params p) {
;     ...
;       const int l = (ph - 1) / 6, k = (ph - 1) % 6;
;       if (k == 0) phase_gemm<MODE_PROJ>(p, l, smem);
;       else if (k == 1) phase_cmp(p, l, smem);
;       else if (k == 2) phase_attn(p, l, smem);
;       else if (k == 3) phase_gemm<MODE_OUT>(p, l, smem);
;       else if (k == 4) phase_gemm<MODE_UP>(p, l, smem);
;       else phase_gemm<MODE_DOWN>(p, l, smem);
.LBB0_23:
	v_readlane_b32 s0, v245, 52
	s_add_i32 s0, s0, -1
	s_mul_hi_i32 s1, s0, 0x2aaaaaab
	s_lshr_b32 s2, s1, 31
	s_add_i32 s4, s1, s2
	s_mov_b32 s2, s4
	v_writelane_b32 v245, s2, 53
	s_mul_i32 s1, s4, 6
	s_nop 0
	v_writelane_b32 v245, s3, 54
	s_sub_i32 s2, s0, s1
	v_writelane_b32 v245, s2, 55
	s_cmp_lt_i32 s2, 2
	s_mov_b64 s[2:3], 0
	s_mov_b64 s[0:1], -1
	v_writelane_b32 v245, s2, 56
	s_nop 1
	v_writelane_b32 v245, s3, 57
	s_cbranch_scc1 .LBB0_497
	v_readlane_b32 s0, v245, 55
	s_cmp_gt_i32 s0, 2
	s_cbranch_scc0 .LBB0_51
	s_cmp_gt_i32 s0, 3
	s_cbranch_scc0 .LBB0_52
	s_cmp_eq_u32 s0, 4
	s_mov_b64 s[0:1], -1
	s_cbranch_scc0 .LBB0_50
	v_readlane_b32 s0, v246, 5
	v_readlane_b32 s1, v246, 6
	s_andn2_b64 vcc, exec, s[0:1]
	s_cbranch_vccnz .LBB0_49
	v_readlane_b32 s0, v245, 53
	v_readlane_b32 s1, v245, 54
	s_mov_b32 s2, s0
	s_ashr_i32 s3, s0, 31
	v_writelane_b32 v245, s0, 53
	v_readlane_b32 s22, v246, 31
	s_nop 0
	v_writelane_b32 v245, s1, 54
	s_lshl_b64 s[0:1], s[2:3], 23
	v_readlane_b32 s2, v247, 17
	s_add_u32 s18, s2, s0
	v_readlane_b32 s2, v247, 18
	s_addc_u32 s19, s2, s1
	v_readlane_b32 s2, v245, 19
	s_add_u32 s20, s2, s0
	v_readlane_b32 s0, v245, 20
	s_addc_u32 s21, s0, s1
	s_mov_b32 s98, 0

; DI int my_tid() { int t = threadIdx.x; asm volatile("" : "+v"(t)); return t; }
; #define WAIT_V(n) asm volatile("s_waitcnt vmcnt(" #n ")" ::: "memory")
; #define BAR __builtin_amdgcn_s_barrier()
; template <int MODE>
; DI void gemm_tile(const Params& p, const bf16_t* __restrict__ A, const bf16_t* __restrict__ Bt, int K, int brow, int bcol, int mp, int nt, bool vt, char* smem) {
;     ...
;   const int tid = my_tid();
;   int go0, go1;
;   { int r_, c_; stage_rc(tid * 16, r_, c_); go0 = r_ * K + c_; stage_rc(tid * 16 + 8192, r_, c_); go1 = r_ * K + c_; }
;     ...
;   const int wid = tid >> 6, lane = tid & 63, wr = wid >> 2, wc = wid & 3, fr = lane & 15, fq = lane >> 4;
;   const int laneoff = (fr * 64 + fq * 16) ^ ((fr >> 3) << 5);
;   const __attribute__((address_space(3))) char* aB = (const __attribute__((address_space(3))) char*)smem + wr * 8192 + laneoff;
;   const __attribute__((address_space(3))) char* bB = (const __attribute__((address_space(3))) char*)smem + 65536 + wc * 4096 + laneoff;
;   f32x4 acc[2][2][4][2];
; #pragma unroll
;   for (int a = 0; a < 2; ++a)
; #pragma unroll
;     for (int b = 0; b < 2; ++b)
; #pragma unroll
;       for (int m = 0; m < 4; ++m)
; #pragma unroll
;         for (int n = 0; n < 2; ++n) acc[a][b][m][n] = (f32x4){0.f, 0.f, 0.f, 0.f};
;   bf16x8 At[4][2], B0[2][2], B1[2][2];
;   const int ntk = K / 64;
;   const int m0 = mp * 256, n0 = nt * 256;
;   float* rsl = (float*)(smem + 131072);
;   float4 ssa = make_float4(0.f, 0.f, 0.f, 0.f);
;   if (MODE == MODE_PROJ || MODE == MODE_UP)
;     ssa = *(const float4*)((const float*)(p.ws + (MODE == MODE_UP ? OFF_SSB : OFF_SSA)) + (size_t)m0 * 8 + tid * 4);
;   STAGE(SB(0, 0), Bt, bcol, 0); STAGE(SA(0, 0), A, brow, 0);
;   STAGE(SB(0, 1), Bt, bcol + 128, 0); STAGE(SA(0, 1), A, brow + 128, 0);
;   if (wr == 1) BAR;
;   WAIT_V(4); BAR;
;   STAGE(SB(1, 0), Bt, bcol, 1); STAGE(SA(1, 0), A, brow, 1); STAGE(SB(1, 1), Bt, bcol + 128, 1);
;   WAIT_V(6); BAR;
;   if (MODE == MODE_PROJ || MODE == MODE_UP) {
;     float t = (ssa.x + ssa.y) + (ssa.z + ssa.w);
;     t += __shfl_xor(t, 1);
;     if ((tid & 1) == 0) rsl[tid >> 1] = rsqrtf(t * (1.f / 1024.f) + 1e-6f);
.LBB0_32:
	s_cmp_eq_u32 s98, 1
	s_cselect_b64 vcc, -1, 0
	v_mov_b32_e32 v0, v152
	s_lshl_b32 s2, s0, 8
	v_bfe_i32 v3, v0, 27, 1
	v_lshlrev_b32_e32 v140, 4, v0
	v_lshrrev_b32_e32 v3, 22, v3
	v_add_u32_e32 v3, v140, v3
	v_and_b32_e32 v3, 0xfffffc00, v3
	s_waitcnt lgkmcnt(0)
	v_ashrrev_i32_e32 v2, 31, v0
	v_sub_u32_e32 v3, v140, v3
	v_lshrrev_b32_e32 v2, 26, v2
	v_lshrrev_b32_e32 v4, 4, v3
	v_add_u32_e32 v2, v0, v2
	v_bitop3_b32 v4, v4, v3, 32 bitop3:0x6c
	v_ashrrev_i32_e32 v3, 31, v3
	v_ashrrev_i32_e32 v2, 6, v2
	v_lshrrev_b32_e32 v3, 26, v3
	v_lshlrev_b32_e32 v5, 3, v2
	v_add_u32_e32 v3, v4, v3
	v_and_b32_e32 v5, 0x3ffff0, v5
	v_ashrrev_i32_e32 v3, 6, v3
	v_add_u32_e32 v5, v3, v5
	v_mul_i32_i24_e32 v3, 64, v3
	v_add_u32_e32 v143, 0x2000, v140
	v_sub_u32_e32 v3, v4, v3
	v_ashrrev_i32_e32 v4, 31, v143
	v_lshrrev_b32_e32 v4, 22, v4
	v_lshlrev_b32_e32 v2, 5, v2
	v_add_u32_e32 v4, v143, v4
	v_and_b32_e32 v2, 32, v2
	v_ashrrev_i32_e32 v4, 10, v4
	v_lshl_or_b32 v2, v5, 10, v2
	v_mul_i32_i24_e32 v5, 0x400, v4
	v_sub_u32_e32 v5, v143, v5
	v_lshrrev_b32_e32 v6, 4, v5
	v_bitop3_b32 v5, v6, v5, 32 bitop3:0x6c
	v_ashrrev_i32_e32 v7, 31, v5
	s_ashr_i32 s3, s2, 31
	s_lshl_b32 s4, s1, 8
	v_lshrrev_b32_e32 v7, 26, v7
	s_lshl_b64 s[0:1], s[2:3], 5
	v_readlane_b32 s5, v246, 12
	v_lshlrev_b32_e32 v6, 3, v4
	v_add_u32_e32 v7, v5, v7
	s_add_u32 s0, s5, s0
	v_readlane_b32 s5, v246, 13
	v_lshlrev_b32_e32 v130, 2, v0
	v_ashrrev_i16_sdwa v3, v200, sext(v3) dst_sel:DWORD dst_unused:UNUSED_PAD src0_sel:DWORD src1_sel:BYTE_0
	v_and_b32_e32 v6, 0x3ffff0, v6
	v_lshrrev_b32_e32 v8, 6, v7
	v_lshlrev_b32_e32 v4, 5, v4
	v_and_b32_e32 v7, 0xc0, v7
	s_addc_u32 s1, s5, s1
	v_ashrrev_i32_e32 v131, 31, v130
	v_add_u32_e32 v6, v8, v6
	v_and_b32_e32 v4, 32, v4
	v_sub_u32_e32 v5, v5, v7
	v_add_u32_sdwa v134, v2, sext(v3) dst_sel:DWORD dst_unused:UNUSED_PAD src0_sel:DWORD src1_sel:WORD_0
	v_lshl_add_u64 v[2:3], v[130:131], 2, s[0:1]
	s_lshl_b64 s[0:1], s[2:3], 11
	v_readlane_b32 s12, v247, 7
	v_ashrrev_i16_sdwa v5, v200, sext(v5) dst_sel:DWORD dst_unused:UNUSED_PAD src0_sel:DWORD src1_sel:BYTE_0
	v_lshl_or_b32 v4, v6, 10, v4
	v_readlane_b32 s13, v247, 8
	s_add_u32 s6, s12, s0
	v_add_u32_sdwa v132, v4, sext(v5) dst_sel:DWORD dst_unused:UNUSED_PAD src0_sel:DWORD src1_sel:WORD_0
	s_addc_u32 s7, s13, s1
	v_ashrrev_i32_e32 v135, 31, v134
	v_add_u32_e32 v144, 0x10000, v140
	s_ashr_i32 s5, s4, 31
	s_mov_b64 s[0:1], s[6:7]
	v_lshlrev_b64 v[136:137], 1, v[134:135]
	v_readfirstlane_b32 s3, v144
	v_ashrrev_i32_e32 v133, 31, v132
	s_lshl_b64 s[14:15], s[4:5], 11
	global_load_dwordx4 v[2:5], v[2:3], off
	s_mov_b32 m0, s3
	v_lshl_add_u64 v[8:9], s[0:1], 0, v[136:137]
	v_lshlrev_b64 v[138:139], 1, v[132:133]
	v_mov_b32_e32 v248, v136
	v_mov_b32_e32 v249, v137
	v_mov_b32_e32 v250, v138
	v_mov_b32_e32 v251, v139
	v_add_u32_e32 v146, 0x12000, v140
	s_add_u32 s8, s18, s14
	s_cbranch_vccnz .Lup_skipld0
	global_load_lds_dwordx4 v[8:9], off
.Lup_skipld0:
	v_lshl_add_u64 v[8:9], s[0:1], 0, v[138:139]
	v_readfirstlane_b32 s0, v146
	s_addc_u32 s9, s19, s15
	s_mov_b32 m0, s0
	s_mov_b64 s[0:1], s[8:9]
	v_readfirstlane_b32 s3, v140
	s_cbranch_vccnz .Lup_skipld1
	global_load_lds_dwordx4 v[8:9], off
.Lup_skipld1:
	s_mov_b32 m0, s3
	v_lshl_add_u64 v[8:9], s[0:1], 0, v[136:137]
	s_cbranch_vccnz .Lup_skipld2
	global_load_lds_dwordx4 v[8:9], off
.Lup_skipld2:
	v_lshl_add_u64 v[8:9], s[0:1], 0, v[138:139]
	v_readfirstlane_b32 s0, v143
	s_mov_b32 m0, s0
	s_or_b32 s0, s2, 0x80
	s_ashr_i32 s1, s0, 31
	s_lshl_b64 s[10:11], s[0:1], 11
	s_add_u32 s10, s12, s10
	s_addc_u32 s11, s13, s11
	v_add_u32_e32 v148, 0x14000, v140
	s_mov_b64 s[12:13], s[10:11]
	v_readfirstlane_b32 s1, v148
	s_cbranch_vccnz .Lup_skipld3
	global_load_lds_dwordx4 v[8:9], off
.Lup_skipld3:
	s_mov_b32 m0, s1
	v_lshl_add_u64 v[8:9], s[12:13], 0, v[136:137]
	s_cbranch_vccnz .Lup_skipld4
	global_load_lds_dwordx4 v[8:9], off
.Lup_skipld4:
	v_lshl_add_u64 v[8:9], s[12:13], 0, v[138:139]
	s_or_b32 s12, s4, 0x80
	s_ashr_i32 s13, s12, 31
	s_lshl_b64 s[12:13], s[12:13], 11
	v_add_u32_e32 v149, 0x16000, v140
	s_add_u32 s12, s18, s12
	v_readfirstlane_b32 s1, v149
	s_addc_u32 s13, s19, s13
	v_add_u32_e32 v150, 0x4000, v140
	s_mov_b32 m0, s1
	s_mov_b64 s[16:17], s[12:13]
	v_readfirstlane_b32 s1, v150
	v_add_u32_e32 v151, 0x6000, v140
	s_cbranch_vccnz .Lup_skipld5
	global_load_lds_dwordx4 v[8:9], off
.Lup_skipld5:
	s_mov_b32 m0, s1
	v_lshl_add_u64 v[8:9], s[16:17], 0, v[136:137]
	v_readfirstlane_b32 s1, v151
	s_cbranch_vccnz .Lup_skipld6
	global_load_lds_dwordx4 v[8:9], off
.Lup_skipld6:
	v_lshl_add_u64 v[8:9], s[16:17], 0, v[138:139]
	s_mov_b32 m0, s1
	v_ashrrev_i32_e32 v6, 8, v0
	s_cbranch_vccnz .Lup_skipld7
	global_load_lds_dwordx4 v[8:9], off
.Lup_skipld7:
	v_cmp_eq_u32_e32 vcc, 1, v6
	s_and_saveexec_b64 s[16:17], vcc
	s_cbranch_execz .LBB0_34
	s_barrier
.LBB0_34:
	s_or_b64 exec, exec, s[16:17]
	s_add_u32 s16, s6, 0x80
	v_add_u32_e32 v156, 0x18000, v140
	s_addc_u32 s17, s7, 0
	v_readfirstlane_b32 s1, v156
	s_waitcnt vmcnt(4)
	s_barrier
	s_mov_b32 m0, s1
	v_lshl_add_u64 v[8:9], s[16:17], 0, v[136:137]
	v_add_u32_e32 v157, 0x1a000, v140
	global_load_lds_dwordx4 v[8:9], off
	v_lshl_add_u64 v[8:9], s[16:17], 0, v[138:139]
	v_readfirstlane_b32 s1, v157
	s_add_u32 s16, s8, 0x80
	v_add_u32_e32 v158, 0x8000, v140
	s_mov_b32 m0, s1
	s_addc_u32 s17, s9, 0
	v_readfirstlane_b32 s1, v158
	global_load_lds_dwordx4 v[8:9], off
	s_mov_b32 m0, s1
	v_lshl_add_u64 v[8:9], s[16:17], 0, v[136:137]
	v_add_u32_e32 v159, 0xa000, v140
	global_load_lds_dwordx4 v[8:9], off
	v_lshl_add_u64 v[8:9], s[16:17], 0, v[138:139]
	v_readfirstlane_b32 s1, v159
	s_add_u32 s16, s10, 0x80
	v_add_u32_e32 v160, 0x1c000, v140
	s_mov_b32 m0, s1
	s_addc_u32 s17, s11, 0
	v_readfirstlane_b32 s1, v160
	v_add_u32_e32 v161, 0x1e000, v140
	global_load_lds_dwordx4 v[8:9], off
	s_mov_b32 m0, s1
	v_lshl_add_u64 v[8:9], s[16:17], 0, v[136:137]
	v_readfirstlane_b32 s1, v161
	global_load_lds_dwordx4 v[8:9], off
	v_lshl_add_u64 v[8:9], s[16:17], 0, v[138:139]
	s_mov_b32 m0, s1
	s_waitcnt vmcnt(5)
	v_add_f32_e32 v2, v2, v3
	global_load_lds_dwordx4 v[8:9], off
	v_add_f32_e32 v3, v4, v5
	v_and_b32_e32 v4, 64, v203
	v_add_f32_e32 v2, v2, v3
	v_xor_b32_e32 v3, 1, v203
	v_add_u32_e32 v4, 64, v4
	v_cmp_lt_i32_e32 vcc, v3, v4
	s_waitcnt vmcnt(6)
	v_and_b32_e32 v4, 1, v0
	s_barrier
	v_cndmask_b32_e32 v3, v203, v3, vcc
	v_lshlrev_b32_e32 v3, 2, v3
	ds_bpermute_b32 v3, v3, v2
	v_cmp_eq_u32_e32 vcc, 0, v4
	s_and_saveexec_b64 s[16:17], vcc
	s_cbranch_execz .LBB0_36
	s_waitcnt lgkmcnt(0)
	v_add_f32_e32 v2, v2, v3
	v_fmamk_f32 v2, v2, 0x3a800000, v154
	s_mov_b32 s1, 0x800000
	v_mul_f32_e32 v3, 0x4b800000, v2
	v_cmp_gt_f32_e32 vcc, s1, v2
	s_nop 1
	v_cndmask_b32_e32 v2, v2, v3, vcc
	v_rsq_f32_e32 v2, v2
	s_nop 0
	v_mul_f32_e32 v3, 0x45800000, v2
	v_cndmask_b32_e32 v2, v2, v3, vcc
	v_lshl_add_u32 v3, v0, 1, v204
	s_nop 0
	ds_write_b32 v3, v2

; DI unsigned pk2(float a, float b) { f32x2 v = {a, b}; bf2_t r = __builtin_convertvector(v, bf2_t); return __builtin_bit_cast(unsigned, r); }
; template <int MODE>
; DI void gemm_tile(const Params& p, const bf16_t* __restrict__ A, const bf16_t* __restrict__ Bt, int K, int brow, int bcol, int mp, int nt, bool vt, char* smem) {
;     ...
;   for (int ai = 0; ai < 2; ++ai)
; #pragma unroll
;     for (int bj = 0; bj < 2; ++bj) {
; #pragma unroll
;       for (int m = 0; m < 4; ++m)
; #pragma unroll
;         for (int n = 0; n < 2; ++n) *(f32x4*)(st + (wc * 32 + n * 16 + fr) * 132 + wr * 64 + m * 16 + fq * 4) = acc[ai][bj][m][n];
;       __syncthreads();
;     ...
;         } else if (MODE == MODE_UP) {
;           const int tok = m0 + bj * 128 + y, col = n0 + ai * 128 + x4;
;           const float rs = rsl[bj * 128 + y];
;           const float a0 = fmaxf(v[0] * rs, 0.f), a1 = fmaxf(v[1] * rs, 0.f), a2 = fmaxf(v[2] * rs, 0.f), a3 = fmaxf(v[3] * rs, 0.f);
;           u32x2 o = {pk2(a0 * a0, a1 * a1), pk2(a2 * a2, a3 * a3)};
;           *(u32x2*)((bf16_t*)(p.ws + OFF_U) + (size_t)tok * DFF + col) = o;
.LBB0_40:
	s_or_b64 exec, exec, s[6:7]
	v_lshrrev_b32_e32 v130, 5, v152
	v_and_b32_e32 v131, 31, v152
	v_lshlrev_b32_e32 v136, 3, v131
	v_add_u32_e32 v137, s2, v130
	s_lshl_b32 s5, s4, 1
	v_lshl_add_u32 v132, v137, 13, v136
	v_add_u32_e32 v132, s5, v132
	v_mul_u32_u24_e32 v137, 264, v130
	v_add_u32_e32 v135, v137, v136
	v_add_u32_e32 v135, 0x18000, v135
	v_bfe_u32 v136, v152, 6, 2
	v_and_b32_e32 v137, 15, v152
	v_lshl_add_u32 v136, v136, 5, v137
	v_lshl_add_u32 v137, v136, 2, v204
	ds_read2_b32 v[144:145], v137 offset1:16
	ds_read2_b32 v[146:147], v137 offset0:128 offset1:144
	v_mul_u32_u24_e32 v136, 264, v136
	v_lshrrev_b32_e32 v137, 8, v152
	v_lshl_add_u32 v136, v137, 7, v136
	v_bfe_u32 v137, v152, 4, 2
	v_lshl_add_u32 v136, v137, 3, v136
	v_add_u32_e32 v134, 0x18000, v136
	v_readlane_b32 s6, v246, 14
	v_readlane_b32 s7, v246, 15
	s_add_i32 s12, s22, s60
	v_readlane_b32 s13, v246, 4
	s_mov_b32 s98, 0
	s_cmp_ge_i32 s12, s13
	s_cbranch_scc1 .Lup_noearly
	v_readlane_b32 s14, v246, 9
	v_readlane_b32 s15, v246, 10
	s_nop 0
	s_andn2_b64 vcc, exec, s[14:15]
	s_cbranch_vccnz .Lup_gen
	s_ashr_i32 s14, s12, 4
	s_and_b32 s14, s14, -8
	v_readlane_b32 s15, v246, 11
	s_nop 0
	s_sub_i32 s14, s15, s14
	s_bfe_u32 s15, s12, 0x30002
	s_or_b32 s14, s14, s15
	s_lshr_b32 s15, s12, 3
	s_and_b32 s15, s15, 12
	s_and_b32 s16, s12, 3
	s_or_b32 s15, s15, s16
	s_branch .Lup_idx
.Lup_gen:
	s_ashr_i32 s14, s12, 31
	s_lshr_b32 s14, s14, 28
	s_add_i32 s15, s12, s14
	s_ashr_i32 s14, s15, 4
	s_and_b32 s15, s15, -16
	s_add_i32 s14, s14, s76
	s_sub_i32 s15, s12, s15
.Lup_idx:
	s_lshl_b32 s14, s14, 8
	s_lshl_b32 s15, s15, 8
	v_readlane_b32 s8, v247, 7
	v_readlane_b32 s9, v247, 8
	s_mov_b32 s16, s14
	s_mov_b32 s17, 0
	s_lshl_b64 s[16:17], s[16:17], 11
	s_add_u32 s8, s8, s16
	s_addc_u32 s9, s9, s17
	s_add_u32 s10, s8, 0x40000
	s_addc_u32 s11, s9, 0
	s_mov_b32 s16, s15
	s_mov_b32 s17, 0
	s_lshl_b64 s[16:17], s[16:17], 11
	s_add_u32 s12, s18, s16
	s_addc_u32 s13, s19, s17
	s_add_u32 s16, s12, 0x40000
	s_addc_u32 s17, s13, 0
	v_lshlrev_b32_e32 v136, 4, v152
	s_nop 0
	v_readfirstlane_b32 s99, v136
	s_add_u32 s5, s99, 0x10000
	s_mov_b32 m0, s5
	v_lshl_add_u64 v[138:139], s[8:9], 0, v[248:249]
	global_load_lds_dwordx4 v[138:139], off
	s_add_u32 s5, s99, 0x12000
	s_mov_b32 m0, s5
	v_lshl_add_u64 v[138:139], s[8:9], 0, v[250:251]
	global_load_lds_dwordx4 v[138:139], off
	s_mov_b32 s5, s99
	s_mov_b32 m0, s5
	v_lshl_add_u64 v[138:139], s[12:13], 0, v[248:249]
	global_load_lds_dwordx4 v[138:139], off
	s_add_u32 s5, s99, 0x2000
	s_mov_b32 m0, s5
	v_lshl_add_u64 v[138:139], s[12:13], 0, v[250:251]
	global_load_lds_dwordx4 v[138:139], off
	s_add_u32 s5, s99, 0x14000
	s_mov_b32 m0, s5
	v_lshl_add_u64 v[138:139], s[10:11], 0, v[248:249]
	global_load_lds_dwordx4 v[138:139], off
	s_add_u32 s5, s99, 0x16000
	s_mov_b32 m0, s5
	v_lshl_add_u64 v[138:139], s[10:11], 0, v[250:251]
	global_load_lds_dwordx4 v[138:139], off
	s_add_u32 s5, s99, 0x4000
	s_mov_b32 m0, s5
	v_lshl_add_u64 v[138:139], s[16:17], 0, v[248:249]
	global_load_lds_dwordx4 v[138:139], off
	s_add_u32 s5, s99, 0x6000
	s_mov_b32 m0, s5
	v_lshl_add_u64 v[138:139], s[16:17], 0, v[250:251]
	global_load_lds_dwordx4 v[138:139], off
	s_mov_b32 s98, 1
.Lup_noearly:
	s_waitcnt lgkmcnt(0)
	s_barrier
	v_mul_f32_e32 v98, v98, v144
	v_mul_f32_e32 v99, v99, v144
	v_mul_f32_e32 v100, v100, v144
	v_mul_f32_e32 v101, v101, v144
	v_max_f32_e32 v98, 0, v98
	v_max_f32_e32 v99, 0, v99
	v_max_f32_e32 v100, 0, v100
	v_max_f32_e32 v101, 0, v101
	v_pk_mul_f32 v[98:99], v[98:99], v[98:99]
	v_pk_mul_f32 v[100:101], v[100:101], v[100:101]
	v_cvt_pk_bf16_f32 v98, v98, v99
	v_cvt_pk_bf16_f32 v99, v100, v101
	ds_write_b64 v134, v[98:99]
	v_mul_f32_e32 v102, v102, v145
	v_mul_f32_e32 v103, v103, v145
	v_mul_f32_e32 v104, v104, v145
	v_mul_f32_e32 v105, v105, v145
	v_max_f32_e32 v102, 0, v102
	v_max_f32_e32 v103, 0, v103
	v_max_f32_e32 v104, 0, v104
	v_max_f32_e32 v105, 0, v105
	v_pk_mul_f32 v[102:103], v[102:103], v[102:103]
	v_pk_mul_f32 v[104:105], v[104:105], v[104:105]
	v_cvt_pk_bf16_f32 v102, v102, v103
	v_cvt_pk_bf16_f32 v103, v104, v105
	ds_write_b64 v134, v[102:103] offset:4224
	v_mul_f32_e32 v106, v106, v144
	v_mul_f32_e32 v107, v107, v144
	v_mul_f32_e32 v108, v108, v144
	v_mul_f32_e32 v109, v109, v144
	v_max_f32_e32 v106, 0, v106
	v_max_f32_e32 v107, 0, v107
	v_max_f32_e32 v108, 0, v108
	v_max_f32_e32 v109, 0, v109
	v_pk_mul_f32 v[106:107], v[106:107], v[106:107]
	v_pk_mul_f32 v[108:109], v[108:109], v[108:109]
	v_cvt_pk_bf16_f32 v106, v106, v107
	v_cvt_pk_bf16_f32 v107, v108, v109
	ds_write_b64 v134, v[106:107] offset:32
	v_mul_f32_e32 v110, v110, v145
	v_mul_f32_e32 v111, v111, v145
	v_mul_f32_e32 v112, v112, v145
	v_mul_f32_e32 v113, v113, v145
	v_max_f32_e32 v110, 0, v110
	v_max_f32_e32 v111, 0, v111
	v_max_f32_e32 v112, 0, v112
	v_max_f32_e32 v113, 0, v113
	v_pk_mul_f32 v[110:111], v[110:111], v[110:111]
	v_pk_mul_f32 v[112:113], v[112:113], v[112:113]
	v_cvt_pk_bf16_f32 v110, v110, v111
	v_cvt_pk_bf16_f32 v111, v112, v113
	ds_write_b64 v134, v[110:111] offset:4256
	v_mul_f32_e32 v114, v114, v144
	v_mul_f32_e32 v115, v115, v144
	v_mul_f32_e32 v116, v116, v144
	v_mul_f32_e32 v117, v117, v144
	v_max_f32_e32 v114, 0, v114
	v_max_f32_e32 v115, 0, v115
	v_max_f32_e32 v116, 0, v116
	v_max_f32_e32 v117, 0, v117
	v_pk_mul_f32 v[114:115], v[114:115], v[114:115]
	v_pk_mul_f32 v[116:117], v[116:117], v[116:117]
	v_cvt_pk_bf16_f32 v114, v114, v115
	v_cvt_pk_bf16_f32 v115, v116, v117
	ds_write_b64 v134, v[114:115] offset:64
	v_mul_f32_e32 v118, v118, v145
	v_mul_f32_e32 v119, v119, v145
	v_mul_f32_e32 v120, v120, v145
	v_mul_f32_e32 v121, v121, v145
	v_max_f32_e32 v118, 0, v118
	v_max_f32_e32 v119, 0, v119
	v_max_f32_e32 v120, 0, v120
	v_max_f32_e32 v121, 0, v121
	v_pk_mul_f32 v[118:119], v[118:119], v[118:119]
	v_pk_mul_f32 v[120:121], v[120:121], v[120:121]
	v_cvt_pk_bf16_f32 v118, v118, v119
	v_cvt_pk_bf16_f32 v119, v120, v121
	ds_write_b64 v134, v[118:119] offset:4288
	v_mul_f32_e32 v122, v122, v144
	v_mul_f32_e32 v123, v123, v144
	v_mul_f32_e32 v124, v124, v144
	v_mul_f32_e32 v125, v125, v144
	v_max_f32_e32 v122, 0, v122
	v_max_f32_e32 v123, 0, v123
	v_max_f32_e32 v124, 0, v124
	v_max_f32_e32 v125, 0, v125
	v_pk_mul_f32 v[122:123], v[122:123], v[122:123]
	v_pk_mul_f32 v[124:125], v[124:125], v[124:125]
	v_cvt_pk_bf16_f32 v122, v122, v123
	v_cvt_pk_bf16_f32 v123, v124, v125
	ds_write_b64 v134, v[122:123] offset:96
	v_mul_f32_e32 v126, v126, v145
	v_mul_f32_e32 v127, v127, v145
	v_mul_f32_e32 v128, v128, v145
	v_mul_f32_e32 v129, v129, v145
	v_max_f32_e32 v126, 0, v126
	v_max_f32_e32 v127, 0, v127
	v_max_f32_e32 v128, 0, v128
	v_max_f32_e32 v129, 0, v129
	v_pk_mul_f32 v[126:127], v[126:127], v[126:127]
	v_pk_mul_f32 v[128:129], v[128:129], v[128:129]
	v_cvt_pk_bf16_f32 v126, v126, v127
	v_cvt_pk_bf16_f32 v127, v128, v129
	ds_write_b64 v134, v[126:127] offset:4320
	s_waitcnt lgkmcnt(0)
	s_barrier
; DI unsigned pk2(float a, float b) { f32x2 v = {a, b}; bf2_t r = __builtin_convertvector(v, bf2_t); return __builtin_bit_cast(unsigned, r); }
; template <int MODE>
; DI void gemm_tile(const Params& p, const bf16_t* __restrict__ A, const bf16_t* __restrict__ Bt, int K, int brow, int bcol, int mp, int nt, bool vt, char* smem) {
;     ...
;       for (int pq = 0; pq < 4; ++pq) {
;         const int pass = pg * 4 + pq;
;         const int y = pass * 16 + (tid >> 5), x4 = (tid & 31) * 4;
;         const f32x4 v = *(const f32x4*)(st + y * 132 + x4);
;         if (MODE == MODE_PROJ) {
;           if (vt) {
;             const int vrow = (nt - 8) * 256 + bj * 128 + y, tk = m0 + ai * 128 + x4, b = tk >> 11, sq = tk & 2047;
;             const f32x4 rr = *(const f32x4*)(rsl + ai * 128 + x4);
;             u32x2 o = {pk2(v[0] * rr[0], v[1] * rr[1]), pk2(v[2] * rr[2], v[3] * rr[3])};
;             *(u32x2*)((bf16_t*)(p.ws + OFF_VT) + ((size_t)(b * VROWS + vrow)) * SEQ + sq) = o;
;           } else {
;             const int tok = m0 + bj * 128 + y, col = n0 + ai * 128 + x4;
;             const float rs = rsl[bj * 128 + y];
;             if (col < QKW) {
;               u32x2 o = {pk2(v[0] * rs, v[1] * rs), pk2(v[2] * rs, v[3] * rs)};
;               *(u32x2*)((bf16_t*)(p.ws + OFF_QK) + (size_t)tok * QKW + col) = o;
;             } else if (col < QKW + 16) {
;               f32x4 o = {v[0] * rs, v[1] * rs, v[2] * rs, v[3] * rs};
;               *(f32x4*)((float*)(p.ws + OFF_GATE) + (size_t)tok * 16 + (col - QKW)) = o;
;             }
;           }
;         } else if (MODE == MODE_UP) {
;           const int tok = m0 + bj * 128 + y, col = n0 + ai * 128 + x4;
;           const float rs = rsl[bj * 128 + y];
;           const float a0 = fmaxf(v[0] * rs, 0.f), a1 = fmaxf(v[1] * rs, 0.f), a2 = fmaxf(v[2] * rs, 0.f), a3 = fmaxf(v[3] * rs, 0.f);
;           u32x2 o = {pk2(a0 * a0, a1 * a1), pk2(a2 * a2, a3 * a3)};
;           *(u32x2*)((bf16_t*)(p.ws + OFF_U) + (size_t)tok * DFF + col) = o;
	ds_read_b64 v[114:115], v135
	ds_read_b64 v[116:117], v135 offset:4224
	ds_read_b64 v[118:119], v135 offset:8448
	ds_read_b64 v[120:121], v135 offset:12672
	ds_read_b64 v[122:123], v135 offset:16896
	ds_read_b64 v[124:125], v135 offset:21120
	ds_read_b64 v[126:127], v135 offset:25344
	ds_read_b64 v[128:129], v135 offset:29568
	s_waitcnt lgkmcnt(7)
	global_store_dwordx2 v132, v[114:115], s[6:7]
	s_waitcnt lgkmcnt(6)
	v_add_u32_e32 v136, 0x20000, v132
	global_store_dwordx2 v136, v[116:117], s[6:7]
	s_waitcnt lgkmcnt(5)
	v_add_u32_e32 v136, 0x40000, v132
	global_store_dwordx2 v136, v[118:119], s[6:7]
	s_waitcnt lgkmcnt(4)
	v_add_u32_e32 v136, 0x60000, v132
	global_store_dwordx2 v136, v[120:121], s[6:7]
	s_waitcnt lgkmcnt(3)
	v_add_u32_e32 v136, 0x80000, v132
	global_store_dwordx2 v136, v[122:123], s[6:7]
	s_waitcnt lgkmcnt(2)
	v_add_u32_e32 v136, 0xa0000, v132
	global_store_dwordx2 v136, v[124:125], s[6:7]
	s_waitcnt lgkmcnt(1)
	v_add_u32_e32 v136, 0xc0000, v132
	global_store_dwordx2 v136, v[126:127], s[6:7]
	s_waitcnt lgkmcnt(0)
	v_add_u32_e32 v136, 0xe0000, v132
	global_store_dwordx2 v136, v[128:129], s[6:7]
	s_barrier
	v_mul_f32_e32 v66, v66, v146
	v_mul_f32_e32 v67, v67, v146
	v_mul_f32_e32 v68, v68, v146
	v_mul_f32_e32 v69, v69, v146
	v_max_f32_e32 v66, 0, v66
	v_max_f32_e32 v67, 0, v67
	v_max_f32_e32 v68, 0, v68
	v_max_f32_e32 v69, 0, v69
	v_pk_mul_f32 v[66:67], v[66:67], v[66:67]
	v_pk_mul_f32 v[68:69], v[68:69], v[68:69]
	v_cvt_pk_bf16_f32 v66, v66, v67
	v_cvt_pk_bf16_f32 v67, v68, v69
	ds_write_b64 v134, v[66:67]
	v_mul_f32_e32 v70, v70, v147
	v_mul_f32_e32 v71, v71, v147
	v_mul_f32_e32 v72, v72, v147
	v_mul_f32_e32 v73, v73, v147
	v_max_f32_e32 v70, 0, v70
	v_max_f32_e32 v71, 0, v71
	v_max_f32_e32 v72, 0, v72
	v_max_f32_e32 v73, 0, v73
	v_pk_mul_f32 v[70:71], v[70:71], v[70:71]
	v_pk_mul_f32 v[72:73], v[72:73], v[72:73]
	v_cvt_pk_bf16_f32 v70, v70, v71
	v_cvt_pk_bf16_f32 v71, v72, v73
	ds_write_b64 v134, v[70:71] offset:4224
	v_mul_f32_e32 v74, v74, v146
	v_mul_f32_e32 v75, v75, v146
	v_mul_f32_e32 v76, v76, v146
	v_mul_f32_e32 v77, v77, v146
	v_max_f32_e32 v74, 0, v74
	v_max_f32_e32 v75, 0, v75
	v_max_f32_e32 v76, 0, v76
	v_max_f32_e32 v77, 0, v77
	v_pk_mul_f32 v[74:75], v[74:75], v[74:75]
	v_pk_mul_f32 v[76:77], v[76:77], v[76:77]
	v_cvt_pk_bf16_f32 v74, v74, v75
	v_cvt_pk_bf16_f32 v75, v76, v77
	ds_write_b64 v134, v[74:75] offset:32
	v_mul_f32_e32 v78, v78, v147
	v_mul_f32_e32 v79, v79, v147
	v_mul_f32_e32 v80, v80, v147
	v_mul_f32_e32 v81, v81, v147
	v_max_f32_e32 v78, 0, v78
	v_max_f32_e32 v79, 0, v79
	v_max_f32_e32 v80, 0, v80
	v_max_f32_e32 v81, 0, v81
	v_pk_mul_f32 v[78:79], v[78:79], v[78:79]
	v_pk_mul_f32 v[80:81], v[80:81], v[80:81]
	v_cvt_pk_bf16_f32 v78, v78, v79
	v_cvt_pk_bf16_f32 v79, v80, v81
	ds_write_b64 v134, v[78:79] offset:4256
	v_mul_f32_e32 v82, v82, v146
	v_mul_f32_e32 v83, v83, v146
	v_mul_f32_e32 v84, v84, v146
	v_mul_f32_e32 v85, v85, v146
	v_max_f32_e32 v82, 0, v82
	v_max_f32_e32 v83, 0, v83
	v_max_f32_e32 v84, 0, v84
	v_max_f32_e32 v85, 0, v85
	v_pk_mul_f32 v[82:83], v[82:83], v[82:83]
	v_pk_mul_f32 v[84:85], v[84:85], v[84:85]
	v_cvt_pk_bf16_f32 v82, v82, v83
	v_cvt_pk_bf16_f32 v83, v84, v85
	ds_write_b64 v134, v[82:83] offset:64
	v_mul_f32_e32 v86, v86, v147
	v_mul_f32_e32 v87, v87, v147
	v_mul_f32_e32 v88, v88, v147
	v_mul_f32_e32 v89, v89, v147
	v_max_f32_e32 v86, 0, v86
	v_max_f32_e32 v87, 0, v87
	v_max_f32_e32 v88, 0, v88
	v_max_f32_e32 v89, 0, v89
	v_pk_mul_f32 v[86:87], v[86:87], v[86:87]
	v_pk_mul_f32 v[88:89], v[88:89], v[88:89]
	v_cvt_pk_bf16_f32 v86, v86, v87
	v_cvt_pk_bf16_f32 v87, v88, v89
	ds_write_b64 v134, v[86:87] offset:4288
	v_mul_f32_e32 v90, v90, v146
	v_mul_f32_e32 v91, v91, v146
	v_mul_f32_e32 v92, v92, v146
	v_mul_f32_e32 v93, v93, v146
	v_max_f32_e32 v90, 0, v90
	v_max_f32_e32 v91, 0, v91
	v_max_f32_e32 v92, 0, v92
	v_max_f32_e32 v93, 0, v93
	v_pk_mul_f32 v[90:91], v[90:91], v[90:91]
	v_pk_mul_f32 v[92:93], v[92:93], v[92:93]
	v_cvt_pk_bf16_f32 v90, v90, v91
	v_cvt_pk_bf16_f32 v91, v92, v93
	ds_write_b64 v134, v[90:91] offset:96
	v_mul_f32_e32 v94, v94, v147
	v_mul_f32_e32 v95, v95, v147
	v_mul_f32_e32 v96, v96, v147
	v_mul_f32_e32 v97, v97, v147
	v_max_f32_e32 v94, 0, v94
	v_max_f32_e32 v95, 0, v95
	v_max_f32_e32 v96, 0, v96
	v_max_f32_e32 v97, 0, v97
	v_pk_mul_f32 v[94:95], v[94:95], v[94:95]
	v_pk_mul_f32 v[96:97], v[96:97], v[96:97]
	v_cvt_pk_bf16_f32 v94, v94, v95
	v_cvt_pk_bf16_f32 v95, v96, v97
	ds_write_b64 v134, v[94:95] offset:4320
	s_waitcnt lgkmcnt(0)
	s_barrier
	ds_read_b64 v[82:83], v135
	ds_read_b64 v[84:85], v135 offset:4224
	ds_read_b64 v[86:87], v135 offset:8448
	ds_read_b64 v[88:89], v135 offset:12672
	ds_read_b64 v[90:91], v135 offset:16896
	ds_read_b64 v[92:93], v135 offset:21120
	ds_read_b64 v[94:95], v135 offset:25344
	ds_read_b64 v[96:97], v135 offset:29568
	s_waitcnt lgkmcnt(7)
	v_add_u32_e32 v136, 0x100000, v132
	global_store_dwordx2 v136, v[82:83], s[6:7]
	s_waitcnt lgkmcnt(6)
	v_add_u32_e32 v136, 0x120000, v132
	global_store_dwordx2 v136, v[84:85], s[6:7]
	s_waitcnt lgkmcnt(5)
	v_add_u32_e32 v136, 0x140000, v132
	global_store_dwordx2 v136, v[86:87], s[6:7]
	s_waitcnt lgkmcnt(4)
	v_add_u32_e32 v136, 0x160000, v132
	global_store_dwordx2 v136, v[88:89], s[6:7]
	s_waitcnt lgkmcnt(3)
	v_add_u32_e32 v136, 0x180000, v132
	global_store_dwordx2 v136, v[90:91], s[6:7]
	s_waitcnt lgkmcnt(2)
	v_add_u32_e32 v136, 0x1a0000, v132
	global_store_dwordx2 v136, v[92:93], s[6:7]
	s_waitcnt lgkmcnt(1)
	v_add_u32_e32 v136, 0x1c0000, v132
	global_store_dwordx2 v136, v[94:95], s[6:7]
	s_waitcnt lgkmcnt(0)
	v_add_u32_e32 v136, 0x1e0000, v132
	global_store_dwordx2 v136, v[96:97], s[6:7]
	s_barrier
; DI unsigned pk2(float a, float b) { f32x2 v = {a, b}; bf2_t r = __builtin_convertvector(v, bf2_t); return __builtin_bit_cast(unsigned, r); }
; template <int MODE>
; DI void gemm_tile(const Params& p, const bf16_t* __restrict__ A, const bf16_t* __restrict__ Bt, int K, int brow, int bcol, int mp, int nt, bool vt, char* smem) {
;     ...
;       for (int pq = 0; pq < 4; ++pq) {
;         const int pass = pg * 4 + pq;
;         const int y = pass * 16 + (tid >> 5), x4 = (tid & 31) * 4;
;         const f32x4 v = *(const f32x4*)(st + y * 132 + x4);
;         if (MODE == MODE_PROJ) {
;           if (vt) {
;             const int vrow = (nt - 8) * 256 + bj * 128 + y, tk = m0 + ai * 128 + x4, b = tk >> 11, sq = tk & 2047;
;             const f32x4 rr = *(const f32x4*)(rsl + ai * 128 + x4);
;             u32x2 o = {pk2(v[0] * rr[0], v[1] * rr[1]), pk2(v[2] * rr[2], v[3] * rr[3])};
;             *(u32x2*)((bf16_t*)(p.ws + OFF_VT) + ((size_t)(b * VROWS + vrow)) * SEQ + sq) = o;
;           } else {
;             const int tok = m0 + bj * 128 + y, col = n0 + ai * 128 + x4;
;             const float rs = rsl[bj * 128 + y];
;             if (col < QKW) {
;               u32x2 o = {pk2(v[0] * rs, v[1] * rs), pk2(v[2] * rs, v[3] * rs)};
;               *(u32x2*)((bf16_t*)(p.ws + OFF_QK) + (size_t)tok * QKW + col) = o;
;             } else if (col < QKW + 16) {
;               f32x4 o = {v[0] * rs, v[1] * rs, v[2] * rs, v[3] * rs};
;               *(f32x4*)((float*)(p.ws + OFF_GATE) + (size_t)tok * 16 + (col - QKW)) = o;
;             }
;           }
;         } else if (MODE == MODE_UP) {
;           const int tok = m0 + bj * 128 + y, col = n0 + ai * 128 + x4;
;           const float rs = rsl[bj * 128 + y];
;           const float a0 = fmaxf(v[0] * rs, 0.f), a1 = fmaxf(v[1] * rs, 0.f), a2 = fmaxf(v[2] * rs, 0.f), a3 = fmaxf(v[3] * rs, 0.f);
;           u32x2 o = {pk2(a0 * a0, a1 * a1), pk2(a2 * a2, a3 * a3)};
;           *(u32x2*)((bf16_t*)(p.ws + OFF_U) + (size_t)tok * DFF + col) = o;
	v_mul_f32_e32 v34, v34, v144
	v_mul_f32_e32 v35, v35, v144
	v_mul_f32_e32 v36, v36, v144
	v_mul_f32_e32 v37, v37, v144
	v_max_f32_e32 v34, 0, v34
	v_max_f32_e32 v35, 0, v35
	v_max_f32_e32 v36, 0, v36
	v_max_f32_e32 v37, 0, v37
	v_pk_mul_f32 v[34:35], v[34:35], v[34:35]
	v_pk_mul_f32 v[36:37], v[36:37], v[36:37]
	v_cvt_pk_bf16_f32 v34, v34, v35
	v_cvt_pk_bf16_f32 v35, v36, v37
	ds_write_b64 v134, v[34:35]
	v_mul_f32_e32 v38, v38, v145
	v_mul_f32_e32 v39, v39, v145
	v_mul_f32_e32 v40, v40, v145
	v_mul_f32_e32 v41, v41, v145
	v_max_f32_e32 v38, 0, v38
	v_max_f32_e32 v39, 0, v39
	v_max_f32_e32 v40, 0, v40
	v_max_f32_e32 v41, 0, v41
	v_pk_mul_f32 v[38:39], v[38:39], v[38:39]
	v_pk_mul_f32 v[40:41], v[40:41], v[40:41]
	v_cvt_pk_bf16_f32 v38, v38, v39
	v_cvt_pk_bf16_f32 v39, v40, v41
	ds_write_b64 v134, v[38:39] offset:4224
	v_mul_f32_e32 v42, v42, v144
	v_mul_f32_e32 v43, v43, v144
	v_mul_f32_e32 v44, v44, v144
	v_mul_f32_e32 v45, v45, v144
	v_max_f32_e32 v42, 0, v42
	v_max_f32_e32 v43, 0, v43
	v_max_f32_e32 v44, 0, v44
	v_max_f32_e32 v45, 0, v45
	v_pk_mul_f32 v[42:43], v[42:43], v[42:43]
	v_pk_mul_f32 v[44:45], v[44:45], v[44:45]
	v_cvt_pk_bf16_f32 v42, v42, v43
	v_cvt_pk_bf16_f32 v43, v44, v45
	ds_write_b64 v134, v[42:43] offset:32
	v_mul_f32_e32 v46, v46, v145
	v_mul_f32_e32 v47, v47, v145
	v_mul_f32_e32 v48, v48, v145
	v_mul_f32_e32 v49, v49, v145
	v_max_f32_e32 v46, 0, v46
	v_max_f32_e32 v47, 0, v47
	v_max_f32_e32 v48, 0, v48
	v_max_f32_e32 v49, 0, v49
	v_pk_mul_f32 v[46:47], v[46:47], v[46:47]
	v_pk_mul_f32 v[48:49], v[48:49], v[48:49]
	v_cvt_pk_bf16_f32 v46, v46, v47
	v_cvt_pk_bf16_f32 v47, v48, v49
	ds_write_b64 v134, v[46:47] offset:4256
	v_mul_f32_e32 v50, v50, v144
	v_mul_f32_e32 v51, v51, v144
	v_mul_f32_e32 v52, v52, v144
	v_mul_f32_e32 v53, v53, v144
	v_max_f32_e32 v50, 0, v50
	v_max_f32_e32 v51, 0, v51
	v_max_f32_e32 v52, 0, v52
	v_max_f32_e32 v53, 0, v53
	v_pk_mul_f32 v[50:51], v[50:51], v[50:51]
	v_pk_mul_f32 v[52:53], v[52:53], v[52:53]
	v_cvt_pk_bf16_f32 v50, v50, v51
	v_cvt_pk_bf16_f32 v51, v52, v53
	ds_write_b64 v134, v[50:51] offset:64
	v_mul_f32_e32 v54, v54, v145
	v_mul_f32_e32 v55, v55, v145
	v_mul_f32_e32 v56, v56, v145
	v_mul_f32_e32 v57, v57, v145
	v_max_f32_e32 v54, 0, v54
	v_max_f32_e32 v55, 0, v55
	v_max_f32_e32 v56, 0, v56
	v_max_f32_e32 v57, 0, v57
	v_pk_mul_f32 v[54:55], v[54:55], v[54:55]
	v_pk_mul_f32 v[56:57], v[56:57], v[56:57]
	v_cvt_pk_bf16_f32 v54, v54, v55
	v_cvt_pk_bf16_f32 v55, v56, v57
	ds_write_b64 v134, v[54:55] offset:4288
	v_mul_f32_e32 v58, v58, v144
	v_mul_f32_e32 v59, v59, v144
	v_mul_f32_e32 v60, v60, v144
	v_mul_f32_e32 v61, v61, v144
	v_max_f32_e32 v58, 0, v58
	v_max_f32_e32 v59, 0, v59
	v_max_f32_e32 v60, 0, v60
	v_max_f32_e32 v61, 0, v61
	v_pk_mul_f32 v[58:59], v[58:59], v[58:59]
	v_pk_mul_f32 v[60:61], v[60:61], v[60:61]
	v_cvt_pk_bf16_f32 v58, v58, v59
	v_cvt_pk_bf16_f32 v59, v60, v61
	ds_write_b64 v134, v[58:59] offset:96
	v_mul_f32_e32 v62, v62, v145
	v_mul_f32_e32 v63, v63, v145
	v_mul_f32_e32 v64, v64, v145
	v_mul_f32_e32 v65, v65, v145
	v_max_f32_e32 v62, 0, v62
	v_max_f32_e32 v63, 0, v63
	v_max_f32_e32 v64, 0, v64
	v_max_f32_e32 v65, 0, v65
	v_pk_mul_f32 v[62:63], v[62:63], v[62:63]
	v_pk_mul_f32 v[64:65], v[64:65], v[64:65]
	v_cvt_pk_bf16_f32 v62, v62, v63
	v_cvt_pk_bf16_f32 v63, v64, v65
	ds_write_b64 v134, v[62:63] offset:4320
	s_waitcnt lgkmcnt(0)
	s_barrier
	ds_read_b64 v[50:51], v135
	ds_read_b64 v[52:53], v135 offset:4224
	ds_read_b64 v[54:55], v135 offset:8448
	ds_read_b64 v[56:57], v135 offset:12672
	ds_read_b64 v[58:59], v135 offset:16896
	ds_read_b64 v[60:61], v135 offset:21120
	ds_read_b64 v[62:63], v135 offset:25344
	ds_read_b64 v[64:65], v135 offset:29568
	s_waitcnt lgkmcnt(7)
	global_store_dwordx2 v132, v[50:51], s[6:7] offset:256
	s_waitcnt lgkmcnt(6)
	v_add_u32_e32 v136, 0x20000, v132
	global_store_dwordx2 v136, v[52:53], s[6:7] offset:256
	s_waitcnt lgkmcnt(5)
	v_add_u32_e32 v136, 0x40000, v132
	global_store_dwordx2 v136, v[54:55], s[6:7] offset:256
	s_waitcnt lgkmcnt(4)
	v_add_u32_e32 v136, 0x60000, v132
	global_store_dwordx2 v136, v[56:57], s[6:7] offset:256
	s_waitcnt lgkmcnt(3)
	v_add_u32_e32 v136, 0x80000, v132
	global_store_dwordx2 v136, v[58:59], s[6:7] offset:256
	s_waitcnt lgkmcnt(2)
	v_add_u32_e32 v136, 0xa0000, v132
	global_store_dwordx2 v136, v[60:61], s[6:7] offset:256
	s_waitcnt lgkmcnt(1)
	v_add_u32_e32 v136, 0xc0000, v132
	global_store_dwordx2 v136, v[62:63], s[6:7] offset:256
	s_waitcnt lgkmcnt(0)
	v_add_u32_e32 v136, 0xe0000, v132
	global_store_dwordx2 v136, v[64:65], s[6:7] offset:256
	s_barrier
; DI unsigned pk2(float a, float b) { f32x2 v = {a, b}; bf2_t r = __builtin_convertvector(v, bf2_t); return __builtin_bit_cast(unsigned, r); }
; template <int MODE>
; DI void gemm_tile(const Params& p, const bf16_t* __restrict__ A, const bf16_t* __restrict__ Bt, int K, int brow, int bcol, int mp, int nt, bool vt, char* smem) {
;     ...
;       for (int pq = 0; pq < 4; ++pq) {
;         const int pass = pg * 4 + pq;
;         const int y = pass * 16 + (tid >> 5), x4 = (tid & 31) * 4;
;         const f32x4 v = *(const f32x4*)(st + y * 132 + x4);
;         if (MODE == MODE_PROJ) {
;           if (vt) {
;             const int vrow = (nt - 8) * 256 + bj * 128 + y, tk = m0 + ai * 128 + x4, b = tk >> 11, sq = tk & 2047;
;             const f32x4 rr = *(const f32x4*)(rsl + ai * 128 + x4);
;             u32x2 o = {pk2(v[0] * rr[0], v[1] * rr[1]), pk2(v[2] * rr[2], v[3] * rr[3])};
;             *(u32x2*)((bf16_t*)(p.ws + OFF_VT) + ((size_t)(b * VROWS + vrow)) * SEQ + sq) = o;
;           } else {
;             const int tok = m0 + bj * 128 + y, col = n0 + ai * 128 + x4;
;             const float rs = rsl[bj * 128 + y];
;             if (col < QKW) {
;               u32x2 o = {pk2(v[0] * rs, v[1] * rs), pk2(v[2] * rs, v[3] * rs)};
;               *(u32x2*)((bf16_t*)(p.ws + OFF_QK) + (size_t)tok * QKW + col) = o;
;             } else if (col < QKW + 16) {
;               f32x4 o = {v[0] * rs, v[1] * rs, v[2] * rs, v[3] * rs};
;               *(f32x4*)((float*)(p.ws + OFF_GATE) + (size_t)tok * 16 + (col - QKW)) = o;
;             }
;           }
;         } else if (MODE == MODE_UP) {
;           const int tok = m0 + bj * 128 + y, col = n0 + ai * 128 + x4;
;           const float rs = rsl[bj * 128 + y];
;           const float a0 = fmaxf(v[0] * rs, 0.f), a1 = fmaxf(v[1] * rs, 0.f), a2 = fmaxf(v[2] * rs, 0.f), a3 = fmaxf(v[3] * rs, 0.f);
;           u32x2 o = {pk2(a0 * a0, a1 * a1), pk2(a2 * a2, a3 * a3)};
;           *(u32x2*)((bf16_t*)(p.ws + OFF_U) + (size_t)tok * DFF + col) = o;
	v_mul_f32_e32 v2, v2, v146
	v_mul_f32_e32 v3, v3, v146
	v_mul_f32_e32 v4, v4, v146
	v_mul_f32_e32 v5, v5, v146
	v_max_f32_e32 v2, 0, v2
	v_max_f32_e32 v3, 0, v3
	v_max_f32_e32 v4, 0, v4
	v_max_f32_e32 v5, 0, v5
	v_pk_mul_f32 v[2:3], v[2:3], v[2:3]
	v_pk_mul_f32 v[4:5], v[4:5], v[4:5]
	v_cvt_pk_bf16_f32 v2, v2, v3
	v_cvt_pk_bf16_f32 v3, v4, v5
	ds_write_b64 v134, v[2:3]
	v_mul_f32_e32 v6, v6, v147
	v_mul_f32_e32 v7, v7, v147
	v_mul_f32_e32 v8, v8, v147
	v_mul_f32_e32 v9, v9, v147
	v_max_f32_e32 v6, 0, v6
	v_max_f32_e32 v7, 0, v7
	v_max_f32_e32 v8, 0, v8
	v_max_f32_e32 v9, 0, v9
	v_pk_mul_f32 v[6:7], v[6:7], v[6:7]
	v_pk_mul_f32 v[8:9], v[8:9], v[8:9]
	v_cvt_pk_bf16_f32 v6, v6, v7
	v_cvt_pk_bf16_f32 v7, v8, v9
	ds_write_b64 v134, v[6:7] offset:4224
	v_mul_f32_e32 v10, v10, v146
	v_mul_f32_e32 v11, v11, v146
	v_mul_f32_e32 v12, v12, v146
	v_mul_f32_e32 v13, v13, v146
	v_max_f32_e32 v10, 0, v10
	v_max_f32_e32 v11, 0, v11
	v_max_f32_e32 v12, 0, v12
	v_max_f32_e32 v13, 0, v13
	v_pk_mul_f32 v[10:11], v[10:11], v[10:11]
	v_pk_mul_f32 v[12:13], v[12:13], v[12:13]
	v_cvt_pk_bf16_f32 v10, v10, v11
	v_cvt_pk_bf16_f32 v11, v12, v13
	ds_write_b64 v134, v[10:11] offset:32
	v_mul_f32_e32 v14, v14, v147
	v_mul_f32_e32 v15, v15, v147
	v_mul_f32_e32 v16, v16, v147
	v_mul_f32_e32 v17, v17, v147
	v_max_f32_e32 v14, 0, v14
	v_max_f32_e32 v15, 0, v15
	v_max_f32_e32 v16, 0, v16
	v_max_f32_e32 v17, 0, v17
	v_pk_mul_f32 v[14:15], v[14:15], v[14:15]
	v_pk_mul_f32 v[16:17], v[16:17], v[16:17]
	v_cvt_pk_bf16_f32 v14, v14, v15
	v_cvt_pk_bf16_f32 v15, v16, v17
	ds_write_b64 v134, v[14:15] offset:4256
	v_mul_f32_e32 v18, v18, v146
	v_mul_f32_e32 v19, v19, v146
	v_mul_f32_e32 v20, v20, v146
	v_mul_f32_e32 v21, v21, v146
	v_max_f32_e32 v18, 0, v18
	v_max_f32_e32 v19, 0, v19
	v_max_f32_e32 v20, 0, v20
	v_max_f32_e32 v21, 0, v21
	v_pk_mul_f32 v[18:19], v[18:19], v[18:19]
	v_pk_mul_f32 v[20:21], v[20:21], v[20:21]
	v_cvt_pk_bf16_f32 v18, v18, v19
	v_cvt_pk_bf16_f32 v19, v20, v21
	ds_write_b64 v134, v[18:19] offset:64
	v_mul_f32_e32 v22, v22, v147
	v_mul_f32_e32 v23, v23, v147
	v_mul_f32_e32 v24, v24, v147
	v_mul_f32_e32 v25, v25, v147
	v_max_f32_e32 v22, 0, v22
	v_max_f32_e32 v23, 0, v23
	v_max_f32_e32 v24, 0, v24
	v_max_f32_e32 v25, 0, v25
	v_pk_mul_f32 v[22:23], v[22:23], v[22:23]
	v_pk_mul_f32 v[24:25], v[24:25], v[24:25]
	v_cvt_pk_bf16_f32 v22, v22, v23
	v_cvt_pk_bf16_f32 v23, v24, v25
	ds_write_b64 v134, v[22:23] offset:4288
	v_mul_f32_e32 v26, v26, v146
	v_mul_f32_e32 v27, v27, v146
	v_mul_f32_e32 v28, v28, v146
	v_mul_f32_e32 v29, v29, v146
	v_max_f32_e32 v26, 0, v26
	v_max_f32_e32 v27, 0, v27
	v_max_f32_e32 v28, 0, v28
	v_max_f32_e32 v29, 0, v29
	v_pk_mul_f32 v[26:27], v[26:27], v[26:27]
	v_pk_mul_f32 v[28:29], v[28:29], v[28:29]
	v_cvt_pk_bf16_f32 v26, v26, v27
	v_cvt_pk_bf16_f32 v27, v28, v29
	ds_write_b64 v134, v[26:27] offset:96
	v_mul_f32_e32 v30, v30, v147
	v_mul_f32_e32 v31, v31, v147
	v_mul_f32_e32 v32, v32, v147
	v_mul_f32_e32 v33, v33, v147
	v_max_f32_e32 v30, 0, v30
	v_max_f32_e32 v31, 0, v31
	v_max_f32_e32 v32, 0, v32
	v_max_f32_e32 v33, 0, v33
	v_pk_mul_f32 v[30:31], v[30:31], v[30:31]
	v_pk_mul_f32 v[32:33], v[32:33], v[32:33]
	v_cvt_pk_bf16_f32 v30, v30, v31
	v_cvt_pk_bf16_f32 v31, v32, v33
	ds_write_b64 v134, v[30:31] offset:4320
	s_waitcnt lgkmcnt(0)
	s_barrier
	ds_read_b64 v[18:19], v135
	ds_read_b64 v[20:21], v135 offset:4224
	ds_read_b64 v[22:23], v135 offset:8448
	ds_read_b64 v[24:25], v135 offset:12672
	ds_read_b64 v[26:27], v135 offset:16896
	ds_read_b64 v[28:29], v135 offset:21120
	ds_read_b64 v[30:31], v135 offset:25344
	ds_read_b64 v[32:33], v135 offset:29568
	s_waitcnt lgkmcnt(7)
	v_add_u32_e32 v136, 0x100000, v132
	global_store_dwordx2 v136, v[18:19], s[6:7] offset:256
	s_waitcnt lgkmcnt(6)
	v_add_u32_e32 v136, 0x120000, v132
	global_store_dwordx2 v136, v[20:21], s[6:7] offset:256
	s_waitcnt lgkmcnt(5)
	v_add_u32_e32 v136, 0x140000, v132
	global_store_dwordx2 v136, v[22:23], s[6:7] offset:256
	s_waitcnt lgkmcnt(4)
	v_add_u32_e32 v136, 0x160000, v132
	global_store_dwordx2 v136, v[24:25], s[6:7] offset:256
	s_waitcnt lgkmcnt(3)
	v_add_u32_e32 v136, 0x180000, v132
	global_store_dwordx2 v136, v[26:27], s[6:7] offset:256
	s_waitcnt lgkmcnt(2)
	v_add_u32_e32 v136, 0x1a0000, v132
	global_store_dwordx2 v136, v[28:29], s[6:7] offset:256
	s_waitcnt lgkmcnt(1)
	v_add_u32_e32 v136, 0x1c0000, v132
	global_store_dwordx2 v136, v[30:31], s[6:7] offset:256
	s_waitcnt lgkmcnt(0)
	v_add_u32_e32 v136, 0x1e0000, v132
	global_store_dwordx2 v136, v[32:33], s[6:7] offset:256
	s_add_i32 s22, s22, s60
	v_readlane_b32 s0, v246, 4
	s_cmp_ge_i32 s22, s0
	s_barrier
	s_cbranch_scc0 .LBB0_29

; DI unsigned pk2(float a, float b) { f32x2 v = {a, b}; bf2_t r = __builtin_convertvector(v, bf2_t); return __builtin_bit_cast(unsigned, r); }
; DI f32x4 unpk4(u32x2 u) { f32x4 r = {__uint_as_float(u[0] << 16), __uint_as_float(u[0] & 0xffff0000u), __uint_as_float(u[1] << 16), __uint_as_float(u[1] & 0xffff0000u)}; return r; }
; template <int MODE>
; DI void gemm_tile(const Params& p, const bf16_t* __restrict__ A, const bf16_t* __restrict__ Bt, int K, int brow, int bcol, int mp, int nt, bool vt, char* smem) {
;     ...
;   u32x2 xnx[4];
;   if (RESID) {
; #pragma unroll
;     for (int pq = 0; pq < 4; ++pq) xnx[pq] = *(const u32x2*)((const bf16_t*)(p.ws + OFF_XB) + (size_t)(m0 + pq * 16 + (tid >> 5)) * DM + n0 + (tid & 31) * 4);
;   }
; #pragma unroll
;   for (int ai = 0; ai < 2; ++ai)
; #pragma unroll
;     for (int bj = 0; bj < 2; ++bj) {
; #pragma unroll
;       for (int m = 0; m < 4; ++m)
; #pragma unroll
;         for (int n = 0; n < 2; ++n) *(f32x4*)(st + (wc * 32 + n * 16 + fr) * 132 + wr * 64 + m * 16 + fq * 4) = acc[ai][bj][m][n];
;       __syncthreads();
; #pragma unroll 1
;       for (int pg = 0; pg < 2; ++pg) {
;       u32x2 xo[4];
;       if (RESID) {
; #pragma unroll
;         for (int pq = 0; pq < 4; ++pq) xo[pq] = xnx[pq];
;         const int q = ai * 2 + bj, nq = pg ? q + 1 : q, npg = pg ^ 1;
;         if (nq < 4) {
;           const int nai = nq >> 1, nbj = nq & 1;
; #pragma unroll
;           for (int pq = 0; pq < 4; ++pq)
;             xnx[pq] = *(const u32x2*)((const bf16_t*)(p.ws + OFF_XB) + (size_t)(m0 + nbj * 128 + (npg * 4 + pq) * 16 + (tid >> 5)) * DM + n0 + nai * 128 + (tid & 31) * 4);
;     ...
;           const int tok = m0 + bj * 128 + y, col = n0 + ai * 128 + x4;
;           const f32x4 xs = unpk4(xo[pq]) + v;
;           u32x2 o = {pk2(xs[0], xs[1]), pk2(xs[2], xs[3])};
;           *(u32x2*)((bf16_t*)(p.ws + OFF_XB) + (size_t)tok * DM + col) = o;
;           const f32x4 xn = unpk4(o);
;           float ss = xn[0] * xn[0] + xn[1] * xn[1] + xn[2] * xn[2] + xn[3] * xn[3];
; #pragma unroll
;           for (int o2 = 16; o2 > 0; o2 >>= 1) ss += __shfl_xor(ss, o2);
;           if ((tid & 31) == 0) ((float*)(p.ws + (MODE == MODE_OUT ? OFF_SSB : OFF_SSA)))[(size_t)tok * 8 + nt * 2 + ai] = ss;
.LBB0_62:
	s_or_b64 exec, exec, s[6:7]
	v_lshrrev_b32_e32 v130, 5, v152
	v_and_b32_e32 v131, 31, v152
	v_cmp_eq_u32_e64 s[10:11], 0, v131
	v_lshlrev_b32_e32 v136, 3, v131
	v_add_u32_e32 v137, s4, v130
	s_lshl_b32 s5, s2, 1
	v_lshl_add_u32 v132, v137, 11, v136
	v_add_u32_e32 v132, s5, v132
	v_lshlrev_b32_e32 v133, 5, v137
	v_bfe_u32 v136, v152, 6, 2
	v_and_b32_e32 v137, 15, v152
	v_lshl_add_u32 v136, v136, 5, v137
	v_mul_u32_u24_e32 v136, 0x210, v136
	v_lshrrev_b32_e32 v137, 8, v152
	v_lshl_add_u32 v136, v137, 8, v136
	v_bfe_u32 v137, v152, 4, 2
	v_lshl_add_u32 v134, v137, 4, v136
	v_mul_u32_u24_e32 v136, 0x210, v130
	v_lshl_add_u32 v135, v131, 4, v136
	v_readlane_b32 s6, v247, 7
	v_readlane_b32 s7, v247, 8
	v_readlane_b32 s8, v246, 12
	v_readlane_b32 s9, v246, 13
	s_lshl_b32 s12, s23, 3
	s_nop 1
	s_add_u32 s8, s8, s12
	s_addc_u32 s9, s9, 0
	s_nop 4
	global_load_dwordx2 v[164:165], v132, s[6:7]
	v_add_u32_e32 v136, 0x8000, v132
	global_load_dwordx2 v[166:167], v136, s[6:7]
	v_add_u32_e32 v136, 0x10000, v132
	global_load_dwordx2 v[168:169], v136, s[6:7]
	v_add_u32_e32 v136, 0x18000, v132
	global_load_dwordx2 v[170:171], v136, s[6:7]
	v_add_u32_e32 v136, 0x20000, v132
	global_load_dwordx2 v[172:173], v136, s[6:7]
	v_add_u32_e32 v136, 0x28000, v132
	global_load_dwordx2 v[174:175], v136, s[6:7]
	v_add_u32_e32 v136, 0x30000, v132
	global_load_dwordx2 v[176:177], v136, s[6:7]
	v_add_u32_e32 v136, 0x38000, v132
	global_load_dwordx2 v[178:179], v136, s[6:7]
	v_add_u32_e32 v136, 0x40000, v132
	global_load_dwordx2 v[180:181], v136, s[6:7]
	v_add_u32_e32 v136, 0x48000, v132
	global_load_dwordx2 v[182:183], v136, s[6:7]
	v_add_u32_e32 v136, 0x50000, v132
	global_load_dwordx2 v[184:185], v136, s[6:7]
	v_add_u32_e32 v136, 0x58000, v132
	global_load_dwordx2 v[186:187], v136, s[6:7]
	v_add_u32_e32 v136, 0x60000, v132
	global_load_dwordx2 v[188:189], v136, s[6:7]
	v_add_u32_e32 v136, 0x68000, v132
	global_load_dwordx2 v[190:191], v136, s[6:7]
	v_add_u32_e32 v136, 0x70000, v132
	global_load_dwordx2 v[192:193], v136, s[6:7]
	v_add_u32_e32 v136, 0x78000, v132
	global_load_dwordx2 v[194:195], v136, s[6:7]
	global_load_dwordx2 v[196:197], v132, s[6:7] offset:256
	v_add_u32_e32 v136, 0x8000, v132
	global_load_dwordx2 v[198:199], v136, s[6:7] offset:256
	v_add_u32_e32 v136, 0x10000, v132
	global_load_dwordx2 v[214:215], v136, s[6:7] offset:256
	v_add_u32_e32 v136, 0x18000, v132
	global_load_dwordx2 v[216:217], v136, s[6:7] offset:256
	v_add_u32_e32 v136, 0x20000, v132
	global_load_dwordx2 v[218:219], v136, s[6:7] offset:256
	v_add_u32_e32 v136, 0x28000, v132
	global_load_dwordx2 v[220:221], v136, s[6:7] offset:256
	v_add_u32_e32 v136, 0x30000, v132
	global_load_dwordx2 v[222:223], v136, s[6:7] offset:256
	v_add_u32_e32 v136, 0x38000, v132
	global_load_dwordx2 v[224:225], v136, s[6:7] offset:256
	v_add_u32_e32 v136, 0x40000, v132
	global_load_dwordx2 v[226:227], v136, s[6:7] offset:256
	v_add_u32_e32 v136, 0x48000, v132
	global_load_dwordx2 v[228:229], v136, s[6:7] offset:256
	v_add_u32_e32 v136, 0x50000, v132
	global_load_dwordx2 v[230:231], v136, s[6:7] offset:256
	v_add_u32_e32 v136, 0x58000, v132
	global_load_dwordx2 v[232:233], v136, s[6:7] offset:256
	v_add_u32_e32 v136, 0x60000, v132
	global_load_dwordx2 v[234:235], v136, s[6:7] offset:256
	v_add_u32_e32 v136, 0x68000, v132
	global_load_dwordx2 v[236:237], v136, s[6:7] offset:256
	v_add_u32_e32 v136, 0x70000, v132
	global_load_dwordx2 v[238:239], v136, s[6:7] offset:256
	v_add_u32_e32 v136, 0x78000, v132
	global_load_dwordx2 v[240:241], v136, s[6:7] offset:256
	ds_write_b128 v134, v[98:101]
	ds_write_b128 v134, v[102:105] offset:8448
	ds_write_b128 v134, v[106:109] offset:64
	ds_write_b128 v134, v[110:113] offset:8512
	ds_write_b128 v134, v[114:117] offset:128
	ds_write_b128 v134, v[118:121] offset:8576
	ds_write_b128 v134, v[122:125] offset:192
	ds_write_b128 v134, v[126:129] offset:8640
	s_waitcnt lgkmcnt(0)
	s_barrier
	ds_read_b128 v[98:101], v135
	ds_read_b128 v[102:105], v135 offset:8448
	ds_read_b128 v[106:109], v135 offset:16896
	ds_read_b128 v[110:113], v135 offset:25344
	ds_read_b128 v[114:117], v135 offset:33792
	ds_read_b128 v[118:121], v135 offset:42240
	ds_read_b128 v[122:125], v135 offset:50688
	ds_read_b128 v[126:129], v135 offset:59136
	s_waitcnt vmcnt(31) lgkmcnt(7)
	v_lshlrev_b32_e32 v138, 16, v164
	v_and_b32_e32 v139, 0xffff0000, v164
	v_lshlrev_b32_e32 v140, 16, v165
	v_and_b32_e32 v141, 0xffff0000, v165
	v_pk_add_f32 v[98:99], v[98:99], v[138:139]
	v_pk_add_f32 v[100:101], v[100:101], v[140:141]
	v_cvt_pk_bf16_f32 v164, v98, v99
	v_cvt_pk_bf16_f32 v165, v100, v101
	global_store_dwordx2 v132, v[164:165], s[6:7]
	v_and_b32_e32 v139, 0xffff0000, v164
	v_lshlrev_b32_e32 v138, 16, v164
	v_mul_f32_e32 v142, v139, v139
	v_lshlrev_b32_e32 v140, 16, v165
	v_fmac_f32_e32 v142, v138, v138
	v_and_b32_e32 v141, 0xffff0000, v165
	v_fmac_f32_e32 v142, v140, v140
	v_fmac_f32_e32 v142, v141, v141
	v_mov_b32_e32 v143, v142
	s_nop 1
	v_permlane16_swap_b32_e32 v143, v142
	v_add_f32_e32 v142, v142, v143
	s_nop 1
	v_mov_b32_dpp v143, v142 row_ror:8 row_mask:0xf bank_mask:0xf
	v_add_f32_e32 v142, v142, v143
	s_nop 1
	v_mov_b32_dpp v143, v142 row_ror:4 row_mask:0xf bank_mask:0xf
	v_add_f32_e32 v142, v142, v143
	s_nop 1
	v_mov_b32_dpp v143, v142 row_ror:2 row_mask:0xf bank_mask:0xf
	v_add_f32_e32 v142, v142, v143
	s_nop 1
	v_mov_b32_dpp v143, v142 row_ror:1 row_mask:0xf bank_mask:0xf
	v_add_f32_e32 v142, v142, v143
	s_mov_b64 exec, s[10:11]
	global_store_dword v133, v142, s[8:9]
	s_mov_b64 exec, -1
	s_waitcnt vmcnt(32) lgkmcnt(6)
; DI unsigned pk2(float a, float b) { f32x2 v = {a, b}; bf2_t r = __builtin_convertvector(v, bf2_t); return __builtin_bit_cast(unsigned, r); }
; DI f32x4 unpk4(u32x2 u) { f32x4 r = {__uint_as_float(u[0] << 16), __uint_as_float(u[0] & 0xffff0000u), __uint_as_float(u[1] << 16), __uint_as_float(u[1] & 0xffff0000u)}; return r; }
; template <int MODE>
; DI void gemm_tile(const Params& p, const bf16_t* __restrict__ A, const bf16_t* __restrict__ Bt, int K, int brow, int bcol, int mp, int nt, bool vt, char* smem) {
;     ...
;           const int tok = m0 + bj * 128 + y, col = n0 + ai * 128 + x4;
;           const f32x4 xs = unpk4(xo[pq]) + v;
;           u32x2 o = {pk2(xs[0], xs[1]), pk2(xs[2], xs[3])};
;           *(u32x2*)((bf16_t*)(p.ws + OFF_XB) + (size_t)tok * DM + col) = o;
;           const f32x4 xn = unpk4(o);
;           float ss = xn[0] * xn[0] + xn[1] * xn[1] + xn[2] * xn[2] + xn[3] * xn[3];
; #pragma unroll
;           for (int o2 = 16; o2 > 0; o2 >>= 1) ss += __shfl_xor(ss, o2);
;           if ((tid & 31) == 0) ((float*)(p.ws + (MODE == MODE_OUT ? OFF_SSB : OFF_SSA)))[(size_t)tok * 8 + nt * 2 + ai] = ss;
	v_lshlrev_b32_e32 v138, 16, v166
	v_and_b32_e32 v139, 0xffff0000, v166
	v_lshlrev_b32_e32 v140, 16, v167
	v_and_b32_e32 v141, 0xffff0000, v167
	v_pk_add_f32 v[102:103], v[102:103], v[138:139]
	v_pk_add_f32 v[104:105], v[104:105], v[140:141]
	v_cvt_pk_bf16_f32 v166, v102, v103
	v_cvt_pk_bf16_f32 v167, v104, v105
	v_add_u32_e32 v136, 0x8000, v132
	global_store_dwordx2 v136, v[166:167], s[6:7]
	v_and_b32_e32 v139, 0xffff0000, v166
	v_lshlrev_b32_e32 v138, 16, v166
	v_mul_f32_e32 v142, v139, v139
	v_lshlrev_b32_e32 v140, 16, v167
	v_fmac_f32_e32 v142, v138, v138
	v_and_b32_e32 v141, 0xffff0000, v167
	v_fmac_f32_e32 v142, v140, v140
	v_fmac_f32_e32 v142, v141, v141
	v_mov_b32_e32 v143, v142
	s_nop 1
	v_permlane16_swap_b32_e32 v143, v142
	v_add_f32_e32 v142, v142, v143
	s_nop 1
	v_mov_b32_dpp v143, v142 row_ror:8 row_mask:0xf bank_mask:0xf
	v_add_f32_e32 v142, v142, v143
	s_nop 1
	v_mov_b32_dpp v143, v142 row_ror:4 row_mask:0xf bank_mask:0xf
	v_add_f32_e32 v142, v142, v143
	s_nop 1
	v_mov_b32_dpp v143, v142 row_ror:2 row_mask:0xf bank_mask:0xf
	v_add_f32_e32 v142, v142, v143
	s_nop 1
	v_mov_b32_dpp v143, v142 row_ror:1 row_mask:0xf bank_mask:0xf
	v_add_f32_e32 v142, v142, v143
	v_add_u32_e32 v137, 0x200, v133
	s_mov_b64 exec, s[10:11]
	global_store_dword v137, v142, s[8:9]
	s_mov_b64 exec, -1
	s_waitcnt vmcnt(33) lgkmcnt(5)
	v_lshlrev_b32_e32 v138, 16, v168
	v_and_b32_e32 v139, 0xffff0000, v168
	v_lshlrev_b32_e32 v140, 16, v169
	v_and_b32_e32 v141, 0xffff0000, v169
	v_pk_add_f32 v[106:107], v[106:107], v[138:139]
	v_pk_add_f32 v[108:109], v[108:109], v[140:141]
	v_cvt_pk_bf16_f32 v168, v106, v107
	v_cvt_pk_bf16_f32 v169, v108, v109
	v_add_u32_e32 v136, 0x10000, v132
	global_store_dwordx2 v136, v[168:169], s[6:7]
	v_and_b32_e32 v139, 0xffff0000, v168
	v_lshlrev_b32_e32 v138, 16, v168
	v_mul_f32_e32 v142, v139, v139
	v_lshlrev_b32_e32 v140, 16, v169
	v_fmac_f32_e32 v142, v138, v138
	v_and_b32_e32 v141, 0xffff0000, v169
	v_fmac_f32_e32 v142, v140, v140
	v_fmac_f32_e32 v142, v141, v141
	v_mov_b32_e32 v143, v142
	s_nop 1
	v_permlane16_swap_b32_e32 v143, v142
	v_add_f32_e32 v142, v142, v143
	s_nop 1
	v_mov_b32_dpp v143, v142 row_ror:8 row_mask:0xf bank_mask:0xf
	v_add_f32_e32 v142, v142, v143
	s_nop 1
	v_mov_b32_dpp v143, v142 row_ror:4 row_mask:0xf bank_mask:0xf
	v_add_f32_e32 v142, v142, v143
	s_nop 1
	v_mov_b32_dpp v143, v142 row_ror:2 row_mask:0xf bank_mask:0xf
	v_add_f32_e32 v142, v142, v143
	s_nop 1
	v_mov_b32_dpp v143, v142 row_ror:1 row_mask:0xf bank_mask:0xf
	v_add_f32_e32 v142, v142, v143
	v_add_u32_e32 v137, 0x400, v133
	s_mov_b64 exec, s[10:11]
	global_store_dword v137, v142, s[8:9]
	s_mov_b64 exec, -1
	s_waitcnt vmcnt(34) lgkmcnt(4)
	v_lshlrev_b32_e32 v138, 16, v170
	v_and_b32_e32 v139, 0xffff0000, v170
	v_lshlrev_b32_e32 v140, 16, v171
	v_and_b32_e32 v141, 0xffff0000, v171
	v_pk_add_f32 v[110:111], v[110:111], v[138:139]
	v_pk_add_f32 v[112:113], v[112:113], v[140:141]
	v_cvt_pk_bf16_f32 v170, v110, v111
	v_cvt_pk_bf16_f32 v171, v112, v113
	v_add_u32_e32 v136, 0x18000, v132
	global_store_dwordx2 v136, v[170:171], s[6:7]
	v_and_b32_e32 v139, 0xffff0000, v170
	v_lshlrev_b32_e32 v138, 16, v170
	v_mul_f32_e32 v142, v139, v139
	v_lshlrev_b32_e32 v140, 16, v171
	v_fmac_f32_e32 v142, v138, v138
	v_and_b32_e32 v141, 0xffff0000, v171
	v_fmac_f32_e32 v142, v140, v140
	v_fmac_f32_e32 v142, v141, v141
	v_mov_b32_e32 v143, v142
	s_nop 1
	v_permlane16_swap_b32_e32 v143, v142
	v_add_f32_e32 v142, v142, v143
	s_nop 1
	v_mov_b32_dpp v143, v142 row_ror:8 row_mask:0xf bank_mask:0xf
	v_add_f32_e32 v142, v142, v143
	s_nop 1
	v_mov_b32_dpp v143, v142 row_ror:4 row_mask:0xf bank_mask:0xf
	v_add_f32_e32 v142, v142, v143
	s_nop 1
	v_mov_b32_dpp v143, v142 row_ror:2 row_mask:0xf bank_mask:0xf
	v_add_f32_e32 v142, v142, v143
	s_nop 1
	v_mov_b32_dpp v143, v142 row_ror:1 row_mask:0xf bank_mask:0xf
	v_add_f32_e32 v142, v142, v143
	v_add_u32_e32 v137, 0x600, v133
	s_mov_b64 exec, s[10:11]
	global_store_dword v137, v142, s[8:9]
	s_mov_b64 exec, -1
	s_waitcnt vmcnt(35) lgkmcnt(3)
	v_lshlrev_b32_e32 v138, 16, v172
	v_and_b32_e32 v139, 0xffff0000, v172
	v_lshlrev_b32_e32 v140, 16, v173
	v_and_b32_e32 v141, 0xffff0000, v173
	v_pk_add_f32 v[114:115], v[114:115], v[138:139]
	v_pk_add_f32 v[116:117], v[116:117], v[140:141]
	v_cvt_pk_bf16_f32 v172, v114, v115
	v_cvt_pk_bf16_f32 v173, v116, v117
	v_add_u32_e32 v136, 0x20000, v132
	global_store_dwordx2 v136, v[172:173], s[6:7]
	v_and_b32_e32 v139, 0xffff0000, v172
	v_lshlrev_b32_e32 v138, 16, v172
	v_mul_f32_e32 v142, v139, v139
	v_lshlrev_b32_e32 v140, 16, v173
	v_fmac_f32_e32 v142, v138, v138
	v_and_b32_e32 v141, 0xffff0000, v173
	v_fmac_f32_e32 v142, v140, v140
	v_fmac_f32_e32 v142, v141, v141
	v_mov_b32_e32 v143, v142
	s_nop 1
	v_permlane16_swap_b32_e32 v143, v142
	v_add_f32_e32 v142, v142, v143
	s_nop 1
	v_mov_b32_dpp v143, v142 row_ror:8 row_mask:0xf bank_mask:0xf
	v_add_f32_e32 v142, v142, v143
	s_nop 1
	v_mov_b32_dpp v143, v142 row_ror:4 row_mask:0xf bank_mask:0xf
	v_add_f32_e32 v142, v142, v143
	s_nop 1
	v_mov_b32_dpp v143, v142 row_ror:2 row_mask:0xf bank_mask:0xf
	v_add_f32_e32 v142, v142, v143
	s_nop 1
	v_mov_b32_dpp v143, v142 row_ror:1 row_mask:0xf bank_mask:0xf
	v_add_f32_e32 v142, v142, v143
	v_add_u32_e32 v137, 0x800, v133
	s_mov_b64 exec, s[10:11]
	global_store_dword v137, v142, s[8:9]
	s_mov_b64 exec, -1
	s_waitcnt vmcnt(36) lgkmcnt(2)
; DI unsigned pk2(float a, float b) { f32x2 v = {a, b}; bf2_t r = __builtin_convertvector(v, bf2_t); return __builtin_bit_cast(unsigned, r); }
; DI f32x4 unpk4(u32x2 u) { f32x4 r = {__uint_as_float(u[0] << 16), __uint_as_float(u[0] & 0xffff0000u), __uint_as_float(u[1] << 16), __uint_as_float(u[1] & 0xffff0000u)}; return r; }
; template <int MODE>
; DI void gemm_tile(const Params& p, const bf16_t* __restrict__ A, const bf16_t* __restrict__ Bt, int K, int brow, int bcol, int mp, int nt, bool vt, char* smem) {
;     ...
;   for (int ai = 0; ai < 2; ++ai)
; #pragma unroll
;     for (int bj = 0; bj < 2; ++bj) {
; #pragma unroll
;       for (int m = 0; m < 4; ++m)
; #pragma unroll
;         for (int n = 0; n < 2; ++n) *(f32x4*)(st + (wc * 32 + n * 16 + fr) * 132 + wr * 64 + m * 16 + fq * 4) = acc[ai][bj][m][n];
;       __syncthreads();
;     ...
;           const int tok = m0 + bj * 128 + y, col = n0 + ai * 128 + x4;
;           const f32x4 xs = unpk4(xo[pq]) + v;
;           u32x2 o = {pk2(xs[0], xs[1]), pk2(xs[2], xs[3])};
;           *(u32x2*)((bf16_t*)(p.ws + OFF_XB) + (size_t)tok * DM + col) = o;
;           const f32x4 xn = unpk4(o);
;           float ss = xn[0] * xn[0] + xn[1] * xn[1] + xn[2] * xn[2] + xn[3] * xn[3];
; #pragma unroll
;           for (int o2 = 16; o2 > 0; o2 >>= 1) ss += __shfl_xor(ss, o2);
;           if ((tid & 31) == 0) ((float*)(p.ws + (MODE == MODE_OUT ? OFF_SSB : OFF_SSA)))[(size_t)tok * 8 + nt * 2 + ai] = ss;
	v_lshlrev_b32_e32 v138, 16, v174
	v_and_b32_e32 v139, 0xffff0000, v174
	v_lshlrev_b32_e32 v140, 16, v175
	v_and_b32_e32 v141, 0xffff0000, v175
	v_pk_add_f32 v[118:119], v[118:119], v[138:139]
	v_pk_add_f32 v[120:121], v[120:121], v[140:141]
	v_cvt_pk_bf16_f32 v174, v118, v119
	v_cvt_pk_bf16_f32 v175, v120, v121
	v_add_u32_e32 v136, 0x28000, v132
	global_store_dwordx2 v136, v[174:175], s[6:7]
	v_and_b32_e32 v139, 0xffff0000, v174
	v_lshlrev_b32_e32 v138, 16, v174
	v_mul_f32_e32 v142, v139, v139
	v_lshlrev_b32_e32 v140, 16, v175
	v_fmac_f32_e32 v142, v138, v138
	v_and_b32_e32 v141, 0xffff0000, v175
	v_fmac_f32_e32 v142, v140, v140
	v_fmac_f32_e32 v142, v141, v141
	v_mov_b32_e32 v143, v142
	s_nop 1
	v_permlane16_swap_b32_e32 v143, v142
	v_add_f32_e32 v142, v142, v143
	s_nop 1
	v_mov_b32_dpp v143, v142 row_ror:8 row_mask:0xf bank_mask:0xf
	v_add_f32_e32 v142, v142, v143
	s_nop 1
	v_mov_b32_dpp v143, v142 row_ror:4 row_mask:0xf bank_mask:0xf
	v_add_f32_e32 v142, v142, v143
	s_nop 1
	v_mov_b32_dpp v143, v142 row_ror:2 row_mask:0xf bank_mask:0xf
	v_add_f32_e32 v142, v142, v143
	s_nop 1
	v_mov_b32_dpp v143, v142 row_ror:1 row_mask:0xf bank_mask:0xf
	v_add_f32_e32 v142, v142, v143
	v_add_u32_e32 v137, 0xa00, v133
	s_mov_b64 exec, s[10:11]
	global_store_dword v137, v142, s[8:9]
	s_mov_b64 exec, -1
	s_waitcnt vmcnt(37) lgkmcnt(1)
	v_lshlrev_b32_e32 v138, 16, v176
	v_and_b32_e32 v139, 0xffff0000, v176
	v_lshlrev_b32_e32 v140, 16, v177
	v_and_b32_e32 v141, 0xffff0000, v177
	v_pk_add_f32 v[122:123], v[122:123], v[138:139]
	v_pk_add_f32 v[124:125], v[124:125], v[140:141]
	v_cvt_pk_bf16_f32 v176, v122, v123
	v_cvt_pk_bf16_f32 v177, v124, v125
	v_add_u32_e32 v136, 0x30000, v132
	global_store_dwordx2 v136, v[176:177], s[6:7]
	v_and_b32_e32 v139, 0xffff0000, v176
	v_lshlrev_b32_e32 v138, 16, v176
	v_mul_f32_e32 v142, v139, v139
	v_lshlrev_b32_e32 v140, 16, v177
	v_fmac_f32_e32 v142, v138, v138
	v_and_b32_e32 v141, 0xffff0000, v177
	v_fmac_f32_e32 v142, v140, v140
	v_fmac_f32_e32 v142, v141, v141
	v_mov_b32_e32 v143, v142
	s_nop 1
	v_permlane16_swap_b32_e32 v143, v142
	v_add_f32_e32 v142, v142, v143
	s_nop 1
	v_mov_b32_dpp v143, v142 row_ror:8 row_mask:0xf bank_mask:0xf
	v_add_f32_e32 v142, v142, v143
	s_nop 1
	v_mov_b32_dpp v143, v142 row_ror:4 row_mask:0xf bank_mask:0xf
	v_add_f32_e32 v142, v142, v143
	s_nop 1
	v_mov_b32_dpp v143, v142 row_ror:2 row_mask:0xf bank_mask:0xf
	v_add_f32_e32 v142, v142, v143
	s_nop 1
	v_mov_b32_dpp v143, v142 row_ror:1 row_mask:0xf bank_mask:0xf
	v_add_f32_e32 v142, v142, v143
	v_add_u32_e32 v137, 0xc00, v133
	s_mov_b64 exec, s[10:11]
	global_store_dword v137, v142, s[8:9]
	s_mov_b64 exec, -1
	s_waitcnt vmcnt(38) lgkmcnt(0)
	v_lshlrev_b32_e32 v138, 16, v178
	v_and_b32_e32 v139, 0xffff0000, v178
	v_lshlrev_b32_e32 v140, 16, v179
	v_and_b32_e32 v141, 0xffff0000, v179
	v_pk_add_f32 v[126:127], v[126:127], v[138:139]
	v_pk_add_f32 v[128:129], v[128:129], v[140:141]
	v_cvt_pk_bf16_f32 v178, v126, v127
	v_cvt_pk_bf16_f32 v179, v128, v129
	v_add_u32_e32 v136, 0x38000, v132
	global_store_dwordx2 v136, v[178:179], s[6:7]
	v_and_b32_e32 v139, 0xffff0000, v178
	v_lshlrev_b32_e32 v138, 16, v178
	v_mul_f32_e32 v142, v139, v139
	v_lshlrev_b32_e32 v140, 16, v179
	v_fmac_f32_e32 v142, v138, v138
	v_and_b32_e32 v141, 0xffff0000, v179
	v_fmac_f32_e32 v142, v140, v140
	v_fmac_f32_e32 v142, v141, v141
	v_mov_b32_e32 v143, v142
	s_nop 1
	v_permlane16_swap_b32_e32 v143, v142
	v_add_f32_e32 v142, v142, v143
	s_nop 1
	v_mov_b32_dpp v143, v142 row_ror:8 row_mask:0xf bank_mask:0xf
	v_add_f32_e32 v142, v142, v143
	s_nop 1
	v_mov_b32_dpp v143, v142 row_ror:4 row_mask:0xf bank_mask:0xf
	v_add_f32_e32 v142, v142, v143
	s_nop 1
	v_mov_b32_dpp v143, v142 row_ror:2 row_mask:0xf bank_mask:0xf
	v_add_f32_e32 v142, v142, v143
	s_nop 1
	v_mov_b32_dpp v143, v142 row_ror:1 row_mask:0xf bank_mask:0xf
	v_add_f32_e32 v142, v142, v143
	v_add_u32_e32 v137, 0xe00, v133
	s_mov_b64 exec, s[10:11]
	global_store_dword v137, v142, s[8:9]
	s_mov_b64 exec, -1
	s_barrier
	ds_write_b128 v134, v[66:69]
	ds_write_b128 v134, v[70:73] offset:8448
	ds_write_b128 v134, v[74:77] offset:64
	ds_write_b128 v134, v[78:81] offset:8512
	ds_write_b128 v134, v[82:85] offset:128
	ds_write_b128 v134, v[86:89] offset:8576
	ds_write_b128 v134, v[90:93] offset:192
	ds_write_b128 v134, v[94:97] offset:8640
	s_waitcnt lgkmcnt(0)
	s_barrier
; template <int MODE>
; DI void gemm_tile(const Params& p, const bf16_t* __restrict__ A, const bf16_t* __restrict__ Bt, int K, int brow, int bcol, int mp, int nt, bool vt, char* smem) {
;     ...
;       for (int pq = 0; pq < 4; ++pq) {
;         const int pass = pg * 4 + pq;
;         const int y = pass * 16 + (tid >> 5), x4 = (tid & 31) * 4;
;         const f32x4 v = *(const f32x4*)(st + y * 132 + x4);
;         if (MODE == MODE_PROJ) {
;           if (vt) {
;             const int vrow = (nt - 8) * 256 + bj * 128 + y, tk = m0 + ai * 128 + x4, b = tk >> 11, sq = tk & 2047;
;             const f32x4 rr = *(const f32x4*)(rsl + ai * 128 + x4);
;             u32x2 o = {pk2(v[0] * rr[0], v[1] * rr[1]), pk2(v[2] * rr[2], v[3] * rr[3])};
;             *(u32x2*)((bf16_t*)(p.ws + OFF_VT) + ((size_t)(b * VROWS + vrow)) * SEQ + sq) = o;
;           } else {
;             const int tok = m0 + bj * 128 + y, col = n0 + ai * 128 + x4;
;             const float rs = rsl[bj * 128 + y];
;             if (col < QKW) {
;               u32x2 o = {pk2(v[0] * rs, v[1] * rs), pk2(v[2] * rs, v[3] * rs)};
;               *(u32x2*)((bf16_t*)(p.ws + OFF_QK) + (size_t)tok * QKW + col) = o;
;             } else if (col < QKW + 16) {
;               f32x4 o = {v[0] * rs, v[1] * rs, v[2] * rs, v[3] * rs};
;               *(f32x4*)((float*)(p.ws + OFF_GATE) + (size_t)tok * 16 + (col - QKW)) = o;
;             }
;           }
;         } else if (MODE == MODE_UP) {
;           const int tok = m0 + bj * 128 + y, col = n0 + ai * 128 + x4;
;           const float rs = rsl[bj * 128 + y];
;           const float a0 = fmaxf(v[0] * rs, 0.f), a1 = fmaxf(v[1] * rs, 0.f), a2 = fmaxf(v[2] * rs, 0.f), a3 = fmaxf(v[3] * rs, 0.f);
;           u32x2 o = {pk2(a0 * a0, a1 * a1), pk2(a2 * a2, a3 * a3)};
;           *(u32x2*)((bf16_t*)(p.ws + OFF_U) + (size_t)tok * DFF + col) = o;
;         } else {
;           const int tok = m0 + bj * 128 + y, col = n0 + ai * 128 + x4;
;           const f32x4 xs = unpk4(xo[pq]) + v;
;           u32x2 o = {pk2(xs[0], xs[1]), pk2(xs[2], xs[3])};
;           *(u32x2*)((bf16_t*)(p.ws + OFF_XB) + (size_t)tok * DM + col) = o;
;           const f32x4 xn = unpk4(o);
;           float ss = xn[0] * xn[0] + xn[1] * xn[1] + xn[2] * xn[2] + xn[3] * xn[3];
; #pragma unroll
;           for (int o2 = 16; o2 > 0; o2 >>= 1) ss += __shfl_xor(ss, o2);
	ds_read_b128 v[66:69], v135
	ds_read_b128 v[70:73], v135 offset:8448
	ds_read_b128 v[74:77], v135 offset:16896
	ds_read_b128 v[78:81], v135 offset:25344
	ds_read_b128 v[82:85], v135 offset:33792
	ds_read_b128 v[86:89], v135 offset:42240
	ds_read_b128 v[90:93], v135 offset:50688
	ds_read_b128 v[94:97], v135 offset:59136
	s_waitcnt vmcnt(39) lgkmcnt(7)
	v_lshlrev_b32_e32 v138, 16, v180
	v_and_b32_e32 v139, 0xffff0000, v180
	v_lshlrev_b32_e32 v140, 16, v181
	v_and_b32_e32 v141, 0xffff0000, v181
	v_pk_add_f32 v[66:67], v[66:67], v[138:139]
	v_pk_add_f32 v[68:69], v[68:69], v[140:141]
	v_cvt_pk_bf16_f32 v180, v66, v67
	v_cvt_pk_bf16_f32 v181, v68, v69
	v_add_u32_e32 v136, 0x40000, v132
	global_store_dwordx2 v136, v[180:181], s[6:7]
	v_and_b32_e32 v139, 0xffff0000, v180
	v_lshlrev_b32_e32 v138, 16, v180
	v_mul_f32_e32 v142, v139, v139
	v_lshlrev_b32_e32 v140, 16, v181
	v_fmac_f32_e32 v142, v138, v138
	v_and_b32_e32 v141, 0xffff0000, v181
	v_fmac_f32_e32 v142, v140, v140
	v_fmac_f32_e32 v142, v141, v141
	v_mov_b32_e32 v143, v142
	s_nop 1
	v_permlane16_swap_b32_e32 v143, v142
	v_add_f32_e32 v142, v142, v143
	s_nop 1
	v_mov_b32_dpp v143, v142 row_ror:8 row_mask:0xf bank_mask:0xf
	v_add_f32_e32 v142, v142, v143
	s_nop 1
	v_mov_b32_dpp v143, v142 row_ror:4 row_mask:0xf bank_mask:0xf
	v_add_f32_e32 v142, v142, v143
	s_nop 1
	v_mov_b32_dpp v143, v142 row_ror:2 row_mask:0xf bank_mask:0xf
	v_add_f32_e32 v142, v142, v143
	s_nop 1
	v_mov_b32_dpp v143, v142 row_ror:1 row_mask:0xf bank_mask:0xf
	v_add_f32_e32 v142, v142, v143
	v_add_u32_e32 v137, 0x1000, v133
	s_mov_b64 exec, s[10:11]
	global_store_dword v137, v142, s[8:9]
	s_mov_b64 exec, -1
	s_waitcnt vmcnt(40) lgkmcnt(6)
	v_lshlrev_b32_e32 v138, 16, v182
	v_and_b32_e32 v139, 0xffff0000, v182
	v_lshlrev_b32_e32 v140, 16, v183
	v_and_b32_e32 v141, 0xffff0000, v183
	v_pk_add_f32 v[70:71], v[70:71], v[138:139]
	v_pk_add_f32 v[72:73], v[72:73], v[140:141]
	v_cvt_pk_bf16_f32 v182, v70, v71
	v_cvt_pk_bf16_f32 v183, v72, v73
	v_add_u32_e32 v136, 0x48000, v132
	global_store_dwordx2 v136, v[182:183], s[6:7]
	v_and_b32_e32 v139, 0xffff0000, v182
	v_lshlrev_b32_e32 v138, 16, v182
	v_mul_f32_e32 v142, v139, v139
	v_lshlrev_b32_e32 v140, 16, v183
	v_fmac_f32_e32 v142, v138, v138
	v_and_b32_e32 v141, 0xffff0000, v183
	v_fmac_f32_e32 v142, v140, v140
	v_fmac_f32_e32 v142, v141, v141
	v_mov_b32_e32 v143, v142
	s_nop 1
	v_permlane16_swap_b32_e32 v143, v142
	v_add_f32_e32 v142, v142, v143
	s_nop 1
	v_mov_b32_dpp v143, v142 row_ror:8 row_mask:0xf bank_mask:0xf
	v_add_f32_e32 v142, v142, v143
	s_nop 1
	v_mov_b32_dpp v143, v142 row_ror:4 row_mask:0xf bank_mask:0xf
	v_add_f32_e32 v142, v142, v143
	s_nop 1
	v_mov_b32_dpp v143, v142 row_ror:2 row_mask:0xf bank_mask:0xf
	v_add_f32_e32 v142, v142, v143
	s_nop 1
	v_mov_b32_dpp v143, v142 row_ror:1 row_mask:0xf bank_mask:0xf
	v_add_f32_e32 v142, v142, v143
	v_add_u32_e32 v137, 0x1200, v133
	s_mov_b64 exec, s[10:11]
	global_store_dword v137, v142, s[8:9]
	s_mov_b64 exec, -1
	s_waitcnt vmcnt(41) lgkmcnt(5)
	v_lshlrev_b32_e32 v138, 16, v184
	v_and_b32_e32 v139, 0xffff0000, v184
	v_lshlrev_b32_e32 v140, 16, v185
	v_and_b32_e32 v141, 0xffff0000, v185
	v_pk_add_f32 v[74:75], v[74:75], v[138:139]
	v_pk_add_f32 v[76:77], v[76:77], v[140:141]
	v_cvt_pk_bf16_f32 v184, v74, v75
	v_cvt_pk_bf16_f32 v185, v76, v77
	v_add_u32_e32 v136, 0x50000, v132
	global_store_dwordx2 v136, v[184:185], s[6:7]
	v_and_b32_e32 v139, 0xffff0000, v184
	v_lshlrev_b32_e32 v138, 16, v184
	v_mul_f32_e32 v142, v139, v139
	v_lshlrev_b32_e32 v140, 16, v185
	v_fmac_f32_e32 v142, v138, v138
	v_and_b32_e32 v141, 0xffff0000, v185
	v_fmac_f32_e32 v142, v140, v140
	v_fmac_f32_e32 v142, v141, v141
	v_mov_b32_e32 v143, v142
	s_nop 1
	v_permlane16_swap_b32_e32 v143, v142
	v_add_f32_e32 v142, v142, v143
	s_nop 1
	v_mov_b32_dpp v143, v142 row_ror:8 row_mask:0xf bank_mask:0xf
	v_add_f32_e32 v142, v142, v143
	s_nop 1
	v_mov_b32_dpp v143, v142 row_ror:4 row_mask:0xf bank_mask:0xf
	v_add_f32_e32 v142, v142, v143
	s_nop 1
	v_mov_b32_dpp v143, v142 row_ror:2 row_mask:0xf bank_mask:0xf
	v_add_f32_e32 v142, v142, v143
	s_nop 1
	v_mov_b32_dpp v143, v142 row_ror:1 row_mask:0xf bank_mask:0xf
	v_add_f32_e32 v142, v142, v143
	v_add_u32_e32 v137, 0x1400, v133
	s_mov_b64 exec, s[10:11]
	global_store_dword v137, v142, s[8:9]
	s_mov_b64 exec, -1
	s_waitcnt vmcnt(42) lgkmcnt(4)
	v_lshlrev_b32_e32 v138, 16, v186
	v_and_b32_e32 v139, 0xffff0000, v186
	v_lshlrev_b32_e32 v140, 16, v187
	v_and_b32_e32 v141, 0xffff0000, v187
	v_pk_add_f32 v[78:79], v[78:79], v[138:139]
	v_pk_add_f32 v[80:81], v[80:81], v[140:141]
	v_cvt_pk_bf16_f32 v186, v78, v79
	v_cvt_pk_bf16_f32 v187, v80, v81
	v_add_u32_e32 v136, 0x58000, v132
	global_store_dwordx2 v136, v[186:187], s[6:7]
	v_and_b32_e32 v139, 0xffff0000, v186
	v_lshlrev_b32_e32 v138, 16, v186
	v_mul_f32_e32 v142, v139, v139
	v_lshlrev_b32_e32 v140, 16, v187
	v_fmac_f32_e32 v142, v138, v138
	v_and_b32_e32 v141, 0xffff0000, v187
	v_fmac_f32_e32 v142, v140, v140
	v_fmac_f32_e32 v142, v141, v141
	v_mov_b32_e32 v143, v142
	s_nop 1
	v_permlane16_swap_b32_e32 v143, v142
	v_add_f32_e32 v142, v142, v143
	s_nop 1
	v_mov_b32_dpp v143, v142 row_ror:8 row_mask:0xf bank_mask:0xf
	v_add_f32_e32 v142, v142, v143
	s_nop 1
	v_mov_b32_dpp v143, v142 row_ror:4 row_mask:0xf bank_mask:0xf
	v_add_f32_e32 v142, v142, v143
	s_nop 1
	v_mov_b32_dpp v143, v142 row_ror:2 row_mask:0xf bank_mask:0xf
	v_add_f32_e32 v142, v142, v143
	s_nop 1
	v_mov_b32_dpp v143, v142 row_ror:1 row_mask:0xf bank_mask:0xf
	v_add_f32_e32 v142, v142, v143
	v_add_u32_e32 v137, 0x1600, v133
	s_mov_b64 exec, s[10:11]
	global_store_dword v137, v142, s[8:9]
	s_mov_b64 exec, -1
	s_waitcnt vmcnt(43) lgkmcnt(3)
; template <int MODE>
; DI void gemm_tile(const Params& p, const bf16_t* __restrict__ A, const bf16_t* __restrict__ Bt, int K, int brow, int bcol, int mp, int nt, bool vt, char* smem) {
;     ...
;       for (int pq = 0; pq < 4; ++pq) {
;         const int pass = pg * 4 + pq;
;         const int y = pass * 16 + (tid >> 5), x4 = (tid & 31) * 4;
;         const f32x4 v = *(const f32x4*)(st + y * 132 + x4);
;         if (MODE == MODE_PROJ) {
;           if (vt) {
;             const int vrow = (nt - 8) * 256 + bj * 128 + y, tk = m0 + ai * 128 + x4, b = tk >> 11, sq = tk & 2047;
;             const f32x4 rr = *(const f32x4*)(rsl + ai * 128 + x4);
;             u32x2 o = {pk2(v[0] * rr[0], v[1] * rr[1]), pk2(v[2] * rr[2], v[3] * rr[3])};
;             *(u32x2*)((bf16_t*)(p.ws + OFF_VT) + ((size_t)(b * VROWS + vrow)) * SEQ + sq) = o;
;           } else {
;             const int tok = m0 + bj * 128 + y, col = n0 + ai * 128 + x4;
;             const float rs = rsl[bj * 128 + y];
;             if (col < QKW) {
;               u32x2 o = {pk2(v[0] * rs, v[1] * rs), pk2(v[2] * rs, v[3] * rs)};
;               *(u32x2*)((bf16_t*)(p.ws + OFF_QK) + (size_t)tok * QKW + col) = o;
;             } else if (col < QKW + 16) {
;               f32x4 o = {v[0] * rs, v[1] * rs, v[2] * rs, v[3] * rs};
;               *(f32x4*)((float*)(p.ws + OFF_GATE) + (size_t)tok * 16 + (col - QKW)) = o;
;             }
;           }
;         } else if (MODE == MODE_UP) {
;           const int tok = m0 + bj * 128 + y, col = n0 + ai * 128 + x4;
;           const float rs = rsl[bj * 128 + y];
;           const float a0 = fmaxf(v[0] * rs, 0.f), a1 = fmaxf(v[1] * rs, 0.f), a2 = fmaxf(v[2] * rs, 0.f), a3 = fmaxf(v[3] * rs, 0.f);
;           u32x2 o = {pk2(a0 * a0, a1 * a1), pk2(a2 * a2, a3 * a3)};
;           *(u32x2*)((bf16_t*)(p.ws + OFF_U) + (size_t)tok * DFF + col) = o;
;         } else {
;           const int tok = m0 + bj * 128 + y, col = n0 + ai * 128 + x4;
;           const f32x4 xs = unpk4(xo[pq]) + v;
;           u32x2 o = {pk2(xs[0], xs[1]), pk2(xs[2], xs[3])};
;           *(u32x2*)((bf16_t*)(p.ws + OFF_XB) + (size_t)tok * DM + col) = o;
;           const f32x4 xn = unpk4(o);
;           float ss = xn[0] * xn[0] + xn[1] * xn[1] + xn[2] * xn[2] + xn[3] * xn[3];
; #pragma unroll
;           for (int o2 = 16; o2 > 0; o2 >>= 1) ss += __shfl_xor(ss, o2);
	v_lshlrev_b32_e32 v138, 16, v188
	v_and_b32_e32 v139, 0xffff0000, v188
	v_lshlrev_b32_e32 v140, 16, v189
	v_and_b32_e32 v141, 0xffff0000, v189
	v_pk_add_f32 v[82:83], v[82:83], v[138:139]
	v_pk_add_f32 v[84:85], v[84:85], v[140:141]
	v_cvt_pk_bf16_f32 v188, v82, v83
	v_cvt_pk_bf16_f32 v189, v84, v85
	v_add_u32_e32 v136, 0x60000, v132
	global_store_dwordx2 v136, v[188:189], s[6:7]
	v_and_b32_e32 v139, 0xffff0000, v188
	v_lshlrev_b32_e32 v138, 16, v188
	v_mul_f32_e32 v142, v139, v139
	v_lshlrev_b32_e32 v140, 16, v189
	v_fmac_f32_e32 v142, v138, v138
	v_and_b32_e32 v141, 0xffff0000, v189
	v_fmac_f32_e32 v142, v140, v140
	v_fmac_f32_e32 v142, v141, v141
	v_mov_b32_e32 v143, v142
	s_nop 1
	v_permlane16_swap_b32_e32 v143, v142
	v_add_f32_e32 v142, v142, v143
	s_nop 1
	v_mov_b32_dpp v143, v142 row_ror:8 row_mask:0xf bank_mask:0xf
	v_add_f32_e32 v142, v142, v143
	s_nop 1
	v_mov_b32_dpp v143, v142 row_ror:4 row_mask:0xf bank_mask:0xf
	v_add_f32_e32 v142, v142, v143
	s_nop 1
	v_mov_b32_dpp v143, v142 row_ror:2 row_mask:0xf bank_mask:0xf
	v_add_f32_e32 v142, v142, v143
	s_nop 1
	v_mov_b32_dpp v143, v142 row_ror:1 row_mask:0xf bank_mask:0xf
	v_add_f32_e32 v142, v142, v143
	v_add_u32_e32 v137, 0x1800, v133
	s_mov_b64 exec, s[10:11]
	global_store_dword v137, v142, s[8:9]
	s_mov_b64 exec, -1
	s_waitcnt vmcnt(44) lgkmcnt(2)
	v_lshlrev_b32_e32 v138, 16, v190
	v_and_b32_e32 v139, 0xffff0000, v190
	v_lshlrev_b32_e32 v140, 16, v191
	v_and_b32_e32 v141, 0xffff0000, v191
	v_pk_add_f32 v[86:87], v[86:87], v[138:139]
	v_pk_add_f32 v[88:89], v[88:89], v[140:141]
	v_cvt_pk_bf16_f32 v190, v86, v87
	v_cvt_pk_bf16_f32 v191, v88, v89
	v_add_u32_e32 v136, 0x68000, v132
	global_store_dwordx2 v136, v[190:191], s[6:7]
	v_and_b32_e32 v139, 0xffff0000, v190
	v_lshlrev_b32_e32 v138, 16, v190
	v_mul_f32_e32 v142, v139, v139
	v_lshlrev_b32_e32 v140, 16, v191
	v_fmac_f32_e32 v142, v138, v138
	v_and_b32_e32 v141, 0xffff0000, v191
	v_fmac_f32_e32 v142, v140, v140
	v_fmac_f32_e32 v142, v141, v141
	v_mov_b32_e32 v143, v142
	s_nop 1
	v_permlane16_swap_b32_e32 v143, v142
	v_add_f32_e32 v142, v142, v143
	s_nop 1
	v_mov_b32_dpp v143, v142 row_ror:8 row_mask:0xf bank_mask:0xf
	v_add_f32_e32 v142, v142, v143
	s_nop 1
	v_mov_b32_dpp v143, v142 row_ror:4 row_mask:0xf bank_mask:0xf
	v_add_f32_e32 v142, v142, v143
	s_nop 1
	v_mov_b32_dpp v143, v142 row_ror:2 row_mask:0xf bank_mask:0xf
	v_add_f32_e32 v142, v142, v143
	s_nop 1
	v_mov_b32_dpp v143, v142 row_ror:1 row_mask:0xf bank_mask:0xf
	v_add_f32_e32 v142, v142, v143
	v_add_u32_e32 v137, 0x1a00, v133
	s_mov_b64 exec, s[10:11]
	global_store_dword v137, v142, s[8:9]
	s_mov_b64 exec, -1
	s_waitcnt vmcnt(45) lgkmcnt(1)
	v_lshlrev_b32_e32 v138, 16, v192
	v_and_b32_e32 v139, 0xffff0000, v192
	v_lshlrev_b32_e32 v140, 16, v193
	v_and_b32_e32 v141, 0xffff0000, v193
	v_pk_add_f32 v[90:91], v[90:91], v[138:139]
	v_pk_add_f32 v[92:93], v[92:93], v[140:141]
	v_cvt_pk_bf16_f32 v192, v90, v91
	v_cvt_pk_bf16_f32 v193, v92, v93
	v_add_u32_e32 v136, 0x70000, v132
	global_store_dwordx2 v136, v[192:193], s[6:7]
	v_and_b32_e32 v139, 0xffff0000, v192
	v_lshlrev_b32_e32 v138, 16, v192
	v_mul_f32_e32 v142, v139, v139
	v_lshlrev_b32_e32 v140, 16, v193
	v_fmac_f32_e32 v142, v138, v138
	v_and_b32_e32 v141, 0xffff0000, v193
	v_fmac_f32_e32 v142, v140, v140
	v_fmac_f32_e32 v142, v141, v141
	v_mov_b32_e32 v143, v142
	s_nop 1
	v_permlane16_swap_b32_e32 v143, v142
	v_add_f32_e32 v142, v142, v143
	s_nop 1
	v_mov_b32_dpp v143, v142 row_ror:8 row_mask:0xf bank_mask:0xf
	v_add_f32_e32 v142, v142, v143
	s_nop 1
	v_mov_b32_dpp v143, v142 row_ror:4 row_mask:0xf bank_mask:0xf
	v_add_f32_e32 v142, v142, v143
	s_nop 1
	v_mov_b32_dpp v143, v142 row_ror:2 row_mask:0xf bank_mask:0xf
	v_add_f32_e32 v142, v142, v143
	s_nop 1
	v_mov_b32_dpp v143, v142 row_ror:1 row_mask:0xf bank_mask:0xf
	v_add_f32_e32 v142, v142, v143
	v_add_u32_e32 v137, 0x1c00, v133
	s_mov_b64 exec, s[10:11]
	global_store_dword v137, v142, s[8:9]
	s_mov_b64 exec, -1
	s_waitcnt vmcnt(46) lgkmcnt(0)
	v_lshlrev_b32_e32 v138, 16, v194
	v_and_b32_e32 v139, 0xffff0000, v194
	v_lshlrev_b32_e32 v140, 16, v195
	v_and_b32_e32 v141, 0xffff0000, v195
	v_pk_add_f32 v[94:95], v[94:95], v[138:139]
	v_pk_add_f32 v[96:97], v[96:97], v[140:141]
	v_cvt_pk_bf16_f32 v194, v94, v95
	v_cvt_pk_bf16_f32 v195, v96, v97
	v_add_u32_e32 v136, 0x78000, v132
	global_store_dwordx2 v136, v[194:195], s[6:7]
	v_and_b32_e32 v139, 0xffff0000, v194
	v_lshlrev_b32_e32 v138, 16, v194
	v_mul_f32_e32 v142, v139, v139
	v_lshlrev_b32_e32 v140, 16, v195
	v_fmac_f32_e32 v142, v138, v138
	v_and_b32_e32 v141, 0xffff0000, v195
	v_fmac_f32_e32 v142, v140, v140
	v_fmac_f32_e32 v142, v141, v141
	v_mov_b32_e32 v143, v142
	s_nop 1
	v_permlane16_swap_b32_e32 v143, v142
	v_add_f32_e32 v142, v142, v143
	s_nop 1
	v_mov_b32_dpp v143, v142 row_ror:8 row_mask:0xf bank_mask:0xf
	v_add_f32_e32 v142, v142, v143
	s_nop 1
	v_mov_b32_dpp v143, v142 row_ror:4 row_mask:0xf bank_mask:0xf
	v_add_f32_e32 v142, v142, v143
	s_nop 1
	v_mov_b32_dpp v143, v142 row_ror:2 row_mask:0xf bank_mask:0xf
	v_add_f32_e32 v142, v142, v143
	s_nop 1
	v_mov_b32_dpp v143, v142 row_ror:1 row_mask:0xf bank_mask:0xf
	v_add_f32_e32 v142, v142, v143
	v_add_u32_e32 v137, 0x1e00, v133
	s_mov_b64 exec, s[10:11]
	global_store_dword v137, v142, s[8:9]
	s_mov_b64 exec, -1
	s_barrier
	ds_write_b128 v134, v[34:37]
	ds_write_b128 v134, v[38:41] offset:8448
	ds_write_b128 v134, v[42:45] offset:64
	ds_write_b128 v134, v[46:49] offset:8512
	ds_write_b128 v134, v[50:53] offset:128
	ds_write_b128 v134, v[54:57] offset:8576
	ds_write_b128 v134, v[58:61] offset:192
	ds_write_b128 v134, v[62:65] offset:8640
	s_waitcnt lgkmcnt(0)
	s_barrier
; template <int MODE>
; DI void gemm_tile(const Params& p, const bf16_t* __restrict__ A, const bf16_t* __restrict__ Bt, int K, int brow, int bcol, int mp, int nt, bool vt, char* smem) {
;     ...
;       for (int pq = 0; pq < 4; ++pq) {
;         const int pass = pg * 4 + pq;
;         const int y = pass * 16 + (tid >> 5), x4 = (tid & 31) * 4;
;         const f32x4 v = *(const f32x4*)(st + y * 132 + x4);
;         if (MODE == MODE_PROJ) {
;           if (vt) {
;             const int vrow = (nt - 8) * 256 + bj * 128 + y, tk = m0 + ai * 128 + x4, b = tk >> 11, sq = tk & 2047;
;             const f32x4 rr = *(const f32x4*)(rsl + ai * 128 + x4);
;             u32x2 o = {pk2(v[0] * rr[0], v[1] * rr[1]), pk2(v[2] * rr[2], v[3] * rr[3])};
;             *(u32x2*)((bf16_t*)(p.ws + OFF_VT) + ((size_t)(b * VROWS + vrow)) * SEQ + sq) = o;
;           } else {
;             const int tok = m0 + bj * 128 + y, col = n0 + ai * 128 + x4;
;             const float rs = rsl[bj * 128 + y];
;             if (col < QKW) {
;               u32x2 o = {pk2(v[0] * rs, v[1] * rs), pk2(v[2] * rs, v[3] * rs)};
;               *(u32x2*)((bf16_t*)(p.ws + OFF_QK) + (size_t)tok * QKW + col) = o;
;             } else if (col < QKW + 16) {
;               f32x4 o = {v[0] * rs, v[1] * rs, v[2] * rs, v[3] * rs};
;               *(f32x4*)((float*)(p.ws + OFF_GATE) + (size_t)tok * 16 + (col - QKW)) = o;
;             }
;           }
;         } else if (MODE == MODE_UP) {
;           const int tok = m0 + bj * 128 + y, col = n0 + ai * 128 + x4;
;           const float rs = rsl[bj * 128 + y];
;           const float a0 = fmaxf(v[0] * rs, 0.f), a1 = fmaxf(v[1] * rs, 0.f), a2 = fmaxf(v[2] * rs, 0.f), a3 = fmaxf(v[3] * rs, 0.f);
;           u32x2 o = {pk2(a0 * a0, a1 * a1), pk2(a2 * a2, a3 * a3)};
;           *(u32x2*)((bf16_t*)(p.ws + OFF_U) + (size_t)tok * DFF + col) = o;
;         } else {
;           const int tok = m0 + bj * 128 + y, col = n0 + ai * 128 + x4;
;           const f32x4 xs = unpk4(xo[pq]) + v;
;           u32x2 o = {pk2(xs[0], xs[1]), pk2(xs[2], xs[3])};
;           *(u32x2*)((bf16_t*)(p.ws + OFF_XB) + (size_t)tok * DM + col) = o;
;           const f32x4 xn = unpk4(o);
;           float ss = xn[0] * xn[0] + xn[1] * xn[1] + xn[2] * xn[2] + xn[3] * xn[3];
; #pragma unroll
;           for (int o2 = 16; o2 > 0; o2 >>= 1) ss += __shfl_xor(ss, o2);
	ds_read_b128 v[34:37], v135
	ds_read_b128 v[38:41], v135 offset:8448
	ds_read_b128 v[42:45], v135 offset:16896
	ds_read_b128 v[46:49], v135 offset:25344
	ds_read_b128 v[50:53], v135 offset:33792
	ds_read_b128 v[54:57], v135 offset:42240
	ds_read_b128 v[58:61], v135 offset:50688
	ds_read_b128 v[62:65], v135 offset:59136
	s_waitcnt vmcnt(47) lgkmcnt(7)
	v_lshlrev_b32_e32 v138, 16, v196
	v_and_b32_e32 v139, 0xffff0000, v196
	v_lshlrev_b32_e32 v140, 16, v197
	v_and_b32_e32 v141, 0xffff0000, v197
	v_pk_add_f32 v[34:35], v[34:35], v[138:139]
	v_pk_add_f32 v[36:37], v[36:37], v[140:141]
	v_cvt_pk_bf16_f32 v196, v34, v35
	v_cvt_pk_bf16_f32 v197, v36, v37
	global_store_dwordx2 v132, v[196:197], s[6:7] offset:256
	v_and_b32_e32 v139, 0xffff0000, v196
	v_lshlrev_b32_e32 v138, 16, v196
	v_mul_f32_e32 v142, v139, v139
	v_lshlrev_b32_e32 v140, 16, v197
	v_fmac_f32_e32 v142, v138, v138
	v_and_b32_e32 v141, 0xffff0000, v197
	v_fmac_f32_e32 v142, v140, v140
	v_fmac_f32_e32 v142, v141, v141
	v_mov_b32_e32 v143, v142
	s_nop 1
	v_permlane16_swap_b32_e32 v143, v142
	v_add_f32_e32 v142, v142, v143
	s_nop 1
	v_mov_b32_dpp v143, v142 row_ror:8 row_mask:0xf bank_mask:0xf
	v_add_f32_e32 v142, v142, v143
	s_nop 1
	v_mov_b32_dpp v143, v142 row_ror:4 row_mask:0xf bank_mask:0xf
	v_add_f32_e32 v142, v142, v143
	s_nop 1
	v_mov_b32_dpp v143, v142 row_ror:2 row_mask:0xf bank_mask:0xf
	v_add_f32_e32 v142, v142, v143
	s_nop 1
	v_mov_b32_dpp v143, v142 row_ror:1 row_mask:0xf bank_mask:0xf
	v_add_f32_e32 v142, v142, v143
	s_mov_b64 exec, s[10:11]
	global_store_dword v133, v142, s[8:9] offset:4
	s_mov_b64 exec, -1
	s_waitcnt vmcnt(48) lgkmcnt(6)
	v_lshlrev_b32_e32 v138, 16, v198
	v_and_b32_e32 v139, 0xffff0000, v198
	v_lshlrev_b32_e32 v140, 16, v199
	v_and_b32_e32 v141, 0xffff0000, v199
	v_pk_add_f32 v[38:39], v[38:39], v[138:139]
	v_pk_add_f32 v[40:41], v[40:41], v[140:141]
	v_cvt_pk_bf16_f32 v198, v38, v39
	v_cvt_pk_bf16_f32 v199, v40, v41
	v_add_u32_e32 v136, 0x8000, v132
	global_store_dwordx2 v136, v[198:199], s[6:7] offset:256
	v_and_b32_e32 v139, 0xffff0000, v198
	v_lshlrev_b32_e32 v138, 16, v198
	v_mul_f32_e32 v142, v139, v139
	v_lshlrev_b32_e32 v140, 16, v199
	v_fmac_f32_e32 v142, v138, v138
	v_and_b32_e32 v141, 0xffff0000, v199
	v_fmac_f32_e32 v142, v140, v140
	v_fmac_f32_e32 v142, v141, v141
	v_mov_b32_e32 v143, v142
	s_nop 1
	v_permlane16_swap_b32_e32 v143, v142
	v_add_f32_e32 v142, v142, v143
	s_nop 1
	v_mov_b32_dpp v143, v142 row_ror:8 row_mask:0xf bank_mask:0xf
	v_add_f32_e32 v142, v142, v143
	s_nop 1
	v_mov_b32_dpp v143, v142 row_ror:4 row_mask:0xf bank_mask:0xf
	v_add_f32_e32 v142, v142, v143
	s_nop 1
	v_mov_b32_dpp v143, v142 row_ror:2 row_mask:0xf bank_mask:0xf
	v_add_f32_e32 v142, v142, v143
	s_nop 1
	v_mov_b32_dpp v143, v142 row_ror:1 row_mask:0xf bank_mask:0xf
	v_add_f32_e32 v142, v142, v143
	v_add_u32_e32 v137, 0x200, v133
	s_mov_b64 exec, s[10:11]
	global_store_dword v137, v142, s[8:9] offset:4
	s_mov_b64 exec, -1
	s_waitcnt vmcnt(49) lgkmcnt(5)
	v_lshlrev_b32_e32 v138, 16, v214
	v_and_b32_e32 v139, 0xffff0000, v214
	v_lshlrev_b32_e32 v140, 16, v215
	v_and_b32_e32 v141, 0xffff0000, v215
	v_pk_add_f32 v[42:43], v[42:43], v[138:139]
	v_pk_add_f32 v[44:45], v[44:45], v[140:141]
	v_cvt_pk_bf16_f32 v214, v42, v43
	v_cvt_pk_bf16_f32 v215, v44, v45
	v_add_u32_e32 v136, 0x10000, v132
	global_store_dwordx2 v136, v[214:215], s[6:7] offset:256
	v_and_b32_e32 v139, 0xffff0000, v214
	v_lshlrev_b32_e32 v138, 16, v214
	v_mul_f32_e32 v142, v139, v139
	v_lshlrev_b32_e32 v140, 16, v215
	v_fmac_f32_e32 v142, v138, v138
	v_and_b32_e32 v141, 0xffff0000, v215
	v_fmac_f32_e32 v142, v140, v140
	v_fmac_f32_e32 v142, v141, v141
	v_mov_b32_e32 v143, v142
	s_nop 1
	v_permlane16_swap_b32_e32 v143, v142
	v_add_f32_e32 v142, v142, v143
	s_nop 1
	v_mov_b32_dpp v143, v142 row_ror:8 row_mask:0xf bank_mask:0xf
	v_add_f32_e32 v142, v142, v143
	s_nop 1
	v_mov_b32_dpp v143, v142 row_ror:4 row_mask:0xf bank_mask:0xf
	v_add_f32_e32 v142, v142, v143
	s_nop 1
	v_mov_b32_dpp v143, v142 row_ror:2 row_mask:0xf bank_mask:0xf
	v_add_f32_e32 v142, v142, v143
	s_nop 1
	v_mov_b32_dpp v143, v142 row_ror:1 row_mask:0xf bank_mask:0xf
	v_add_f32_e32 v142, v142, v143
	v_add_u32_e32 v137, 0x400, v133
	s_mov_b64 exec, s[10:11]
	global_store_dword v137, v142, s[8:9] offset:4
	s_mov_b64 exec, -1
	s_waitcnt vmcnt(50) lgkmcnt(4)
	v_lshlrev_b32_e32 v138, 16, v216
	v_and_b32_e32 v139, 0xffff0000, v216
	v_lshlrev_b32_e32 v140, 16, v217
	v_and_b32_e32 v141, 0xffff0000, v217
	v_pk_add_f32 v[46:47], v[46:47], v[138:139]
	v_pk_add_f32 v[48:49], v[48:49], v[140:141]
	v_cvt_pk_bf16_f32 v216, v46, v47
	v_cvt_pk_bf16_f32 v217, v48, v49
	v_add_u32_e32 v136, 0x18000, v132
	global_store_dwordx2 v136, v[216:217], s[6:7] offset:256
	v_and_b32_e32 v139, 0xffff0000, v216
	v_lshlrev_b32_e32 v138, 16, v216
	v_mul_f32_e32 v142, v139, v139
	v_lshlrev_b32_e32 v140, 16, v217
	v_fmac_f32_e32 v142, v138, v138
	v_and_b32_e32 v141, 0xffff0000, v217
	v_fmac_f32_e32 v142, v140, v140
	v_fmac_f32_e32 v142, v141, v141
	v_mov_b32_e32 v143, v142
	s_nop 1
	v_permlane16_swap_b32_e32 v143, v142
	v_add_f32_e32 v142, v142, v143
	s_nop 1
	v_mov_b32_dpp v143, v142 row_ror:8 row_mask:0xf bank_mask:0xf
	v_add_f32_e32 v142, v142, v143
	s_nop 1
	v_mov_b32_dpp v143, v142 row_ror:4 row_mask:0xf bank_mask:0xf
	v_add_f32_e32 v142, v142, v143
	s_nop 1
	v_mov_b32_dpp v143, v142 row_ror:2 row_mask:0xf bank_mask:0xf
	v_add_f32_e32 v142, v142, v143
	s_nop 1
	v_mov_b32_dpp v143, v142 row_ror:1 row_mask:0xf bank_mask:0xf
	v_add_f32_e32 v142, v142, v143
	v_add_u32_e32 v137, 0x600, v133
	s_mov_b64 exec, s[10:11]
	global_store_dword v137, v142, s[8:9] offset:4
	s_mov_b64 exec, -1
	s_waitcnt vmcnt(51) lgkmcnt(3)
; template <int MODE>
; DI void gemm_tile(const Params& p, const bf16_t* __restrict__ A, const bf16_t* __restrict__ Bt, int K, int brow, int bcol, int mp, int nt, bool vt, char* smem) {
;     ...
;       for (int pq = 0; pq < 4; ++pq) {
;         const int pass = pg * 4 + pq;
;         const int y = pass * 16 + (tid >> 5), x4 = (tid & 31) * 4;
;         const f32x4 v = *(const f32x4*)(st + y * 132 + x4);
;         if (MODE == MODE_PROJ) {
;           if (vt) {
;             const int vrow = (nt - 8) * 256 + bj * 128 + y, tk = m0 + ai * 128 + x4, b = tk >> 11, sq = tk & 2047;
;             const f32x4 rr = *(const f32x4*)(rsl + ai * 128 + x4);
;             u32x2 o = {pk2(v[0] * rr[0], v[1] * rr[1]), pk2(v[2] * rr[2], v[3] * rr[3])};
;             *(u32x2*)((bf16_t*)(p.ws + OFF_VT) + ((size_t)(b * VROWS + vrow)) * SEQ + sq) = o;
;           } else {
;             const int tok = m0 + bj * 128 + y, col = n0 + ai * 128 + x4;
;             const float rs = rsl[bj * 128 + y];
;             if (col < QKW) {
;               u32x2 o = {pk2(v[0] * rs, v[1] * rs), pk2(v[2] * rs, v[3] * rs)};
;               *(u32x2*)((bf16_t*)(p.ws + OFF_QK) + (size_t)tok * QKW + col) = o;
;             } else if (col < QKW + 16) {
;               f32x4 o = {v[0] * rs, v[1] * rs, v[2] * rs, v[3] * rs};
;               *(f32x4*)((float*)(p.ws + OFF_GATE) + (size_t)tok * 16 + (col - QKW)) = o;
;             }
;           }
;         } else if (MODE == MODE_UP) {
;           const int tok = m0 + bj * 128 + y, col = n0 + ai * 128 + x4;
;           const float rs = rsl[bj * 128 + y];
;           const float a0 = fmaxf(v[0] * rs, 0.f), a1 = fmaxf(v[1] * rs, 0.f), a2 = fmaxf(v[2] * rs, 0.f), a3 = fmaxf(v[3] * rs, 0.f);
;           u32x2 o = {pk2(a0 * a0, a1 * a1), pk2(a2 * a2, a3 * a3)};
;           *(u32x2*)((bf16_t*)(p.ws + OFF_U) + (size_t)tok * DFF + col) = o;
;         } else {
;           const int tok = m0 + bj * 128 + y, col = n0 + ai * 128 + x4;
;           const f32x4 xs = unpk4(xo[pq]) + v;
;           u32x2 o = {pk2(xs[0], xs[1]), pk2(xs[2], xs[3])};
;           *(u32x2*)((bf16_t*)(p.ws + OFF_XB) + (size_t)tok * DM + col) = o;
;           const f32x4 xn = unpk4(o);
;           float ss = xn[0] * xn[0] + xn[1] * xn[1] + xn[2] * xn[2] + xn[3] * xn[3];
; #pragma unroll
;           for (int o2 = 16; o2 > 0; o2 >>= 1) ss += __shfl_xor(ss, o2);
	v_lshlrev_b32_e32 v138, 16, v218
	v_and_b32_e32 v139, 0xffff0000, v218
	v_lshlrev_b32_e32 v140, 16, v219
	v_and_b32_e32 v141, 0xffff0000, v219
	v_pk_add_f32 v[50:51], v[50:51], v[138:139]
	v_pk_add_f32 v[52:53], v[52:53], v[140:141]
	v_cvt_pk_bf16_f32 v218, v50, v51
	v_cvt_pk_bf16_f32 v219, v52, v53
	v_add_u32_e32 v136, 0x20000, v132
	global_store_dwordx2 v136, v[218:219], s[6:7] offset:256
	v_and_b32_e32 v139, 0xffff0000, v218
	v_lshlrev_b32_e32 v138, 16, v218
	v_mul_f32_e32 v142, v139, v139
	v_lshlrev_b32_e32 v140, 16, v219
	v_fmac_f32_e32 v142, v138, v138
	v_and_b32_e32 v141, 0xffff0000, v219
	v_fmac_f32_e32 v142, v140, v140
	v_fmac_f32_e32 v142, v141, v141
	v_mov_b32_e32 v143, v142
	s_nop 1
	v_permlane16_swap_b32_e32 v143, v142
	v_add_f32_e32 v142, v142, v143
	s_nop 1
	v_mov_b32_dpp v143, v142 row_ror:8 row_mask:0xf bank_mask:0xf
	v_add_f32_e32 v142, v142, v143
	s_nop 1
	v_mov_b32_dpp v143, v142 row_ror:4 row_mask:0xf bank_mask:0xf
	v_add_f32_e32 v142, v142, v143
	s_nop 1
	v_mov_b32_dpp v143, v142 row_ror:2 row_mask:0xf bank_mask:0xf
	v_add_f32_e32 v142, v142, v143
	s_nop 1
	v_mov_b32_dpp v143, v142 row_ror:1 row_mask:0xf bank_mask:0xf
	v_add_f32_e32 v142, v142, v143
	v_add_u32_e32 v137, 0x800, v133
	s_mov_b64 exec, s[10:11]
	global_store_dword v137, v142, s[8:9] offset:4
	s_mov_b64 exec, -1
	s_waitcnt vmcnt(52) lgkmcnt(2)
	v_lshlrev_b32_e32 v138, 16, v220
	v_and_b32_e32 v139, 0xffff0000, v220
	v_lshlrev_b32_e32 v140, 16, v221
	v_and_b32_e32 v141, 0xffff0000, v221
	v_pk_add_f32 v[54:55], v[54:55], v[138:139]
	v_pk_add_f32 v[56:57], v[56:57], v[140:141]
	v_cvt_pk_bf16_f32 v220, v54, v55
	v_cvt_pk_bf16_f32 v221, v56, v57
	v_add_u32_e32 v136, 0x28000, v132
	global_store_dwordx2 v136, v[220:221], s[6:7] offset:256
	v_and_b32_e32 v139, 0xffff0000, v220
	v_lshlrev_b32_e32 v138, 16, v220
	v_mul_f32_e32 v142, v139, v139
	v_lshlrev_b32_e32 v140, 16, v221
	v_fmac_f32_e32 v142, v138, v138
	v_and_b32_e32 v141, 0xffff0000, v221
	v_fmac_f32_e32 v142, v140, v140
	v_fmac_f32_e32 v142, v141, v141
	v_mov_b32_e32 v143, v142
	s_nop 1
	v_permlane16_swap_b32_e32 v143, v142
	v_add_f32_e32 v142, v142, v143
	s_nop 1
	v_mov_b32_dpp v143, v142 row_ror:8 row_mask:0xf bank_mask:0xf
	v_add_f32_e32 v142, v142, v143
	s_nop 1
	v_mov_b32_dpp v143, v142 row_ror:4 row_mask:0xf bank_mask:0xf
	v_add_f32_e32 v142, v142, v143
	s_nop 1
	v_mov_b32_dpp v143, v142 row_ror:2 row_mask:0xf bank_mask:0xf
	v_add_f32_e32 v142, v142, v143
	s_nop 1
	v_mov_b32_dpp v143, v142 row_ror:1 row_mask:0xf bank_mask:0xf
	v_add_f32_e32 v142, v142, v143
	v_add_u32_e32 v137, 0xa00, v133
	s_mov_b64 exec, s[10:11]
	global_store_dword v137, v142, s[8:9] offset:4
	s_mov_b64 exec, -1
	s_waitcnt vmcnt(53) lgkmcnt(1)
	v_lshlrev_b32_e32 v138, 16, v222
	v_and_b32_e32 v139, 0xffff0000, v222
	v_lshlrev_b32_e32 v140, 16, v223
	v_and_b32_e32 v141, 0xffff0000, v223
	v_pk_add_f32 v[58:59], v[58:59], v[138:139]
	v_pk_add_f32 v[60:61], v[60:61], v[140:141]
	v_cvt_pk_bf16_f32 v222, v58, v59
	v_cvt_pk_bf16_f32 v223, v60, v61
	v_add_u32_e32 v136, 0x30000, v132
	global_store_dwordx2 v136, v[222:223], s[6:7] offset:256
	v_and_b32_e32 v139, 0xffff0000, v222
	v_lshlrev_b32_e32 v138, 16, v222
	v_mul_f32_e32 v142, v139, v139
	v_lshlrev_b32_e32 v140, 16, v223
	v_fmac_f32_e32 v142, v138, v138
	v_and_b32_e32 v141, 0xffff0000, v223
	v_fmac_f32_e32 v142, v140, v140
	v_fmac_f32_e32 v142, v141, v141
	v_mov_b32_e32 v143, v142
	s_nop 1
	v_permlane16_swap_b32_e32 v143, v142
	v_add_f32_e32 v142, v142, v143
	s_nop 1
	v_mov_b32_dpp v143, v142 row_ror:8 row_mask:0xf bank_mask:0xf
	v_add_f32_e32 v142, v142, v143
	s_nop 1
	v_mov_b32_dpp v143, v142 row_ror:4 row_mask:0xf bank_mask:0xf
	v_add_f32_e32 v142, v142, v143
	s_nop 1
	v_mov_b32_dpp v143, v142 row_ror:2 row_mask:0xf bank_mask:0xf
	v_add_f32_e32 v142, v142, v143
	s_nop 1
	v_mov_b32_dpp v143, v142 row_ror:1 row_mask:0xf bank_mask:0xf
	v_add_f32_e32 v142, v142, v143
	v_add_u32_e32 v137, 0xc00, v133
	s_mov_b64 exec, s[10:11]
	global_store_dword v137, v142, s[8:9] offset:4
	s_mov_b64 exec, -1
	s_waitcnt vmcnt(54) lgkmcnt(0)
	v_lshlrev_b32_e32 v138, 16, v224
	v_and_b32_e32 v139, 0xffff0000, v224
	v_lshlrev_b32_e32 v140, 16, v225
	v_and_b32_e32 v141, 0xffff0000, v225
	v_pk_add_f32 v[62:63], v[62:63], v[138:139]
	v_pk_add_f32 v[64:65], v[64:65], v[140:141]
	v_cvt_pk_bf16_f32 v224, v62, v63
	v_cvt_pk_bf16_f32 v225, v64, v65
	v_add_u32_e32 v136, 0x38000, v132
	global_store_dwordx2 v136, v[224:225], s[6:7] offset:256
	v_and_b32_e32 v139, 0xffff0000, v224
	v_lshlrev_b32_e32 v138, 16, v224
	v_mul_f32_e32 v142, v139, v139
	v_lshlrev_b32_e32 v140, 16, v225
	v_fmac_f32_e32 v142, v138, v138
	v_and_b32_e32 v141, 0xffff0000, v225
	v_fmac_f32_e32 v142, v140, v140
	v_fmac_f32_e32 v142, v141, v141
	v_mov_b32_e32 v143, v142
	s_nop 1
	v_permlane16_swap_b32_e32 v143, v142
	v_add_f32_e32 v142, v142, v143
	s_nop 1
	v_mov_b32_dpp v143, v142 row_ror:8 row_mask:0xf bank_mask:0xf
	v_add_f32_e32 v142, v142, v143
	s_nop 1
	v_mov_b32_dpp v143, v142 row_ror:4 row_mask:0xf bank_mask:0xf
	v_add_f32_e32 v142, v142, v143
	s_nop 1
	v_mov_b32_dpp v143, v142 row_ror:2 row_mask:0xf bank_mask:0xf
	v_add_f32_e32 v142, v142, v143
	s_nop 1
	v_mov_b32_dpp v143, v142 row_ror:1 row_mask:0xf bank_mask:0xf
	v_add_f32_e32 v142, v142, v143
	v_add_u32_e32 v137, 0xe00, v133
	s_mov_b64 exec, s[10:11]
	global_store_dword v137, v142, s[8:9] offset:4
	s_mov_b64 exec, -1
	s_barrier
	ds_write_b128 v134, v[2:5]
	ds_write_b128 v134, v[6:9] offset:8448
	ds_write_b128 v134, v[10:13] offset:64
	ds_write_b128 v134, v[14:17] offset:8512
	ds_write_b128 v134, v[18:21] offset:128
	ds_write_b128 v134, v[22:25] offset:8576
	ds_write_b128 v134, v[26:29] offset:192
	ds_write_b128 v134, v[30:33] offset:8640
	s_waitcnt lgkmcnt(0)
	s_barrier
; template <int MODE>
; DI void gemm_tile(const Params& p, const bf16_t* __restrict__ A, const bf16_t* __restrict__ Bt, int K, int brow, int bcol, int mp, int nt, bool vt, char* smem) {
;     ...
;       for (int pq = 0; pq < 4; ++pq) {
;         const int pass = pg * 4 + pq;
;         const int y = pass * 16 + (tid >> 5), x4 = (tid & 31) * 4;
;         const f32x4 v = *(const f32x4*)(st + y * 132 + x4);
;         if (MODE == MODE_PROJ) {
;           if (vt) {
;             const int vrow = (nt - 8) * 256 + bj * 128 + y, tk = m0 + ai * 128 + x4, b = tk >> 11, sq = tk & 2047;
;             const f32x4 rr = *(const f32x4*)(rsl + ai * 128 + x4);
;             u32x2 o = {pk2(v[0] * rr[0], v[1] * rr[1]), pk2(v[2] * rr[2], v[3] * rr[3])};
;             *(u32x2*)((bf16_t*)(p.ws + OFF_VT) + ((size_t)(b * VROWS + vrow)) * SEQ + sq) = o;
;           } else {
;             const int tok = m0 + bj * 128 + y, col = n0 + ai * 128 + x4;
;             const float rs = rsl[bj * 128 + y];
;             if (col < QKW) {
;               u32x2 o = {pk2(v[0] * rs, v[1] * rs), pk2(v[2] * rs, v[3] * rs)};
;               *(u32x2*)((bf16_t*)(p.ws + OFF_QK) + (size_t)tok * QKW + col) = o;
;             } else if (col < QKW + 16) {
;               f32x4 o = {v[0] * rs, v[1] * rs, v[2] * rs, v[3] * rs};
;               *(f32x4*)((float*)(p.ws + OFF_GATE) + (size_t)tok * 16 + (col - QKW)) = o;
;             }
;           }
;         } else if (MODE == MODE_UP) {
;           const int tok = m0 + bj * 128 + y, col = n0 + ai * 128 + x4;
;           const float rs = rsl[bj * 128 + y];
;           const float a0 = fmaxf(v[0] * rs, 0.f), a1 = fmaxf(v[1] * rs, 0.f), a2 = fmaxf(v[2] * rs, 0.f), a3 = fmaxf(v[3] * rs, 0.f);
;           u32x2 o = {pk2(a0 * a0, a1 * a1), pk2(a2 * a2, a3 * a3)};
;           *(u32x2*)((bf16_t*)(p.ws + OFF_U) + (size_t)tok * DFF + col) = o;
;         } else {
;           const int tok = m0 + bj * 128 + y, col = n0 + ai * 128 + x4;
;           const f32x4 xs = unpk4(xo[pq]) + v;
;           u32x2 o = {pk2(xs[0], xs[1]), pk2(xs[2], xs[3])};
;           *(u32x2*)((bf16_t*)(p.ws + OFF_XB) + (size_t)tok * DM + col) = o;
;           const f32x4 xn = unpk4(o);
;           float ss = xn[0] * xn[0] + xn[1] * xn[1] + xn[2] * xn[2] + xn[3] * xn[3];
; #pragma unroll
;           for (int o2 = 16; o2 > 0; o2 >>= 1) ss += __shfl_xor(ss, o2);
	ds_read_b128 v[2:5], v135
	ds_read_b128 v[6:9], v135 offset:8448
	ds_read_b128 v[10:13], v135 offset:16896
	ds_read_b128 v[14:17], v135 offset:25344
	ds_read_b128 v[18:21], v135 offset:33792
	ds_read_b128 v[22:25], v135 offset:42240
	ds_read_b128 v[26:29], v135 offset:50688
	ds_read_b128 v[30:33], v135 offset:59136
	s_waitcnt vmcnt(55) lgkmcnt(7)
	v_lshlrev_b32_e32 v138, 16, v226
	v_and_b32_e32 v139, 0xffff0000, v226
	v_lshlrev_b32_e32 v140, 16, v227
	v_and_b32_e32 v141, 0xffff0000, v227
	v_pk_add_f32 v[2:3], v[2:3], v[138:139]
	v_pk_add_f32 v[4:5], v[4:5], v[140:141]
	v_cvt_pk_bf16_f32 v226, v2, v3
	v_cvt_pk_bf16_f32 v227, v4, v5
	v_add_u32_e32 v136, 0x40000, v132
	global_store_dwordx2 v136, v[226:227], s[6:7] offset:256
	v_and_b32_e32 v139, 0xffff0000, v226
	v_lshlrev_b32_e32 v138, 16, v226
	v_mul_f32_e32 v142, v139, v139
	v_lshlrev_b32_e32 v140, 16, v227
	v_fmac_f32_e32 v142, v138, v138
	v_and_b32_e32 v141, 0xffff0000, v227
	v_fmac_f32_e32 v142, v140, v140
	v_fmac_f32_e32 v142, v141, v141
	v_mov_b32_e32 v143, v142
	s_nop 1
	v_permlane16_swap_b32_e32 v143, v142
	v_add_f32_e32 v142, v142, v143
	s_nop 1
	v_mov_b32_dpp v143, v142 row_ror:8 row_mask:0xf bank_mask:0xf
	v_add_f32_e32 v142, v142, v143
	s_nop 1
	v_mov_b32_dpp v143, v142 row_ror:4 row_mask:0xf bank_mask:0xf
	v_add_f32_e32 v142, v142, v143
	s_nop 1
	v_mov_b32_dpp v143, v142 row_ror:2 row_mask:0xf bank_mask:0xf
	v_add_f32_e32 v142, v142, v143
	s_nop 1
	v_mov_b32_dpp v143, v142 row_ror:1 row_mask:0xf bank_mask:0xf
	v_add_f32_e32 v142, v142, v143
	v_add_u32_e32 v137, 0x1000, v133
	s_mov_b64 exec, s[10:11]
	global_store_dword v137, v142, s[8:9] offset:4
	s_mov_b64 exec, -1
	s_waitcnt vmcnt(56) lgkmcnt(6)
	v_lshlrev_b32_e32 v138, 16, v228
	v_and_b32_e32 v139, 0xffff0000, v228
	v_lshlrev_b32_e32 v140, 16, v229
	v_and_b32_e32 v141, 0xffff0000, v229
	v_pk_add_f32 v[6:7], v[6:7], v[138:139]
	v_pk_add_f32 v[8:9], v[8:9], v[140:141]
	v_cvt_pk_bf16_f32 v228, v6, v7
	v_cvt_pk_bf16_f32 v229, v8, v9
	v_add_u32_e32 v136, 0x48000, v132
	global_store_dwordx2 v136, v[228:229], s[6:7] offset:256
	v_and_b32_e32 v139, 0xffff0000, v228
	v_lshlrev_b32_e32 v138, 16, v228
	v_mul_f32_e32 v142, v139, v139
	v_lshlrev_b32_e32 v140, 16, v229
	v_fmac_f32_e32 v142, v138, v138
	v_and_b32_e32 v141, 0xffff0000, v229
	v_fmac_f32_e32 v142, v140, v140
	v_fmac_f32_e32 v142, v141, v141
	v_mov_b32_e32 v143, v142
	s_nop 1
	v_permlane16_swap_b32_e32 v143, v142
	v_add_f32_e32 v142, v142, v143
	s_nop 1
	v_mov_b32_dpp v143, v142 row_ror:8 row_mask:0xf bank_mask:0xf
	v_add_f32_e32 v142, v142, v143
	s_nop 1
	v_mov_b32_dpp v143, v142 row_ror:4 row_mask:0xf bank_mask:0xf
	v_add_f32_e32 v142, v142, v143
	s_nop 1
	v_mov_b32_dpp v143, v142 row_ror:2 row_mask:0xf bank_mask:0xf
	v_add_f32_e32 v142, v142, v143
	s_nop 1
	v_mov_b32_dpp v143, v142 row_ror:1 row_mask:0xf bank_mask:0xf
	v_add_f32_e32 v142, v142, v143
	v_add_u32_e32 v137, 0x1200, v133
	s_mov_b64 exec, s[10:11]
	global_store_dword v137, v142, s[8:9] offset:4
	s_mov_b64 exec, -1
	s_waitcnt vmcnt(57) lgkmcnt(5)
	v_lshlrev_b32_e32 v138, 16, v230
	v_and_b32_e32 v139, 0xffff0000, v230
	v_lshlrev_b32_e32 v140, 16, v231
	v_and_b32_e32 v141, 0xffff0000, v231
	v_pk_add_f32 v[10:11], v[10:11], v[138:139]
	v_pk_add_f32 v[12:13], v[12:13], v[140:141]
	v_cvt_pk_bf16_f32 v230, v10, v11
	v_cvt_pk_bf16_f32 v231, v12, v13
	v_add_u32_e32 v136, 0x50000, v132
	global_store_dwordx2 v136, v[230:231], s[6:7] offset:256
	v_and_b32_e32 v139, 0xffff0000, v230
	v_lshlrev_b32_e32 v138, 16, v230
	v_mul_f32_e32 v142, v139, v139
	v_lshlrev_b32_e32 v140, 16, v231
	v_fmac_f32_e32 v142, v138, v138
	v_and_b32_e32 v141, 0xffff0000, v231
	v_fmac_f32_e32 v142, v140, v140
	v_fmac_f32_e32 v142, v141, v141
	v_mov_b32_e32 v143, v142
	s_nop 1
	v_permlane16_swap_b32_e32 v143, v142
	v_add_f32_e32 v142, v142, v143
	s_nop 1
	v_mov_b32_dpp v143, v142 row_ror:8 row_mask:0xf bank_mask:0xf
	v_add_f32_e32 v142, v142, v143
	s_nop 1
	v_mov_b32_dpp v143, v142 row_ror:4 row_mask:0xf bank_mask:0xf
	v_add_f32_e32 v142, v142, v143
	s_nop 1
	v_mov_b32_dpp v143, v142 row_ror:2 row_mask:0xf bank_mask:0xf
	v_add_f32_e32 v142, v142, v143
	s_nop 1
	v_mov_b32_dpp v143, v142 row_ror:1 row_mask:0xf bank_mask:0xf
	v_add_f32_e32 v142, v142, v143
	v_add_u32_e32 v137, 0x1400, v133
	s_mov_b64 exec, s[10:11]
	global_store_dword v137, v142, s[8:9] offset:4
	s_mov_b64 exec, -1
	s_waitcnt vmcnt(58) lgkmcnt(4)
	v_lshlrev_b32_e32 v138, 16, v232
	v_and_b32_e32 v139, 0xffff0000, v232
	v_lshlrev_b32_e32 v140, 16, v233
	v_and_b32_e32 v141, 0xffff0000, v233
	v_pk_add_f32 v[14:15], v[14:15], v[138:139]
	v_pk_add_f32 v[16:17], v[16:17], v[140:141]
	v_cvt_pk_bf16_f32 v232, v14, v15
	v_cvt_pk_bf16_f32 v233, v16, v17
	v_add_u32_e32 v136, 0x58000, v132
	global_store_dwordx2 v136, v[232:233], s[6:7] offset:256
	v_and_b32_e32 v139, 0xffff0000, v232
	v_lshlrev_b32_e32 v138, 16, v232
	v_mul_f32_e32 v142, v139, v139
	v_lshlrev_b32_e32 v140, 16, v233
	v_fmac_f32_e32 v142, v138, v138
	v_and_b32_e32 v141, 0xffff0000, v233
	v_fmac_f32_e32 v142, v140, v140
	v_fmac_f32_e32 v142, v141, v141
	v_mov_b32_e32 v143, v142
	s_nop 1
	v_permlane16_swap_b32_e32 v143, v142
	v_add_f32_e32 v142, v142, v143
	s_nop 1
	v_mov_b32_dpp v143, v142 row_ror:8 row_mask:0xf bank_mask:0xf
	v_add_f32_e32 v142, v142, v143
	s_nop 1
	v_mov_b32_dpp v143, v142 row_ror:4 row_mask:0xf bank_mask:0xf
	v_add_f32_e32 v142, v142, v143
	s_nop 1
	v_mov_b32_dpp v143, v142 row_ror:2 row_mask:0xf bank_mask:0xf
	v_add_f32_e32 v142, v142, v143
	s_nop 1
	v_mov_b32_dpp v143, v142 row_ror:1 row_mask:0xf bank_mask:0xf
	v_add_f32_e32 v142, v142, v143
	v_add_u32_e32 v137, 0x1600, v133
	s_mov_b64 exec, s[10:11]
	global_store_dword v137, v142, s[8:9] offset:4
	s_mov_b64 exec, -1
	s_waitcnt vmcnt(59) lgkmcnt(3)
; DI unsigned pk2(float a, float b) { f32x2 v = {a, b}; bf2_t r = __builtin_convertvector(v, bf2_t); return __builtin_bit_cast(unsigned, r); }
; DI f32x4 unpk4(u32x2 u) { f32x4 r = {__uint_as_float(u[0] << 16), __uint_as_float(u[0] & 0xffff0000u), __uint_as_float(u[1] << 16), __uint_as_float(u[1] & 0xffff0000u)}; return r; }
; template <int MODE>
; DI void gemm_tile(const Params& p, const bf16_t* __restrict__ A, const bf16_t* __restrict__ Bt, int K, int brow, int bcol, int mp, int nt, bool vt, char* smem) {
;     ...
;           const int tok = m0 + bj * 128 + y, col = n0 + ai * 128 + x4;
;           const f32x4 xs = unpk4(xo[pq]) + v;
;           u32x2 o = {pk2(xs[0], xs[1]), pk2(xs[2], xs[3])};
;           *(u32x2*)((bf16_t*)(p.ws + OFF_XB) + (size_t)tok * DM + col) = o;
;           const f32x4 xn = unpk4(o);
;           float ss = xn[0] * xn[0] + xn[1] * xn[1] + xn[2] * xn[2] + xn[3] * xn[3];
; #pragma unroll
;           for (int o2 = 16; o2 > 0; o2 >>= 1) ss += __shfl_xor(ss, o2);
;           if ((tid & 31) == 0) ((float*)(p.ws + (MODE == MODE_OUT ? OFF_SSB : OFF_SSA)))[(size_t)tok * 8 + nt * 2 + ai] = ss;
	v_lshlrev_b32_e32 v138, 16, v234
	v_and_b32_e32 v139, 0xffff0000, v234
	v_lshlrev_b32_e32 v140, 16, v235
	v_and_b32_e32 v141, 0xffff0000, v235
	v_pk_add_f32 v[18:19], v[18:19], v[138:139]
	v_pk_add_f32 v[20:21], v[20:21], v[140:141]
	v_cvt_pk_bf16_f32 v234, v18, v19
	v_cvt_pk_bf16_f32 v235, v20, v21
	v_add_u32_e32 v136, 0x60000, v132
	global_store_dwordx2 v136, v[234:235], s[6:7] offset:256
	v_and_b32_e32 v139, 0xffff0000, v234
	v_lshlrev_b32_e32 v138, 16, v234
	v_mul_f32_e32 v142, v139, v139
	v_lshlrev_b32_e32 v140, 16, v235
	v_fmac_f32_e32 v142, v138, v138
	v_and_b32_e32 v141, 0xffff0000, v235
	v_fmac_f32_e32 v142, v140, v140
	v_fmac_f32_e32 v142, v141, v141
	v_mov_b32_e32 v143, v142
	s_nop 1
	v_permlane16_swap_b32_e32 v143, v142
	v_add_f32_e32 v142, v142, v143
	s_nop 1
	v_mov_b32_dpp v143, v142 row_ror:8 row_mask:0xf bank_mask:0xf
	v_add_f32_e32 v142, v142, v143
	s_nop 1
	v_mov_b32_dpp v143, v142 row_ror:4 row_mask:0xf bank_mask:0xf
	v_add_f32_e32 v142, v142, v143
	s_nop 1
	v_mov_b32_dpp v143, v142 row_ror:2 row_mask:0xf bank_mask:0xf
	v_add_f32_e32 v142, v142, v143
	s_nop 1
	v_mov_b32_dpp v143, v142 row_ror:1 row_mask:0xf bank_mask:0xf
	v_add_f32_e32 v142, v142, v143
	v_add_u32_e32 v137, 0x1800, v133
	s_mov_b64 exec, s[10:11]
	global_store_dword v137, v142, s[8:9] offset:4
	s_mov_b64 exec, -1
	s_waitcnt vmcnt(60) lgkmcnt(2)
	v_lshlrev_b32_e32 v138, 16, v236
	v_and_b32_e32 v139, 0xffff0000, v236
	v_lshlrev_b32_e32 v140, 16, v237
	v_and_b32_e32 v141, 0xffff0000, v237
	v_pk_add_f32 v[22:23], v[22:23], v[138:139]
	v_pk_add_f32 v[24:25], v[24:25], v[140:141]
	v_cvt_pk_bf16_f32 v236, v22, v23
	v_cvt_pk_bf16_f32 v237, v24, v25
	v_add_u32_e32 v136, 0x68000, v132
	global_store_dwordx2 v136, v[236:237], s[6:7] offset:256
	v_and_b32_e32 v139, 0xffff0000, v236
	v_lshlrev_b32_e32 v138, 16, v236
	v_mul_f32_e32 v142, v139, v139
	v_lshlrev_b32_e32 v140, 16, v237
	v_fmac_f32_e32 v142, v138, v138
	v_and_b32_e32 v141, 0xffff0000, v237
	v_fmac_f32_e32 v142, v140, v140
	v_fmac_f32_e32 v142, v141, v141
	v_mov_b32_e32 v143, v142
	s_nop 1
	v_permlane16_swap_b32_e32 v143, v142
	v_add_f32_e32 v142, v142, v143
	s_nop 1
	v_mov_b32_dpp v143, v142 row_ror:8 row_mask:0xf bank_mask:0xf
	v_add_f32_e32 v142, v142, v143
	s_nop 1
	v_mov_b32_dpp v143, v142 row_ror:4 row_mask:0xf bank_mask:0xf
	v_add_f32_e32 v142, v142, v143
	s_nop 1
	v_mov_b32_dpp v143, v142 row_ror:2 row_mask:0xf bank_mask:0xf
	v_add_f32_e32 v142, v142, v143
	s_nop 1
	v_mov_b32_dpp v143, v142 row_ror:1 row_mask:0xf bank_mask:0xf
	v_add_f32_e32 v142, v142, v143
	v_add_u32_e32 v137, 0x1a00, v133
	s_mov_b64 exec, s[10:11]
	global_store_dword v137, v142, s[8:9] offset:4
	s_mov_b64 exec, -1
	s_waitcnt vmcnt(61) lgkmcnt(1)
	v_lshlrev_b32_e32 v138, 16, v238
	v_and_b32_e32 v139, 0xffff0000, v238
	v_lshlrev_b32_e32 v140, 16, v239
	v_and_b32_e32 v141, 0xffff0000, v239
	v_pk_add_f32 v[26:27], v[26:27], v[138:139]
	v_pk_add_f32 v[28:29], v[28:29], v[140:141]
	v_cvt_pk_bf16_f32 v238, v26, v27
	v_cvt_pk_bf16_f32 v239, v28, v29
	v_add_u32_e32 v136, 0x70000, v132
	global_store_dwordx2 v136, v[238:239], s[6:7] offset:256
	v_and_b32_e32 v139, 0xffff0000, v238
	v_lshlrev_b32_e32 v138, 16, v238
	v_mul_f32_e32 v142, v139, v139
	v_lshlrev_b32_e32 v140, 16, v239
	v_fmac_f32_e32 v142, v138, v138
	v_and_b32_e32 v141, 0xffff0000, v239
	v_fmac_f32_e32 v142, v140, v140
	v_fmac_f32_e32 v142, v141, v141
	v_mov_b32_e32 v143, v142
	s_nop 1
	v_permlane16_swap_b32_e32 v143, v142
	v_add_f32_e32 v142, v142, v143
	s_nop 1
	v_mov_b32_dpp v143, v142 row_ror:8 row_mask:0xf bank_mask:0xf
	v_add_f32_e32 v142, v142, v143
	s_nop 1
	v_mov_b32_dpp v143, v142 row_ror:4 row_mask:0xf bank_mask:0xf
	v_add_f32_e32 v142, v142, v143
	s_nop 1
	v_mov_b32_dpp v143, v142 row_ror:2 row_mask:0xf bank_mask:0xf
	v_add_f32_e32 v142, v142, v143
	s_nop 1
	v_mov_b32_dpp v143, v142 row_ror:1 row_mask:0xf bank_mask:0xf
	v_add_f32_e32 v142, v142, v143
	v_add_u32_e32 v137, 0x1c00, v133
	s_mov_b64 exec, s[10:11]
	global_store_dword v137, v142, s[8:9] offset:4
	s_mov_b64 exec, -1
	s_waitcnt vmcnt(62) lgkmcnt(0)
	v_lshlrev_b32_e32 v138, 16, v240
	v_and_b32_e32 v139, 0xffff0000, v240
	v_lshlrev_b32_e32 v140, 16, v241
	v_and_b32_e32 v141, 0xffff0000, v241
	v_pk_add_f32 v[30:31], v[30:31], v[138:139]
	v_pk_add_f32 v[32:33], v[32:33], v[140:141]
	v_cvt_pk_bf16_f32 v240, v30, v31
	v_cvt_pk_bf16_f32 v241, v32, v33
	v_add_u32_e32 v136, 0x78000, v132
	global_store_dwordx2 v136, v[240:241], s[6:7] offset:256
	v_and_b32_e32 v139, 0xffff0000, v240
	v_lshlrev_b32_e32 v138, 16, v240
	v_mul_f32_e32 v142, v139, v139
	v_lshlrev_b32_e32 v140, 16, v241
	v_fmac_f32_e32 v142, v138, v138
	v_and_b32_e32 v141, 0xffff0000, v241
	v_fmac_f32_e32 v142, v140, v140
	v_fmac_f32_e32 v142, v141, v141
	v_mov_b32_e32 v143, v142
	s_nop 1
	v_permlane16_swap_b32_e32 v143, v142
	v_add_f32_e32 v142, v142, v143
	s_nop 1
	v_mov_b32_dpp v143, v142 row_ror:8 row_mask:0xf bank_mask:0xf
	v_add_f32_e32 v142, v142, v143
	s_nop 1
	v_mov_b32_dpp v143, v142 row_ror:4 row_mask:0xf bank_mask:0xf
	v_add_f32_e32 v142, v142, v143
	s_nop 1
	v_mov_b32_dpp v143, v142 row_ror:2 row_mask:0xf bank_mask:0xf
	v_add_f32_e32 v142, v142, v143
	s_nop 1
	v_mov_b32_dpp v143, v142 row_ror:1 row_mask:0xf bank_mask:0xf
	v_add_f32_e32 v142, v142, v143
	v_add_u32_e32 v137, 0x1e00, v133
	s_mov_b64 exec, s[10:11]
	global_store_dword v137, v142, s[8:9] offset:4
	s_mov_b64 exec, -1
	s_branch .LBB0_55

; DI unsigned pk2(float a, float b) { f32x2 v = {a, b}; bf2_t r = __builtin_convertvector(v, bf2_t); return __builtin_bit_cast(unsigned, r); }
; DI f32x4 unpk4(u32x2 u) { f32x4 r = {__uint_as_float(u[0] << 16), __uint_as_float(u[0] & 0xffff0000u), __uint_as_float(u[1] << 16), __uint_as_float(u[1] & 0xffff0000u)}; return r; }
; template <int MODE>
; DI void gemm_tile(const Params& p, const bf16_t* __restrict__ A, const bf16_t* __restrict__ Bt, int K, int brow, int bcol, int mp, int nt, bool vt, char* smem) {
;     ...
;   u32x2 xnx[4];
;   if (RESID) {
; #pragma unroll
;     for (int pq = 0; pq < 4; ++pq) xnx[pq] = *(const u32x2*)((const bf16_t*)(p.ws + OFF_XB) + (size_t)(m0 + pq * 16 + (tid >> 5)) * DM + n0 + (tid & 31) * 4);
;   }
; #pragma unroll
;   for (int ai = 0; ai < 2; ++ai)
; #pragma unroll
;     for (int bj = 0; bj < 2; ++bj) {
; #pragma unroll
;       for (int m = 0; m < 4; ++m)
; #pragma unroll
;         for (int n = 0; n < 2; ++n) *(f32x4*)(st + (wc * 32 + n * 16 + fr) * 132 + wr * 64 + m * 16 + fq * 4) = acc[ai][bj][m][n];
;       __syncthreads();
; #pragma unroll 1
;       for (int pg = 0; pg < 2; ++pg) {
;       u32x2 xo[4];
;       if (RESID) {
; #pragma unroll
;         for (int pq = 0; pq < 4; ++pq) xo[pq] = xnx[pq];
;         const int q = ai * 2 + bj, nq = pg ? q + 1 : q, npg = pg ^ 1;
;         if (nq < 4) {
;           const int nai = nq >> 1, nbj = nq & 1;
; #pragma unroll
;           for (int pq = 0; pq < 4; ++pq)
;             xnx[pq] = *(const u32x2*)((const bf16_t*)(p.ws + OFF_XB) + (size_t)(m0 + nbj * 128 + (npg * 4 + pq) * 16 + (tid >> 5)) * DM + n0 + nai * 128 + (tid & 31) * 4);
;     ...
;           const int tok = m0 + bj * 128 + y, col = n0 + ai * 128 + x4;
;           const f32x4 xs = unpk4(xo[pq]) + v;
;           u32x2 o = {pk2(xs[0], xs[1]), pk2(xs[2], xs[3])};
;           *(u32x2*)((bf16_t*)(p.ws + OFF_XB) + (size_t)tok * DM + col) = o;
;           const f32x4 xn = unpk4(o);
;           float ss = xn[0] * xn[0] + xn[1] * xn[1] + xn[2] * xn[2] + xn[3] * xn[3];
; #pragma unroll
;           for (int o2 = 16; o2 > 0; o2 >>= 1) ss += __shfl_xor(ss, o2);
;           if ((tid & 31) == 0) ((float*)(p.ws + (MODE == MODE_OUT ? OFF_SSB : OFF_SSA)))[(size_t)tok * 8 + nt * 2 + ai] = ss;
.LBB0_529:
	s_or_b64 exec, exec, s[6:7]
	v_lshrrev_b32_e32 v130, 5, v152
	v_and_b32_e32 v131, 31, v152
	v_cmp_eq_u32_e64 s[10:11], 0, v131
	v_lshlrev_b32_e32 v136, 3, v131
	v_add_u32_e32 v137, s4, v130
	s_lshl_b32 s5, s2, 1
	v_lshl_add_u32 v132, v137, 11, v136
	v_add_u32_e32 v132, s5, v132
	v_lshlrev_b32_e32 v133, 5, v137
	v_bfe_u32 v136, v152, 6, 2
	v_and_b32_e32 v137, 15, v152
	v_lshl_add_u32 v136, v136, 5, v137
	v_mul_u32_u24_e32 v136, 0x210, v136
	v_lshrrev_b32_e32 v137, 8, v152
	v_lshl_add_u32 v136, v137, 8, v136
	v_bfe_u32 v137, v152, 4, 2
	v_lshl_add_u32 v134, v137, 4, v136
	v_mul_u32_u24_e32 v136, 0x210, v130
	v_lshl_add_u32 v135, v131, 4, v136
	v_readlane_b32 s6, v247, 7
	v_readlane_b32 s7, v247, 8
	s_mov_b64 s[8:9], s[66:67]
	s_lshl_b32 s12, s23, 3
	s_nop 1
	s_add_u32 s8, s8, s12
	s_addc_u32 s9, s9, 0
	s_nop 4
	global_load_dwordx2 v[164:165], v132, s[6:7]
	v_add_u32_e32 v136, 0x8000, v132
	global_load_dwordx2 v[166:167], v136, s[6:7]
	v_add_u32_e32 v136, 0x10000, v132
	global_load_dwordx2 v[168:169], v136, s[6:7]
	v_add_u32_e32 v136, 0x18000, v132
	global_load_dwordx2 v[170:171], v136, s[6:7]
	v_add_u32_e32 v136, 0x20000, v132
	global_load_dwordx2 v[172:173], v136, s[6:7]
	v_add_u32_e32 v136, 0x28000, v132
	global_load_dwordx2 v[174:175], v136, s[6:7]
	v_add_u32_e32 v136, 0x30000, v132
	global_load_dwordx2 v[176:177], v136, s[6:7]
	v_add_u32_e32 v136, 0x38000, v132
	global_load_dwordx2 v[178:179], v136, s[6:7]
	v_add_u32_e32 v136, 0x40000, v132
	global_load_dwordx2 v[180:181], v136, s[6:7]
	v_add_u32_e32 v136, 0x48000, v132
	global_load_dwordx2 v[182:183], v136, s[6:7]
	v_add_u32_e32 v136, 0x50000, v132
	global_load_dwordx2 v[184:185], v136, s[6:7]
	v_add_u32_e32 v136, 0x58000, v132
	global_load_dwordx2 v[186:187], v136, s[6:7]
	v_add_u32_e32 v136, 0x60000, v132
	global_load_dwordx2 v[188:189], v136, s[6:7]
	v_add_u32_e32 v136, 0x68000, v132
	global_load_dwordx2 v[190:191], v136, s[6:7]
	v_add_u32_e32 v136, 0x70000, v132
	global_load_dwordx2 v[192:193], v136, s[6:7]
	v_add_u32_e32 v136, 0x78000, v132
	global_load_dwordx2 v[194:195], v136, s[6:7]
	global_load_dwordx2 v[196:197], v132, s[6:7] offset:256
	v_add_u32_e32 v136, 0x8000, v132
	global_load_dwordx2 v[198:199], v136, s[6:7] offset:256
	v_add_u32_e32 v136, 0x10000, v132
	global_load_dwordx2 v[214:215], v136, s[6:7] offset:256
	v_add_u32_e32 v136, 0x18000, v132
	global_load_dwordx2 v[216:217], v136, s[6:7] offset:256
	v_add_u32_e32 v136, 0x20000, v132
	global_load_dwordx2 v[218:219], v136, s[6:7] offset:256
	v_add_u32_e32 v136, 0x28000, v132
	global_load_dwordx2 v[220:221], v136, s[6:7] offset:256
	v_add_u32_e32 v136, 0x30000, v132
	global_load_dwordx2 v[222:223], v136, s[6:7] offset:256
	v_add_u32_e32 v136, 0x38000, v132
	global_load_dwordx2 v[224:225], v136, s[6:7] offset:256
	v_add_u32_e32 v136, 0x40000, v132
	global_load_dwordx2 v[226:227], v136, s[6:7] offset:256
	v_add_u32_e32 v136, 0x48000, v132
	global_load_dwordx2 v[228:229], v136, s[6:7] offset:256
	v_add_u32_e32 v136, 0x50000, v132
	global_load_dwordx2 v[230:231], v136, s[6:7] offset:256
	v_add_u32_e32 v136, 0x58000, v132
	global_load_dwordx2 v[232:233], v136, s[6:7] offset:256
	v_add_u32_e32 v136, 0x60000, v132
	global_load_dwordx2 v[234:235], v136, s[6:7] offset:256
	v_add_u32_e32 v136, 0x68000, v132
	global_load_dwordx2 v[236:237], v136, s[6:7] offset:256
	v_add_u32_e32 v136, 0x70000, v132
	global_load_dwordx2 v[238:239], v136, s[6:7] offset:256
	v_add_u32_e32 v136, 0x78000, v132
	global_load_dwordx2 v[240:241], v136, s[6:7] offset:256
	ds_write_b128 v134, v[98:101]
	ds_write_b128 v134, v[102:105] offset:8448
	ds_write_b128 v134, v[106:109] offset:64
	ds_write_b128 v134, v[110:113] offset:8512
	ds_write_b128 v134, v[114:117] offset:128
	ds_write_b128 v134, v[118:121] offset:8576
	ds_write_b128 v134, v[122:125] offset:192
	ds_write_b128 v134, v[126:129] offset:8640
	s_waitcnt lgkmcnt(0)
	s_barrier
	ds_read_b128 v[98:101], v135
	ds_read_b128 v[102:105], v135 offset:8448
	ds_read_b128 v[106:109], v135 offset:16896
	ds_read_b128 v[110:113], v135 offset:25344
	ds_read_b128 v[114:117], v135 offset:33792
	ds_read_b128 v[118:121], v135 offset:42240
	ds_read_b128 v[122:125], v135 offset:50688
	ds_read_b128 v[126:129], v135 offset:59136
	s_waitcnt vmcnt(31) lgkmcnt(7)
	v_lshlrev_b32_e32 v138, 16, v164
	v_and_b32_e32 v139, 0xffff0000, v164
	v_lshlrev_b32_e32 v140, 16, v165
	v_and_b32_e32 v141, 0xffff0000, v165
	v_pk_add_f32 v[98:99], v[98:99], v[138:139]
	v_pk_add_f32 v[100:101], v[100:101], v[140:141]
	v_cvt_pk_bf16_f32 v164, v98, v99
	v_cvt_pk_bf16_f32 v165, v100, v101
	global_store_dwordx2 v132, v[164:165], s[6:7]
	v_and_b32_e32 v139, 0xffff0000, v164
	v_lshlrev_b32_e32 v138, 16, v164
	v_mul_f32_e32 v142, v139, v139
	v_lshlrev_b32_e32 v140, 16, v165
	v_fmac_f32_e32 v142, v138, v138
	v_and_b32_e32 v141, 0xffff0000, v165
	v_fmac_f32_e32 v142, v140, v140
	v_fmac_f32_e32 v142, v141, v141
	v_mov_b32_e32 v143, v142
	s_nop 1
	v_permlane16_swap_b32_e32 v143, v142
	v_add_f32_e32 v142, v142, v143
	s_nop 1
	v_mov_b32_dpp v143, v142 row_ror:8 row_mask:0xf bank_mask:0xf
	v_add_f32_e32 v142, v142, v143
	s_nop 1
	v_mov_b32_dpp v143, v142 row_ror:4 row_mask:0xf bank_mask:0xf
	v_add_f32_e32 v142, v142, v143
	s_nop 1
	v_mov_b32_dpp v143, v142 row_ror:2 row_mask:0xf bank_mask:0xf
	v_add_f32_e32 v142, v142, v143
	s_nop 1
	v_mov_b32_dpp v143, v142 row_ror:1 row_mask:0xf bank_mask:0xf
	v_add_f32_e32 v142, v142, v143
	s_mov_b64 exec, s[10:11]
	global_store_dword v133, v142, s[8:9]
	s_mov_b64 exec, -1
	s_waitcnt vmcnt(32) lgkmcnt(6)
; DI unsigned pk2(float a, float b) { f32x2 v = {a, b}; bf2_t r = __builtin_convertvector(v, bf2_t); return __builtin_bit_cast(unsigned, r); }
; DI f32x4 unpk4(u32x2 u) { f32x4 r = {__uint_as_float(u[0] << 16), __uint_as_float(u[0] & 0xffff0000u), __uint_as_float(u[1] << 16), __uint_as_float(u[1] & 0xffff0000u)}; return r; }
; template <int MODE>
; DI void gemm_tile(const Params& p, const bf16_t* __restrict__ A, const bf16_t* __restrict__ Bt, int K, int brow, int bcol, int mp, int nt, bool vt, char* smem) {
;     ...
;           const int tok = m0 + bj * 128 + y, col = n0 + ai * 128 + x4;
;           const f32x4 xs = unpk4(xo[pq]) + v;
;           u32x2 o = {pk2(xs[0], xs[1]), pk2(xs[2], xs[3])};
;           *(u32x2*)((bf16_t*)(p.ws + OFF_XB) + (size_t)tok * DM + col) = o;
;           const f32x4 xn = unpk4(o);
;           float ss = xn[0] * xn[0] + xn[1] * xn[1] + xn[2] * xn[2] + xn[3] * xn[3];
; #pragma unroll
;           for (int o2 = 16; o2 > 0; o2 >>= 1) ss += __shfl_xor(ss, o2);
;           if ((tid & 31) == 0) ((float*)(p.ws + (MODE == MODE_OUT ? OFF_SSB : OFF_SSA)))[(size_t)tok * 8 + nt * 2 + ai] = ss;
	v_lshlrev_b32_e32 v138, 16, v166
	v_and_b32_e32 v139, 0xffff0000, v166
	v_lshlrev_b32_e32 v140, 16, v167
	v_and_b32_e32 v141, 0xffff0000, v167
	v_pk_add_f32 v[102:103], v[102:103], v[138:139]
	v_pk_add_f32 v[104:105], v[104:105], v[140:141]
	v_cvt_pk_bf16_f32 v166, v102, v103
	v_cvt_pk_bf16_f32 v167, v104, v105
	v_add_u32_e32 v136, 0x8000, v132
	global_store_dwordx2 v136, v[166:167], s[6:7]
	v_and_b32_e32 v139, 0xffff0000, v166
	v_lshlrev_b32_e32 v138, 16, v166
	v_mul_f32_e32 v142, v139, v139
	v_lshlrev_b32_e32 v140, 16, v167
	v_fmac_f32_e32 v142, v138, v138
	v_and_b32_e32 v141, 0xffff0000, v167
	v_fmac_f32_e32 v142, v140, v140
	v_fmac_f32_e32 v142, v141, v141
	v_mov_b32_e32 v143, v142
	s_nop 1
	v_permlane16_swap_b32_e32 v143, v142
	v_add_f32_e32 v142, v142, v143
	s_nop 1
	v_mov_b32_dpp v143, v142 row_ror:8 row_mask:0xf bank_mask:0xf
	v_add_f32_e32 v142, v142, v143
	s_nop 1
	v_mov_b32_dpp v143, v142 row_ror:4 row_mask:0xf bank_mask:0xf
	v_add_f32_e32 v142, v142, v143
	s_nop 1
	v_mov_b32_dpp v143, v142 row_ror:2 row_mask:0xf bank_mask:0xf
	v_add_f32_e32 v142, v142, v143
	s_nop 1
	v_mov_b32_dpp v143, v142 row_ror:1 row_mask:0xf bank_mask:0xf
	v_add_f32_e32 v142, v142, v143
	v_add_u32_e32 v137, 0x200, v133
	s_mov_b64 exec, s[10:11]
	global_store_dword v137, v142, s[8:9]
	s_mov_b64 exec, -1
	s_waitcnt vmcnt(33) lgkmcnt(5)
	v_lshlrev_b32_e32 v138, 16, v168
	v_and_b32_e32 v139, 0xffff0000, v168
	v_lshlrev_b32_e32 v140, 16, v169
	v_and_b32_e32 v141, 0xffff0000, v169
	v_pk_add_f32 v[106:107], v[106:107], v[138:139]
	v_pk_add_f32 v[108:109], v[108:109], v[140:141]
	v_cvt_pk_bf16_f32 v168, v106, v107
	v_cvt_pk_bf16_f32 v169, v108, v109
	v_add_u32_e32 v136, 0x10000, v132
	global_store_dwordx2 v136, v[168:169], s[6:7]
	v_and_b32_e32 v139, 0xffff0000, v168
	v_lshlrev_b32_e32 v138, 16, v168
	v_mul_f32_e32 v142, v139, v139
	v_lshlrev_b32_e32 v140, 16, v169
	v_fmac_f32_e32 v142, v138, v138
	v_and_b32_e32 v141, 0xffff0000, v169
	v_fmac_f32_e32 v142, v140, v140
	v_fmac_f32_e32 v142, v141, v141
	v_mov_b32_e32 v143, v142
	s_nop 1
	v_permlane16_swap_b32_e32 v143, v142
	v_add_f32_e32 v142, v142, v143
	s_nop 1
	v_mov_b32_dpp v143, v142 row_ror:8 row_mask:0xf bank_mask:0xf
	v_add_f32_e32 v142, v142, v143
	s_nop 1
	v_mov_b32_dpp v143, v142 row_ror:4 row_mask:0xf bank_mask:0xf
	v_add_f32_e32 v142, v142, v143
	s_nop 1
	v_mov_b32_dpp v143, v142 row_ror:2 row_mask:0xf bank_mask:0xf
	v_add_f32_e32 v142, v142, v143
	s_nop 1
	v_mov_b32_dpp v143, v142 row_ror:1 row_mask:0xf bank_mask:0xf
	v_add_f32_e32 v142, v142, v143
	v_add_u32_e32 v137, 0x400, v133
	s_mov_b64 exec, s[10:11]
	global_store_dword v137, v142, s[8:9]
	s_mov_b64 exec, -1
	s_waitcnt vmcnt(34) lgkmcnt(4)
	v_lshlrev_b32_e32 v138, 16, v170
	v_and_b32_e32 v139, 0xffff0000, v170
	v_lshlrev_b32_e32 v140, 16, v171
	v_and_b32_e32 v141, 0xffff0000, v171
	v_pk_add_f32 v[110:111], v[110:111], v[138:139]
	v_pk_add_f32 v[112:113], v[112:113], v[140:141]
	v_cvt_pk_bf16_f32 v170, v110, v111
	v_cvt_pk_bf16_f32 v171, v112, v113
	v_add_u32_e32 v136, 0x18000, v132
	global_store_dwordx2 v136, v[170:171], s[6:7]
	v_and_b32_e32 v139, 0xffff0000, v170
	v_lshlrev_b32_e32 v138, 16, v170
	v_mul_f32_e32 v142, v139, v139
	v_lshlrev_b32_e32 v140, 16, v171
	v_fmac_f32_e32 v142, v138, v138
	v_and_b32_e32 v141, 0xffff0000, v171
	v_fmac_f32_e32 v142, v140, v140
	v_fmac_f32_e32 v142, v141, v141
	v_mov_b32_e32 v143, v142
	s_nop 1
	v_permlane16_swap_b32_e32 v143, v142
	v_add_f32_e32 v142, v142, v143
	s_nop 1
	v_mov_b32_dpp v143, v142 row_ror:8 row_mask:0xf bank_mask:0xf
	v_add_f32_e32 v142, v142, v143
	s_nop 1
	v_mov_b32_dpp v143, v142 row_ror:4 row_mask:0xf bank_mask:0xf
	v_add_f32_e32 v142, v142, v143
	s_nop 1
	v_mov_b32_dpp v143, v142 row_ror:2 row_mask:0xf bank_mask:0xf
	v_add_f32_e32 v142, v142, v143
	s_nop 1
	v_mov_b32_dpp v143, v142 row_ror:1 row_mask:0xf bank_mask:0xf
	v_add_f32_e32 v142, v142, v143
	v_add_u32_e32 v137, 0x600, v133
	s_mov_b64 exec, s[10:11]
	global_store_dword v137, v142, s[8:9]
	s_mov_b64 exec, -1
	s_waitcnt vmcnt(35) lgkmcnt(3)
	v_lshlrev_b32_e32 v138, 16, v172
	v_and_b32_e32 v139, 0xffff0000, v172
	v_lshlrev_b32_e32 v140, 16, v173
	v_and_b32_e32 v141, 0xffff0000, v173
	v_pk_add_f32 v[114:115], v[114:115], v[138:139]
	v_pk_add_f32 v[116:117], v[116:117], v[140:141]
	v_cvt_pk_bf16_f32 v172, v114, v115
	v_cvt_pk_bf16_f32 v173, v116, v117
	v_add_u32_e32 v136, 0x20000, v132
	global_store_dwordx2 v136, v[172:173], s[6:7]
	v_and_b32_e32 v139, 0xffff0000, v172
	v_lshlrev_b32_e32 v138, 16, v172
	v_mul_f32_e32 v142, v139, v139
	v_lshlrev_b32_e32 v140, 16, v173
	v_fmac_f32_e32 v142, v138, v138
	v_and_b32_e32 v141, 0xffff0000, v173
	v_fmac_f32_e32 v142, v140, v140
	v_fmac_f32_e32 v142, v141, v141
	v_mov_b32_e32 v143, v142
	s_nop 1
	v_permlane16_swap_b32_e32 v143, v142
	v_add_f32_e32 v142, v142, v143
	s_nop 1
	v_mov_b32_dpp v143, v142 row_ror:8 row_mask:0xf bank_mask:0xf
	v_add_f32_e32 v142, v142, v143
	s_nop 1
	v_mov_b32_dpp v143, v142 row_ror:4 row_mask:0xf bank_mask:0xf
	v_add_f32_e32 v142, v142, v143
	s_nop 1
	v_mov_b32_dpp v143, v142 row_ror:2 row_mask:0xf bank_mask:0xf
	v_add_f32_e32 v142, v142, v143
	s_nop 1
	v_mov_b32_dpp v143, v142 row_ror:1 row_mask:0xf bank_mask:0xf
	v_add_f32_e32 v142, v142, v143
	v_add_u32_e32 v137, 0x800, v133
	s_mov_b64 exec, s[10:11]
	global_store_dword v137, v142, s[8:9]
	s_mov_b64 exec, -1
	s_waitcnt vmcnt(36) lgkmcnt(2)
; DI unsigned pk2(float a, float b) { f32x2 v = {a, b}; bf2_t r = __builtin_convertvector(v, bf2_t); return __builtin_bit_cast(unsigned, r); }
; DI f32x4 unpk4(u32x2 u) { f32x4 r = {__uint_as_float(u[0] << 16), __uint_as_float(u[0] & 0xffff0000u), __uint_as_float(u[1] << 16), __uint_as_float(u[1] & 0xffff0000u)}; return r; }
; template <int MODE>
; DI void gemm_tile(const Params& p, const bf16_t* __restrict__ A, const bf16_t* __restrict__ Bt, int K, int brow, int bcol, int mp, int nt, bool vt, char* smem) {
;     ...
;   for (int ai = 0; ai < 2; ++ai)
; #pragma unroll
;     for (int bj = 0; bj < 2; ++bj) {
; #pragma unroll
;       for (int m = 0; m < 4; ++m)
; #pragma unroll
;         for (int n = 0; n < 2; ++n) *(f32x4*)(st + (wc * 32 + n * 16 + fr) * 132 + wr * 64 + m * 16 + fq * 4) = acc[ai][bj][m][n];
;       __syncthreads();
;     ...
;           const int tok = m0 + bj * 128 + y, col = n0 + ai * 128 + x4;
;           const f32x4 xs = unpk4(xo[pq]) + v;
;           u32x2 o = {pk2(xs[0], xs[1]), pk2(xs[2], xs[3])};
;           *(u32x2*)((bf16_t*)(p.ws + OFF_XB) + (size_t)tok * DM + col) = o;
;           const f32x4 xn = unpk4(o);
;           float ss = xn[0] * xn[0] + xn[1] * xn[1] + xn[2] * xn[2] + xn[3] * xn[3];
; #pragma unroll
;           for (int o2 = 16; o2 > 0; o2 >>= 1) ss += __shfl_xor(ss, o2);
;           if ((tid & 31) == 0) ((float*)(p.ws + (MODE == MODE_OUT ? OFF_SSB : OFF_SSA)))[(size_t)tok * 8 + nt * 2 + ai] = ss;
	v_lshlrev_b32_e32 v138, 16, v174
	v_and_b32_e32 v139, 0xffff0000, v174
	v_lshlrev_b32_e32 v140, 16, v175
	v_and_b32_e32 v141, 0xffff0000, v175
	v_pk_add_f32 v[118:119], v[118:119], v[138:139]
	v_pk_add_f32 v[120:121], v[120:121], v[140:141]
	v_cvt_pk_bf16_f32 v174, v118, v119
	v_cvt_pk_bf16_f32 v175, v120, v121
	v_add_u32_e32 v136, 0x28000, v132
	global_store_dwordx2 v136, v[174:175], s[6:7]
	v_and_b32_e32 v139, 0xffff0000, v174
	v_lshlrev_b32_e32 v138, 16, v174
	v_mul_f32_e32 v142, v139, v139
	v_lshlrev_b32_e32 v140, 16, v175
	v_fmac_f32_e32 v142, v138, v138
	v_and_b32_e32 v141, 0xffff0000, v175
	v_fmac_f32_e32 v142, v140, v140
	v_fmac_f32_e32 v142, v141, v141
	v_mov_b32_e32 v143, v142
	s_nop 1
	v_permlane16_swap_b32_e32 v143, v142
	v_add_f32_e32 v142, v142, v143
	s_nop 1
	v_mov_b32_dpp v143, v142 row_ror:8 row_mask:0xf bank_mask:0xf
	v_add_f32_e32 v142, v142, v143
	s_nop 1
	v_mov_b32_dpp v143, v142 row_ror:4 row_mask:0xf bank_mask:0xf
	v_add_f32_e32 v142, v142, v143
	s_nop 1
	v_mov_b32_dpp v143, v142 row_ror:2 row_mask:0xf bank_mask:0xf
	v_add_f32_e32 v142, v142, v143
	s_nop 1
	v_mov_b32_dpp v143, v142 row_ror:1 row_mask:0xf bank_mask:0xf
	v_add_f32_e32 v142, v142, v143
	v_add_u32_e32 v137, 0xa00, v133
	s_mov_b64 exec, s[10:11]
	global_store_dword v137, v142, s[8:9]
	s_mov_b64 exec, -1
	s_waitcnt vmcnt(37) lgkmcnt(1)
	v_lshlrev_b32_e32 v138, 16, v176
	v_and_b32_e32 v139, 0xffff0000, v176
	v_lshlrev_b32_e32 v140, 16, v177
	v_and_b32_e32 v141, 0xffff0000, v177
	v_pk_add_f32 v[122:123], v[122:123], v[138:139]
	v_pk_add_f32 v[124:125], v[124:125], v[140:141]
	v_cvt_pk_bf16_f32 v176, v122, v123
	v_cvt_pk_bf16_f32 v177, v124, v125
	v_add_u32_e32 v136, 0x30000, v132
	global_store_dwordx2 v136, v[176:177], s[6:7]
	v_and_b32_e32 v139, 0xffff0000, v176
	v_lshlrev_b32_e32 v138, 16, v176
	v_mul_f32_e32 v142, v139, v139
	v_lshlrev_b32_e32 v140, 16, v177
	v_fmac_f32_e32 v142, v138, v138
	v_and_b32_e32 v141, 0xffff0000, v177
	v_fmac_f32_e32 v142, v140, v140
	v_fmac_f32_e32 v142, v141, v141
	v_mov_b32_e32 v143, v142
	s_nop 1
	v_permlane16_swap_b32_e32 v143, v142
	v_add_f32_e32 v142, v142, v143
	s_nop 1
	v_mov_b32_dpp v143, v142 row_ror:8 row_mask:0xf bank_mask:0xf
	v_add_f32_e32 v142, v142, v143
	s_nop 1
	v_mov_b32_dpp v143, v142 row_ror:4 row_mask:0xf bank_mask:0xf
	v_add_f32_e32 v142, v142, v143
	s_nop 1
	v_mov_b32_dpp v143, v142 row_ror:2 row_mask:0xf bank_mask:0xf
	v_add_f32_e32 v142, v142, v143
	s_nop 1
	v_mov_b32_dpp v143, v142 row_ror:1 row_mask:0xf bank_mask:0xf
	v_add_f32_e32 v142, v142, v143
	v_add_u32_e32 v137, 0xc00, v133
	s_mov_b64 exec, s[10:11]
	global_store_dword v137, v142, s[8:9]
	s_mov_b64 exec, -1
	s_waitcnt vmcnt(38) lgkmcnt(0)
	v_lshlrev_b32_e32 v138, 16, v178
	v_and_b32_e32 v139, 0xffff0000, v178
	v_lshlrev_b32_e32 v140, 16, v179
	v_and_b32_e32 v141, 0xffff0000, v179
	v_pk_add_f32 v[126:127], v[126:127], v[138:139]
	v_pk_add_f32 v[128:129], v[128:129], v[140:141]
	v_cvt_pk_bf16_f32 v178, v126, v127
	v_cvt_pk_bf16_f32 v179, v128, v129
	v_add_u32_e32 v136, 0x38000, v132
	global_store_dwordx2 v136, v[178:179], s[6:7]
	v_and_b32_e32 v139, 0xffff0000, v178
	v_lshlrev_b32_e32 v138, 16, v178
	v_mul_f32_e32 v142, v139, v139
	v_lshlrev_b32_e32 v140, 16, v179
	v_fmac_f32_e32 v142, v138, v138
	v_and_b32_e32 v141, 0xffff0000, v179
	v_fmac_f32_e32 v142, v140, v140
	v_fmac_f32_e32 v142, v141, v141
	v_mov_b32_e32 v143, v142
	s_nop 1
	v_permlane16_swap_b32_e32 v143, v142
	v_add_f32_e32 v142, v142, v143
	s_nop 1
	v_mov_b32_dpp v143, v142 row_ror:8 row_mask:0xf bank_mask:0xf
	v_add_f32_e32 v142, v142, v143
	s_nop 1
	v_mov_b32_dpp v143, v142 row_ror:4 row_mask:0xf bank_mask:0xf
	v_add_f32_e32 v142, v142, v143
	s_nop 1
	v_mov_b32_dpp v143, v142 row_ror:2 row_mask:0xf bank_mask:0xf
	v_add_f32_e32 v142, v142, v143
	s_nop 1
	v_mov_b32_dpp v143, v142 row_ror:1 row_mask:0xf bank_mask:0xf
	v_add_f32_e32 v142, v142, v143
	v_add_u32_e32 v137, 0xe00, v133
	s_mov_b64 exec, s[10:11]
	global_store_dword v137, v142, s[8:9]
	s_mov_b64 exec, -1
	s_barrier
	ds_write_b128 v134, v[66:69]
	ds_write_b128 v134, v[70:73] offset:8448
	ds_write_b128 v134, v[74:77] offset:64
	ds_write_b128 v134, v[78:81] offset:8512
	ds_write_b128 v134, v[82:85] offset:128
	ds_write_b128 v134, v[86:89] offset:8576
	ds_write_b128 v134, v[90:93] offset:192
	ds_write_b128 v134, v[94:97] offset:8640
	s_waitcnt lgkmcnt(0)
	s_barrier
; template <int MODE>
; DI void gemm_tile(const Params& p, const bf16_t* __restrict__ A, const bf16_t* __restrict__ Bt, int K, int brow, int bcol, int mp, int nt, bool vt, char* smem) {
;     ...
;       for (int pq = 0; pq < 4; ++pq) {
;         const int pass = pg * 4 + pq;
;         const int y = pass * 16 + (tid >> 5), x4 = (tid & 31) * 4;
;         const f32x4 v = *(const f32x4*)(st + y * 132 + x4);
;         if (MODE == MODE_PROJ) {
;           if (vt) {
;             const int vrow = (nt - 8) * 256 + bj * 128 + y, tk = m0 + ai * 128 + x4, b = tk >> 11, sq = tk & 2047;
;             const f32x4 rr = *(const f32x4*)(rsl + ai * 128 + x4);
;             u32x2 o = {pk2(v[0] * rr[0], v[1] * rr[1]), pk2(v[2] * rr[2], v[3] * rr[3])};
;             *(u32x2*)((bf16_t*)(p.ws + OFF_VT) + ((size_t)(b * VROWS + vrow)) * SEQ + sq) = o;
;           } else {
;             const int tok = m0 + bj * 128 + y, col = n0 + ai * 128 + x4;
;             const float rs = rsl[bj * 128 + y];
;             if (col < QKW) {
;               u32x2 o = {pk2(v[0] * rs, v[1] * rs), pk2(v[2] * rs, v[3] * rs)};
;               *(u32x2*)((bf16_t*)(p.ws + OFF_QK) + (size_t)tok * QKW + col) = o;
;             } else if (col < QKW + 16) {
;               f32x4 o = {v[0] * rs, v[1] * rs, v[2] * rs, v[3] * rs};
;               *(f32x4*)((float*)(p.ws + OFF_GATE) + (size_t)tok * 16 + (col - QKW)) = o;
;             }
;           }
;         } else if (MODE == MODE_UP) {
;           const int tok = m0 + bj * 128 + y, col = n0 + ai * 128 + x4;
;           const float rs = rsl[bj * 128 + y];
;           const float a0 = fmaxf(v[0] * rs, 0.f), a1 = fmaxf(v[1] * rs, 0.f), a2 = fmaxf(v[2] * rs, 0.f), a3 = fmaxf(v[3] * rs, 0.f);
;           u32x2 o = {pk2(a0 * a0, a1 * a1), pk2(a2 * a2, a3 * a3)};
;           *(u32x2*)((bf16_t*)(p.ws + OFF_U) + (size_t)tok * DFF + col) = o;
;         } else {
;           const int tok = m0 + bj * 128 + y, col = n0 + ai * 128 + x4;
;           const f32x4 xs = unpk4(xo[pq]) + v;
;           u32x2 o = {pk2(xs[0], xs[1]), pk2(xs[2], xs[3])};
;           *(u32x2*)((bf16_t*)(p.ws + OFF_XB) + (size_t)tok * DM + col) = o;
;           const f32x4 xn = unpk4(o);
;           float ss = xn[0] * xn[0] + xn[1] * xn[1] + xn[2] * xn[2] + xn[3] * xn[3];
; #pragma unroll
;           for (int o2 = 16; o2 > 0; o2 >>= 1) ss += __shfl_xor(ss, o2);
	ds_read_b128 v[66:69], v135
	ds_read_b128 v[70:73], v135 offset:8448
	ds_read_b128 v[74:77], v135 offset:16896
	ds_read_b128 v[78:81], v135 offset:25344
	ds_read_b128 v[82:85], v135 offset:33792
	ds_read_b128 v[86:89], v135 offset:42240
	ds_read_b128 v[90:93], v135 offset:50688
	ds_read_b128 v[94:97], v135 offset:59136
	s_waitcnt vmcnt(39) lgkmcnt(7)
	v_lshlrev_b32_e32 v138, 16, v180
	v_and_b32_e32 v139, 0xffff0000, v180
	v_lshlrev_b32_e32 v140, 16, v181
	v_and_b32_e32 v141, 0xffff0000, v181
	v_pk_add_f32 v[66:67], v[66:67], v[138:139]
	v_pk_add_f32 v[68:69], v[68:69], v[140:141]
	v_cvt_pk_bf16_f32 v180, v66, v67
	v_cvt_pk_bf16_f32 v181, v68, v69
	v_add_u32_e32 v136, 0x40000, v132
	global_store_dwordx2 v136, v[180:181], s[6:7]
	v_and_b32_e32 v139, 0xffff0000, v180
	v_lshlrev_b32_e32 v138, 16, v180
	v_mul_f32_e32 v142, v139, v139
	v_lshlrev_b32_e32 v140, 16, v181
	v_fmac_f32_e32 v142, v138, v138
	v_and_b32_e32 v141, 0xffff0000, v181
	v_fmac_f32_e32 v142, v140, v140
	v_fmac_f32_e32 v142, v141, v141
	v_mov_b32_e32 v143, v142
	s_nop 1
	v_permlane16_swap_b32_e32 v143, v142
	v_add_f32_e32 v142, v142, v143
	s_nop 1
	v_mov_b32_dpp v143, v142 row_ror:8 row_mask:0xf bank_mask:0xf
	v_add_f32_e32 v142, v142, v143
	s_nop 1
	v_mov_b32_dpp v143, v142 row_ror:4 row_mask:0xf bank_mask:0xf
	v_add_f32_e32 v142, v142, v143
	s_nop 1
	v_mov_b32_dpp v143, v142 row_ror:2 row_mask:0xf bank_mask:0xf
	v_add_f32_e32 v142, v142, v143
	s_nop 1
	v_mov_b32_dpp v143, v142 row_ror:1 row_mask:0xf bank_mask:0xf
	v_add_f32_e32 v142, v142, v143
	v_add_u32_e32 v137, 0x1000, v133
	s_mov_b64 exec, s[10:11]
	global_store_dword v137, v142, s[8:9]
	s_mov_b64 exec, -1
	s_waitcnt vmcnt(40) lgkmcnt(6)
	v_lshlrev_b32_e32 v138, 16, v182
	v_and_b32_e32 v139, 0xffff0000, v182
	v_lshlrev_b32_e32 v140, 16, v183
	v_and_b32_e32 v141, 0xffff0000, v183
	v_pk_add_f32 v[70:71], v[70:71], v[138:139]
	v_pk_add_f32 v[72:73], v[72:73], v[140:141]
	v_cvt_pk_bf16_f32 v182, v70, v71
	v_cvt_pk_bf16_f32 v183, v72, v73
	v_add_u32_e32 v136, 0x48000, v132
	global_store_dwordx2 v136, v[182:183], s[6:7]
	v_and_b32_e32 v139, 0xffff0000, v182
	v_lshlrev_b32_e32 v138, 16, v182
	v_mul_f32_e32 v142, v139, v139
	v_lshlrev_b32_e32 v140, 16, v183
	v_fmac_f32_e32 v142, v138, v138
	v_and_b32_e32 v141, 0xffff0000, v183
	v_fmac_f32_e32 v142, v140, v140
	v_fmac_f32_e32 v142, v141, v141
	v_mov_b32_e32 v143, v142
	s_nop 1
	v_permlane16_swap_b32_e32 v143, v142
	v_add_f32_e32 v142, v142, v143
	s_nop 1
	v_mov_b32_dpp v143, v142 row_ror:8 row_mask:0xf bank_mask:0xf
	v_add_f32_e32 v142, v142, v143
	s_nop 1
	v_mov_b32_dpp v143, v142 row_ror:4 row_mask:0xf bank_mask:0xf
	v_add_f32_e32 v142, v142, v143
	s_nop 1
	v_mov_b32_dpp v143, v142 row_ror:2 row_mask:0xf bank_mask:0xf
	v_add_f32_e32 v142, v142, v143
	s_nop 1
	v_mov_b32_dpp v143, v142 row_ror:1 row_mask:0xf bank_mask:0xf
	v_add_f32_e32 v142, v142, v143
	v_add_u32_e32 v137, 0x1200, v133
	s_mov_b64 exec, s[10:11]
	global_store_dword v137, v142, s[8:9]
	s_mov_b64 exec, -1
	s_waitcnt vmcnt(41) lgkmcnt(5)
	v_lshlrev_b32_e32 v138, 16, v184
	v_and_b32_e32 v139, 0xffff0000, v184
	v_lshlrev_b32_e32 v140, 16, v185
	v_and_b32_e32 v141, 0xffff0000, v185
	v_pk_add_f32 v[74:75], v[74:75], v[138:139]
	v_pk_add_f32 v[76:77], v[76:77], v[140:141]
	v_cvt_pk_bf16_f32 v184, v74, v75
	v_cvt_pk_bf16_f32 v185, v76, v77
	v_add_u32_e32 v136, 0x50000, v132
	global_store_dwordx2 v136, v[184:185], s[6:7]
	v_and_b32_e32 v139, 0xffff0000, v184
	v_lshlrev_b32_e32 v138, 16, v184
	v_mul_f32_e32 v142, v139, v139
	v_lshlrev_b32_e32 v140, 16, v185
	v_fmac_f32_e32 v142, v138, v138
	v_and_b32_e32 v141, 0xffff0000, v185
	v_fmac_f32_e32 v142, v140, v140
	v_fmac_f32_e32 v142, v141, v141
	v_mov_b32_e32 v143, v142
	s_nop 1
	v_permlane16_swap_b32_e32 v143, v142
	v_add_f32_e32 v142, v142, v143
	s_nop 1
	v_mov_b32_dpp v143, v142 row_ror:8 row_mask:0xf bank_mask:0xf
	v_add_f32_e32 v142, v142, v143
	s_nop 1
	v_mov_b32_dpp v143, v142 row_ror:4 row_mask:0xf bank_mask:0xf
	v_add_f32_e32 v142, v142, v143
	s_nop 1
	v_mov_b32_dpp v143, v142 row_ror:2 row_mask:0xf bank_mask:0xf
	v_add_f32_e32 v142, v142, v143
	s_nop 1
	v_mov_b32_dpp v143, v142 row_ror:1 row_mask:0xf bank_mask:0xf
	v_add_f32_e32 v142, v142, v143
	v_add_u32_e32 v137, 0x1400, v133
	s_mov_b64 exec, s[10:11]
	global_store_dword v137, v142, s[8:9]
	s_mov_b64 exec, -1
	s_waitcnt vmcnt(42) lgkmcnt(4)
	v_lshlrev_b32_e32 v138, 16, v186
	v_and_b32_e32 v139, 0xffff0000, v186
	v_lshlrev_b32_e32 v140, 16, v187
	v_and_b32_e32 v141, 0xffff0000, v187
	v_pk_add_f32 v[78:79], v[78:79], v[138:139]
	v_pk_add_f32 v[80:81], v[80:81], v[140:141]
	v_cvt_pk_bf16_f32 v186, v78, v79
	v_cvt_pk_bf16_f32 v187, v80, v81
	v_add_u32_e32 v136, 0x58000, v132
	global_store_dwordx2 v136, v[186:187], s[6:7]
	v_and_b32_e32 v139, 0xffff0000, v186
	v_lshlrev_b32_e32 v138, 16, v186
	v_mul_f32_e32 v142, v139, v139
	v_lshlrev_b32_e32 v140, 16, v187
	v_fmac_f32_e32 v142, v138, v138
	v_and_b32_e32 v141, 0xffff0000, v187
	v_fmac_f32_e32 v142, v140, v140
	v_fmac_f32_e32 v142, v141, v141
	v_mov_b32_e32 v143, v142
	s_nop 1
	v_permlane16_swap_b32_e32 v143, v142
	v_add_f32_e32 v142, v142, v143
	s_nop 1
	v_mov_b32_dpp v143, v142 row_ror:8 row_mask:0xf bank_mask:0xf
	v_add_f32_e32 v142, v142, v143
	s_nop 1
	v_mov_b32_dpp v143, v142 row_ror:4 row_mask:0xf bank_mask:0xf
	v_add_f32_e32 v142, v142, v143
	s_nop 1
	v_mov_b32_dpp v143, v142 row_ror:2 row_mask:0xf bank_mask:0xf
	v_add_f32_e32 v142, v142, v143
	s_nop 1
	v_mov_b32_dpp v143, v142 row_ror:1 row_mask:0xf bank_mask:0xf
	v_add_f32_e32 v142, v142, v143
	v_add_u32_e32 v137, 0x1600, v133
	s_mov_b64 exec, s[10:11]
	global_store_dword v137, v142, s[8:9]
	s_mov_b64 exec, -1
	s_waitcnt vmcnt(43) lgkmcnt(3)
; DI unsigned pk2(float a, float b) { f32x2 v = {a, b}; bf2_t r = __builtin_convertvector(v, bf2_t); return __builtin_bit_cast(unsigned, r); }
; DI f32x4 unpk4(u32x2 u) { f32x4 r = {__uint_as_float(u[0] << 16), __uint_as_float(u[0] & 0xffff0000u), __uint_as_float(u[1] << 16), __uint_as_float(u[1] & 0xffff0000u)}; return r; }
; template <int MODE>
; DI void gemm_tile(const Params& p, const bf16_t* __restrict__ A, const bf16_t* __restrict__ Bt, int K, int brow, int bcol, int mp, int nt, bool vt, char* smem) {
;     ...
;       for (int m = 0; m < 4; ++m)
; #pragma unroll
;         for (int n = 0; n < 2; ++n) *(f32x4*)(st + (wc * 32 + n * 16 + fr) * 132 + wr * 64 + m * 16 + fq * 4) = acc[ai][bj][m][n];
;       __syncthreads();
;     ...
;           const int tok = m0 + bj * 128 + y, col = n0 + ai * 128 + x4;
;           const f32x4 xs = unpk4(xo[pq]) + v;
;           u32x2 o = {pk2(xs[0], xs[1]), pk2(xs[2], xs[3])};
;           *(u32x2*)((bf16_t*)(p.ws + OFF_XB) + (size_t)tok * DM + col) = o;
;           const f32x4 xn = unpk4(o);
;           float ss = xn[0] * xn[0] + xn[1] * xn[1] + xn[2] * xn[2] + xn[3] * xn[3];
; #pragma unroll
;           for (int o2 = 16; o2 > 0; o2 >>= 1) ss += __shfl_xor(ss, o2);
;           if ((tid & 31) == 0) ((float*)(p.ws + (MODE == MODE_OUT ? OFF_SSB : OFF_SSA)))[(size_t)tok * 8 + nt * 2 + ai] = ss;
	v_lshlrev_b32_e32 v138, 16, v188
	v_and_b32_e32 v139, 0xffff0000, v188
	v_lshlrev_b32_e32 v140, 16, v189
	v_and_b32_e32 v141, 0xffff0000, v189
	v_pk_add_f32 v[82:83], v[82:83], v[138:139]
	v_pk_add_f32 v[84:85], v[84:85], v[140:141]
	v_cvt_pk_bf16_f32 v188, v82, v83
	v_cvt_pk_bf16_f32 v189, v84, v85
	v_add_u32_e32 v136, 0x60000, v132
	global_store_dwordx2 v136, v[188:189], s[6:7]
	v_and_b32_e32 v139, 0xffff0000, v188
	v_lshlrev_b32_e32 v138, 16, v188
	v_mul_f32_e32 v142, v139, v139
	v_lshlrev_b32_e32 v140, 16, v189
	v_fmac_f32_e32 v142, v138, v138
	v_and_b32_e32 v141, 0xffff0000, v189
	v_fmac_f32_e32 v142, v140, v140
	v_fmac_f32_e32 v142, v141, v141
	v_mov_b32_e32 v143, v142
	s_nop 1
	v_permlane16_swap_b32_e32 v143, v142
	v_add_f32_e32 v142, v142, v143
	s_nop 1
	v_mov_b32_dpp v143, v142 row_ror:8 row_mask:0xf bank_mask:0xf
	v_add_f32_e32 v142, v142, v143
	s_nop 1
	v_mov_b32_dpp v143, v142 row_ror:4 row_mask:0xf bank_mask:0xf
	v_add_f32_e32 v142, v142, v143
	s_nop 1
	v_mov_b32_dpp v143, v142 row_ror:2 row_mask:0xf bank_mask:0xf
	v_add_f32_e32 v142, v142, v143
	s_nop 1
	v_mov_b32_dpp v143, v142 row_ror:1 row_mask:0xf bank_mask:0xf
	v_add_f32_e32 v142, v142, v143
	v_add_u32_e32 v137, 0x1800, v133
	s_mov_b64 exec, s[10:11]
	global_store_dword v137, v142, s[8:9]
	s_mov_b64 exec, -1
	s_waitcnt vmcnt(44) lgkmcnt(2)
	v_lshlrev_b32_e32 v138, 16, v190
	v_and_b32_e32 v139, 0xffff0000, v190
	v_lshlrev_b32_e32 v140, 16, v191
	v_and_b32_e32 v141, 0xffff0000, v191
	v_pk_add_f32 v[86:87], v[86:87], v[138:139]
	v_pk_add_f32 v[88:89], v[88:89], v[140:141]
	v_cvt_pk_bf16_f32 v190, v86, v87
	v_cvt_pk_bf16_f32 v191, v88, v89
	v_add_u32_e32 v136, 0x68000, v132
	global_store_dwordx2 v136, v[190:191], s[6:7]
	v_and_b32_e32 v139, 0xffff0000, v190
	v_lshlrev_b32_e32 v138, 16, v190
	v_mul_f32_e32 v142, v139, v139
	v_lshlrev_b32_e32 v140, 16, v191
	v_fmac_f32_e32 v142, v138, v138
	v_and_b32_e32 v141, 0xffff0000, v191
	v_fmac_f32_e32 v142, v140, v140
	v_fmac_f32_e32 v142, v141, v141
	v_mov_b32_e32 v143, v142
	s_nop 1
	v_permlane16_swap_b32_e32 v143, v142
	v_add_f32_e32 v142, v142, v143
	s_nop 1
	v_mov_b32_dpp v143, v142 row_ror:8 row_mask:0xf bank_mask:0xf
	v_add_f32_e32 v142, v142, v143
	s_nop 1
	v_mov_b32_dpp v143, v142 row_ror:4 row_mask:0xf bank_mask:0xf
	v_add_f32_e32 v142, v142, v143
	s_nop 1
	v_mov_b32_dpp v143, v142 row_ror:2 row_mask:0xf bank_mask:0xf
	v_add_f32_e32 v142, v142, v143
	s_nop 1
	v_mov_b32_dpp v143, v142 row_ror:1 row_mask:0xf bank_mask:0xf
	v_add_f32_e32 v142, v142, v143
	v_add_u32_e32 v137, 0x1a00, v133
	s_mov_b64 exec, s[10:11]
	global_store_dword v137, v142, s[8:9]
	s_mov_b64 exec, -1
	s_waitcnt vmcnt(45) lgkmcnt(1)
	v_lshlrev_b32_e32 v138, 16, v192
	v_and_b32_e32 v139, 0xffff0000, v192
	v_lshlrev_b32_e32 v140, 16, v193
	v_and_b32_e32 v141, 0xffff0000, v193
	v_pk_add_f32 v[90:91], v[90:91], v[138:139]
	v_pk_add_f32 v[92:93], v[92:93], v[140:141]
	v_cvt_pk_bf16_f32 v192, v90, v91
	v_cvt_pk_bf16_f32 v193, v92, v93
	v_add_u32_e32 v136, 0x70000, v132
	global_store_dwordx2 v136, v[192:193], s[6:7]
	v_and_b32_e32 v139, 0xffff0000, v192
	v_lshlrev_b32_e32 v138, 16, v192
	v_mul_f32_e32 v142, v139, v139
	v_lshlrev_b32_e32 v140, 16, v193
	v_fmac_f32_e32 v142, v138, v138
	v_and_b32_e32 v141, 0xffff0000, v193
	v_fmac_f32_e32 v142, v140, v140
	v_fmac_f32_e32 v142, v141, v141
	v_mov_b32_e32 v143, v142
	s_nop 1
	v_permlane16_swap_b32_e32 v143, v142
	v_add_f32_e32 v142, v142, v143
	s_nop 1
	v_mov_b32_dpp v143, v142 row_ror:8 row_mask:0xf bank_mask:0xf
	v_add_f32_e32 v142, v142, v143
	s_nop 1
	v_mov_b32_dpp v143, v142 row_ror:4 row_mask:0xf bank_mask:0xf
	v_add_f32_e32 v142, v142, v143
	s_nop 1
	v_mov_b32_dpp v143, v142 row_ror:2 row_mask:0xf bank_mask:0xf
	v_add_f32_e32 v142, v142, v143
	s_nop 1
	v_mov_b32_dpp v143, v142 row_ror:1 row_mask:0xf bank_mask:0xf
	v_add_f32_e32 v142, v142, v143
	v_add_u32_e32 v137, 0x1c00, v133
	s_mov_b64 exec, s[10:11]
	global_store_dword v137, v142, s[8:9]
	s_mov_b64 exec, -1
	s_waitcnt vmcnt(46) lgkmcnt(0)
	v_lshlrev_b32_e32 v138, 16, v194
	v_and_b32_e32 v139, 0xffff0000, v194
	v_lshlrev_b32_e32 v140, 16, v195
	v_and_b32_e32 v141, 0xffff0000, v195
	v_pk_add_f32 v[94:95], v[94:95], v[138:139]
	v_pk_add_f32 v[96:97], v[96:97], v[140:141]
	v_cvt_pk_bf16_f32 v194, v94, v95
	v_cvt_pk_bf16_f32 v195, v96, v97
	v_add_u32_e32 v136, 0x78000, v132
	global_store_dwordx2 v136, v[194:195], s[6:7]
	v_and_b32_e32 v139, 0xffff0000, v194
	v_lshlrev_b32_e32 v138, 16, v194
	v_mul_f32_e32 v142, v139, v139
	v_lshlrev_b32_e32 v140, 16, v195
	v_fmac_f32_e32 v142, v138, v138
	v_and_b32_e32 v141, 0xffff0000, v195
	v_fmac_f32_e32 v142, v140, v140
	v_fmac_f32_e32 v142, v141, v141
	v_mov_b32_e32 v143, v142
	s_nop 1
	v_permlane16_swap_b32_e32 v143, v142
	v_add_f32_e32 v142, v142, v143
	s_nop 1
	v_mov_b32_dpp v143, v142 row_ror:8 row_mask:0xf bank_mask:0xf
	v_add_f32_e32 v142, v142, v143
	s_nop 1
	v_mov_b32_dpp v143, v142 row_ror:4 row_mask:0xf bank_mask:0xf
	v_add_f32_e32 v142, v142, v143
	s_nop 1
	v_mov_b32_dpp v143, v142 row_ror:2 row_mask:0xf bank_mask:0xf
	v_add_f32_e32 v142, v142, v143
	s_nop 1
	v_mov_b32_dpp v143, v142 row_ror:1 row_mask:0xf bank_mask:0xf
	v_add_f32_e32 v142, v142, v143
	v_add_u32_e32 v137, 0x1e00, v133
	s_mov_b64 exec, s[10:11]
	global_store_dword v137, v142, s[8:9]
	s_mov_b64 exec, -1
	s_barrier
	ds_write_b128 v134, v[34:37]
	ds_write_b128 v134, v[38:41] offset:8448
	ds_write_b128 v134, v[42:45] offset:64
	ds_write_b128 v134, v[46:49] offset:8512
	ds_write_b128 v134, v[50:53] offset:128
	ds_write_b128 v134, v[54:57] offset:8576
	ds_write_b128 v134, v[58:61] offset:192
	ds_write_b128 v134, v[62:65] offset:8640
	s_waitcnt lgkmcnt(0)
	s_barrier
; DI unsigned pk2(float a, float b) { f32x2 v = {a, b}; bf2_t r = __builtin_convertvector(v, bf2_t); return __builtin_bit_cast(unsigned, r); }
; DI f32x4 unpk4(u32x2 u) { f32x4 r = {__uint_as_float(u[0] << 16), __uint_as_float(u[0] & 0xffff0000u), __uint_as_float(u[1] << 16), __uint_as_float(u[1] & 0xffff0000u)}; return r; }
; template <int MODE>
; DI void gemm_tile(const Params& p, const bf16_t* __restrict__ A, const bf16_t* __restrict__ Bt, int K, int brow, int bcol, int mp, int nt, bool vt, char* smem) {
;     ...
;         const f32x4 v = *(const f32x4*)(st + y * 132 + x4);
;     ...
;           const int tok = m0 + bj * 128 + y, col = n0 + ai * 128 + x4;
;           const f32x4 xs = unpk4(xo[pq]) + v;
;           u32x2 o = {pk2(xs[0], xs[1]), pk2(xs[2], xs[3])};
;           *(u32x2*)((bf16_t*)(p.ws + OFF_XB) + (size_t)tok * DM + col) = o;
;           const f32x4 xn = unpk4(o);
;           float ss = xn[0] * xn[0] + xn[1] * xn[1] + xn[2] * xn[2] + xn[3] * xn[3];
; #pragma unroll
;           for (int o2 = 16; o2 > 0; o2 >>= 1) ss += __shfl_xor(ss, o2);
;           if ((tid & 31) == 0) ((float*)(p.ws + (MODE == MODE_OUT ? OFF_SSB : OFF_SSA)))[(size_t)tok * 8 + nt * 2 + ai] = ss;
	ds_read_b128 v[34:37], v135
	ds_read_b128 v[38:41], v135 offset:8448
	ds_read_b128 v[42:45], v135 offset:16896
	ds_read_b128 v[46:49], v135 offset:25344
	ds_read_b128 v[50:53], v135 offset:33792
	ds_read_b128 v[54:57], v135 offset:42240
	ds_read_b128 v[58:61], v135 offset:50688
	ds_read_b128 v[62:65], v135 offset:59136
	s_waitcnt vmcnt(47) lgkmcnt(7)
	v_lshlrev_b32_e32 v138, 16, v196
	v_and_b32_e32 v139, 0xffff0000, v196
	v_lshlrev_b32_e32 v140, 16, v197
	v_and_b32_e32 v141, 0xffff0000, v197
	v_pk_add_f32 v[34:35], v[34:35], v[138:139]
	v_pk_add_f32 v[36:37], v[36:37], v[140:141]
	v_cvt_pk_bf16_f32 v196, v34, v35
	v_cvt_pk_bf16_f32 v197, v36, v37
	global_store_dwordx2 v132, v[196:197], s[6:7] offset:256
	v_and_b32_e32 v139, 0xffff0000, v196
	v_lshlrev_b32_e32 v138, 16, v196
	v_mul_f32_e32 v142, v139, v139
	v_lshlrev_b32_e32 v140, 16, v197
	v_fmac_f32_e32 v142, v138, v138
	v_and_b32_e32 v141, 0xffff0000, v197
	v_fmac_f32_e32 v142, v140, v140
	v_fmac_f32_e32 v142, v141, v141
	v_mov_b32_e32 v143, v142
	s_nop 1
	v_permlane16_swap_b32_e32 v143, v142
	v_add_f32_e32 v142, v142, v143
	s_nop 1
	v_mov_b32_dpp v143, v142 row_ror:8 row_mask:0xf bank_mask:0xf
	v_add_f32_e32 v142, v142, v143
	s_nop 1
	v_mov_b32_dpp v143, v142 row_ror:4 row_mask:0xf bank_mask:0xf
	v_add_f32_e32 v142, v142, v143
	s_nop 1
	v_mov_b32_dpp v143, v142 row_ror:2 row_mask:0xf bank_mask:0xf
	v_add_f32_e32 v142, v142, v143
	s_nop 1
	v_mov_b32_dpp v143, v142 row_ror:1 row_mask:0xf bank_mask:0xf
	v_add_f32_e32 v142, v142, v143
	s_mov_b64 exec, s[10:11]
	global_store_dword v133, v142, s[8:9] offset:4
	s_mov_b64 exec, -1
	s_waitcnt vmcnt(48) lgkmcnt(6)
	v_lshlrev_b32_e32 v138, 16, v198
	v_and_b32_e32 v139, 0xffff0000, v198
	v_lshlrev_b32_e32 v140, 16, v199
	v_and_b32_e32 v141, 0xffff0000, v199
	v_pk_add_f32 v[38:39], v[38:39], v[138:139]
	v_pk_add_f32 v[40:41], v[40:41], v[140:141]
	v_cvt_pk_bf16_f32 v198, v38, v39
	v_cvt_pk_bf16_f32 v199, v40, v41
	v_add_u32_e32 v136, 0x8000, v132
	global_store_dwordx2 v136, v[198:199], s[6:7] offset:256
	v_and_b32_e32 v139, 0xffff0000, v198
	v_lshlrev_b32_e32 v138, 16, v198
	v_mul_f32_e32 v142, v139, v139
	v_lshlrev_b32_e32 v140, 16, v199
	v_fmac_f32_e32 v142, v138, v138
	v_and_b32_e32 v141, 0xffff0000, v199
	v_fmac_f32_e32 v142, v140, v140
	v_fmac_f32_e32 v142, v141, v141
	v_mov_b32_e32 v143, v142
	s_nop 1
	v_permlane16_swap_b32_e32 v143, v142
	v_add_f32_e32 v142, v142, v143
	s_nop 1
	v_mov_b32_dpp v143, v142 row_ror:8 row_mask:0xf bank_mask:0xf
	v_add_f32_e32 v142, v142, v143
	s_nop 1
	v_mov_b32_dpp v143, v142 row_ror:4 row_mask:0xf bank_mask:0xf
	v_add_f32_e32 v142, v142, v143
	s_nop 1
	v_mov_b32_dpp v143, v142 row_ror:2 row_mask:0xf bank_mask:0xf
	v_add_f32_e32 v142, v142, v143
	s_nop 1
	v_mov_b32_dpp v143, v142 row_ror:1 row_mask:0xf bank_mask:0xf
	v_add_f32_e32 v142, v142, v143
	v_add_u32_e32 v137, 0x200, v133
	s_mov_b64 exec, s[10:11]
	global_store_dword v137, v142, s[8:9] offset:4
	s_mov_b64 exec, -1
	s_waitcnt vmcnt(49) lgkmcnt(5)
	v_lshlrev_b32_e32 v138, 16, v214
	v_and_b32_e32 v139, 0xffff0000, v214
	v_lshlrev_b32_e32 v140, 16, v215
	v_and_b32_e32 v141, 0xffff0000, v215
	v_pk_add_f32 v[42:43], v[42:43], v[138:139]
	v_pk_add_f32 v[44:45], v[44:45], v[140:141]
	v_cvt_pk_bf16_f32 v214, v42, v43
	v_cvt_pk_bf16_f32 v215, v44, v45
	v_add_u32_e32 v136, 0x10000, v132
	global_store_dwordx2 v136, v[214:215], s[6:7] offset:256
	v_and_b32_e32 v139, 0xffff0000, v214
	v_lshlrev_b32_e32 v138, 16, v214
	v_mul_f32_e32 v142, v139, v139
	v_lshlrev_b32_e32 v140, 16, v215
	v_fmac_f32_e32 v142, v138, v138
	v_and_b32_e32 v141, 0xffff0000, v215
	v_fmac_f32_e32 v142, v140, v140
	v_fmac_f32_e32 v142, v141, v141
	v_mov_b32_e32 v143, v142
	s_nop 1
	v_permlane16_swap_b32_e32 v143, v142
	v_add_f32_e32 v142, v142, v143
	s_nop 1
	v_mov_b32_dpp v143, v142 row_ror:8 row_mask:0xf bank_mask:0xf
	v_add_f32_e32 v142, v142, v143
	s_nop 1
	v_mov_b32_dpp v143, v142 row_ror:4 row_mask:0xf bank_mask:0xf
	v_add_f32_e32 v142, v142, v143
	s_nop 1
	v_mov_b32_dpp v143, v142 row_ror:2 row_mask:0xf bank_mask:0xf
	v_add_f32_e32 v142, v142, v143
	s_nop 1
	v_mov_b32_dpp v143, v142 row_ror:1 row_mask:0xf bank_mask:0xf
	v_add_f32_e32 v142, v142, v143
	v_add_u32_e32 v137, 0x400, v133
	s_mov_b64 exec, s[10:11]
	global_store_dword v137, v142, s[8:9] offset:4
	s_mov_b64 exec, -1
	s_waitcnt vmcnt(50) lgkmcnt(4)
	v_lshlrev_b32_e32 v138, 16, v216
	v_and_b32_e32 v139, 0xffff0000, v216
	v_lshlrev_b32_e32 v140, 16, v217
	v_and_b32_e32 v141, 0xffff0000, v217
	v_pk_add_f32 v[46:47], v[46:47], v[138:139]
	v_pk_add_f32 v[48:49], v[48:49], v[140:141]
	v_cvt_pk_bf16_f32 v216, v46, v47
	v_cvt_pk_bf16_f32 v217, v48, v49
	v_add_u32_e32 v136, 0x18000, v132
	global_store_dwordx2 v136, v[216:217], s[6:7] offset:256
	v_and_b32_e32 v139, 0xffff0000, v216
	v_lshlrev_b32_e32 v138, 16, v216
	v_mul_f32_e32 v142, v139, v139
	v_lshlrev_b32_e32 v140, 16, v217
	v_fmac_f32_e32 v142, v138, v138
	v_and_b32_e32 v141, 0xffff0000, v217
	v_fmac_f32_e32 v142, v140, v140
	v_fmac_f32_e32 v142, v141, v141
	v_mov_b32_e32 v143, v142
	s_nop 1
	v_permlane16_swap_b32_e32 v143, v142
	v_add_f32_e32 v142, v142, v143
	s_nop 1
	v_mov_b32_dpp v143, v142 row_ror:8 row_mask:0xf bank_mask:0xf
	v_add_f32_e32 v142, v142, v143
	s_nop 1
	v_mov_b32_dpp v143, v142 row_ror:4 row_mask:0xf bank_mask:0xf
	v_add_f32_e32 v142, v142, v143
	s_nop 1
	v_mov_b32_dpp v143, v142 row_ror:2 row_mask:0xf bank_mask:0xf
	v_add_f32_e32 v142, v142, v143
	s_nop 1
	v_mov_b32_dpp v143, v142 row_ror:1 row_mask:0xf bank_mask:0xf
	v_add_f32_e32 v142, v142, v143
	v_add_u32_e32 v137, 0x600, v133
	s_mov_b64 exec, s[10:11]
	global_store_dword v137, v142, s[8:9] offset:4
	s_mov_b64 exec, -1
	s_waitcnt vmcnt(51) lgkmcnt(3)
; DI unsigned pk2(float a, float b) { f32x2 v = {a, b}; bf2_t r = __builtin_convertvector(v, bf2_t); return __builtin_bit_cast(unsigned, r); }
; DI f32x4 unpk4(u32x2 u) { f32x4 r = {__uint_as_float(u[0] << 16), __uint_as_float(u[0] & 0xffff0000u), __uint_as_float(u[1] << 16), __uint_as_float(u[1] & 0xffff0000u)}; return r; }
; template <int MODE>
; DI void gemm_tile(const Params& p, const bf16_t* __restrict__ A, const bf16_t* __restrict__ Bt, int K, int brow, int bcol, int mp, int nt, bool vt, char* smem) {
;     ...
;       for (int m = 0; m < 4; ++m)
; #pragma unroll
;         for (int n = 0; n < 2; ++n) *(f32x4*)(st + (wc * 32 + n * 16 + fr) * 132 + wr * 64 + m * 16 + fq * 4) = acc[ai][bj][m][n];
;       __syncthreads();
;     ...
;           const int tok = m0 + bj * 128 + y, col = n0 + ai * 128 + x4;
;           const f32x4 xs = unpk4(xo[pq]) + v;
;           u32x2 o = {pk2(xs[0], xs[1]), pk2(xs[2], xs[3])};
;           *(u32x2*)((bf16_t*)(p.ws + OFF_XB) + (size_t)tok * DM + col) = o;
;           const f32x4 xn = unpk4(o);
;           float ss = xn[0] * xn[0] + xn[1] * xn[1] + xn[2] * xn[2] + xn[3] * xn[3];
; #pragma unroll
;           for (int o2 = 16; o2 > 0; o2 >>= 1) ss += __shfl_xor(ss, o2);
;           if ((tid & 31) == 0) ((float*)(p.ws + (MODE == MODE_OUT ? OFF_SSB : OFF_SSA)))[(size_t)tok * 8 + nt * 2 + ai] = ss;
	v_lshlrev_b32_e32 v138, 16, v218
	v_and_b32_e32 v139, 0xffff0000, v218
	v_lshlrev_b32_e32 v140, 16, v219
	v_and_b32_e32 v141, 0xffff0000, v219
	v_pk_add_f32 v[50:51], v[50:51], v[138:139]
	v_pk_add_f32 v[52:53], v[52:53], v[140:141]
	v_cvt_pk_bf16_f32 v218, v50, v51
	v_cvt_pk_bf16_f32 v219, v52, v53
	v_add_u32_e32 v136, 0x20000, v132
	global_store_dwordx2 v136, v[218:219], s[6:7] offset:256
	v_and_b32_e32 v139, 0xffff0000, v218
	v_lshlrev_b32_e32 v138, 16, v218
	v_mul_f32_e32 v142, v139, v139
	v_lshlrev_b32_e32 v140, 16, v219
	v_fmac_f32_e32 v142, v138, v138
	v_and_b32_e32 v141, 0xffff0000, v219
	v_fmac_f32_e32 v142, v140, v140
	v_fmac_f32_e32 v142, v141, v141
	v_mov_b32_e32 v143, v142
	s_nop 1
	v_permlane16_swap_b32_e32 v143, v142
	v_add_f32_e32 v142, v142, v143
	s_nop 1
	v_mov_b32_dpp v143, v142 row_ror:8 row_mask:0xf bank_mask:0xf
	v_add_f32_e32 v142, v142, v143
	s_nop 1
	v_mov_b32_dpp v143, v142 row_ror:4 row_mask:0xf bank_mask:0xf
	v_add_f32_e32 v142, v142, v143
	s_nop 1
	v_mov_b32_dpp v143, v142 row_ror:2 row_mask:0xf bank_mask:0xf
	v_add_f32_e32 v142, v142, v143
	s_nop 1
	v_mov_b32_dpp v143, v142 row_ror:1 row_mask:0xf bank_mask:0xf
	v_add_f32_e32 v142, v142, v143
	v_add_u32_e32 v137, 0x800, v133
	s_mov_b64 exec, s[10:11]
	global_store_dword v137, v142, s[8:9] offset:4
	s_mov_b64 exec, -1
	s_waitcnt vmcnt(52) lgkmcnt(2)
	v_lshlrev_b32_e32 v138, 16, v220
	v_and_b32_e32 v139, 0xffff0000, v220
	v_lshlrev_b32_e32 v140, 16, v221
	v_and_b32_e32 v141, 0xffff0000, v221
	v_pk_add_f32 v[54:55], v[54:55], v[138:139]
	v_pk_add_f32 v[56:57], v[56:57], v[140:141]
	v_cvt_pk_bf16_f32 v220, v54, v55
	v_cvt_pk_bf16_f32 v221, v56, v57
	v_add_u32_e32 v136, 0x28000, v132
	global_store_dwordx2 v136, v[220:221], s[6:7] offset:256
	v_and_b32_e32 v139, 0xffff0000, v220
	v_lshlrev_b32_e32 v138, 16, v220
	v_mul_f32_e32 v142, v139, v139
	v_lshlrev_b32_e32 v140, 16, v221
	v_fmac_f32_e32 v142, v138, v138
	v_and_b32_e32 v141, 0xffff0000, v221
	v_fmac_f32_e32 v142, v140, v140
	v_fmac_f32_e32 v142, v141, v141
	v_mov_b32_e32 v143, v142
	s_nop 1
	v_permlane16_swap_b32_e32 v143, v142
	v_add_f32_e32 v142, v142, v143
	s_nop 1
	v_mov_b32_dpp v143, v142 row_ror:8 row_mask:0xf bank_mask:0xf
	v_add_f32_e32 v142, v142, v143
	s_nop 1
	v_mov_b32_dpp v143, v142 row_ror:4 row_mask:0xf bank_mask:0xf
	v_add_f32_e32 v142, v142, v143
	s_nop 1
	v_mov_b32_dpp v143, v142 row_ror:2 row_mask:0xf bank_mask:0xf
	v_add_f32_e32 v142, v142, v143
	s_nop 1
	v_mov_b32_dpp v143, v142 row_ror:1 row_mask:0xf bank_mask:0xf
	v_add_f32_e32 v142, v142, v143
	v_add_u32_e32 v137, 0xa00, v133
	s_mov_b64 exec, s[10:11]
	global_store_dword v137, v142, s[8:9] offset:4
	s_mov_b64 exec, -1
	s_waitcnt vmcnt(53) lgkmcnt(1)
	v_lshlrev_b32_e32 v138, 16, v222
	v_and_b32_e32 v139, 0xffff0000, v222
	v_lshlrev_b32_e32 v140, 16, v223
	v_and_b32_e32 v141, 0xffff0000, v223
	v_pk_add_f32 v[58:59], v[58:59], v[138:139]
	v_pk_add_f32 v[60:61], v[60:61], v[140:141]
	v_cvt_pk_bf16_f32 v222, v58, v59
	v_cvt_pk_bf16_f32 v223, v60, v61
	v_add_u32_e32 v136, 0x30000, v132
	global_store_dwordx2 v136, v[222:223], s[6:7] offset:256
	v_and_b32_e32 v139, 0xffff0000, v222
	v_lshlrev_b32_e32 v138, 16, v222
	v_mul_f32_e32 v142, v139, v139
	v_lshlrev_b32_e32 v140, 16, v223
	v_fmac_f32_e32 v142, v138, v138
	v_and_b32_e32 v141, 0xffff0000, v223
	v_fmac_f32_e32 v142, v140, v140
	v_fmac_f32_e32 v142, v141, v141
	v_mov_b32_e32 v143, v142
	s_nop 1
	v_permlane16_swap_b32_e32 v143, v142
	v_add_f32_e32 v142, v142, v143
	s_nop 1
	v_mov_b32_dpp v143, v142 row_ror:8 row_mask:0xf bank_mask:0xf
	v_add_f32_e32 v142, v142, v143
	s_nop 1
	v_mov_b32_dpp v143, v142 row_ror:4 row_mask:0xf bank_mask:0xf
	v_add_f32_e32 v142, v142, v143
	s_nop 1
	v_mov_b32_dpp v143, v142 row_ror:2 row_mask:0xf bank_mask:0xf
	v_add_f32_e32 v142, v142, v143
	s_nop 1
	v_mov_b32_dpp v143, v142 row_ror:1 row_mask:0xf bank_mask:0xf
	v_add_f32_e32 v142, v142, v143
	v_add_u32_e32 v137, 0xc00, v133
	s_mov_b64 exec, s[10:11]
	global_store_dword v137, v142, s[8:9] offset:4
	s_mov_b64 exec, -1
	s_waitcnt vmcnt(54) lgkmcnt(0)
	v_lshlrev_b32_e32 v138, 16, v224
	v_and_b32_e32 v139, 0xffff0000, v224
	v_lshlrev_b32_e32 v140, 16, v225
	v_and_b32_e32 v141, 0xffff0000, v225
	v_pk_add_f32 v[62:63], v[62:63], v[138:139]
	v_pk_add_f32 v[64:65], v[64:65], v[140:141]
	v_cvt_pk_bf16_f32 v224, v62, v63
	v_cvt_pk_bf16_f32 v225, v64, v65
	v_add_u32_e32 v136, 0x38000, v132
	global_store_dwordx2 v136, v[224:225], s[6:7] offset:256
	v_and_b32_e32 v139, 0xffff0000, v224
	v_lshlrev_b32_e32 v138, 16, v224
	v_mul_f32_e32 v142, v139, v139
	v_lshlrev_b32_e32 v140, 16, v225
	v_fmac_f32_e32 v142, v138, v138
	v_and_b32_e32 v141, 0xffff0000, v225
	v_fmac_f32_e32 v142, v140, v140
	v_fmac_f32_e32 v142, v141, v141
	v_mov_b32_e32 v143, v142
	s_nop 1
	v_permlane16_swap_b32_e32 v143, v142
	v_add_f32_e32 v142, v142, v143
	s_nop 1
	v_mov_b32_dpp v143, v142 row_ror:8 row_mask:0xf bank_mask:0xf
	v_add_f32_e32 v142, v142, v143
	s_nop 1
	v_mov_b32_dpp v143, v142 row_ror:4 row_mask:0xf bank_mask:0xf
	v_add_f32_e32 v142, v142, v143
	s_nop 1
	v_mov_b32_dpp v143, v142 row_ror:2 row_mask:0xf bank_mask:0xf
	v_add_f32_e32 v142, v142, v143
	s_nop 1
	v_mov_b32_dpp v143, v142 row_ror:1 row_mask:0xf bank_mask:0xf
	v_add_f32_e32 v142, v142, v143
	v_add_u32_e32 v137, 0xe00, v133
	s_mov_b64 exec, s[10:11]
	global_store_dword v137, v142, s[8:9] offset:4
	s_mov_b64 exec, -1
	s_barrier
	ds_write_b128 v134, v[2:5]
	ds_write_b128 v134, v[6:9] offset:8448
	ds_write_b128 v134, v[10:13] offset:64
	ds_write_b128 v134, v[14:17] offset:8512
	ds_write_b128 v134, v[18:21] offset:128
	ds_write_b128 v134, v[22:25] offset:8576
	ds_write_b128 v134, v[26:29] offset:192
	ds_write_b128 v134, v[30:33] offset:8640
	s_waitcnt lgkmcnt(0)
	s_barrier
; DI unsigned pk2(float a, float b) { f32x2 v = {a, b}; bf2_t r = __builtin_convertvector(v, bf2_t); return __builtin_bit_cast(unsigned, r); }
; DI f32x4 unpk4(u32x2 u) { f32x4 r = {__uint_as_float(u[0] << 16), __uint_as_float(u[0] & 0xffff0000u), __uint_as_float(u[1] << 16), __uint_as_float(u[1] & 0xffff0000u)}; return r; }
; template <int MODE>
; DI void gemm_tile(const Params& p, const bf16_t* __restrict__ A, const bf16_t* __restrict__ Bt, int K, int brow, int bcol, int mp, int nt, bool vt, char* smem) {
;     ...
;         const f32x4 v = *(const f32x4*)(st + y * 132 + x4);
;     ...
;           const int tok = m0 + bj * 128 + y, col = n0 + ai * 128 + x4;
;           const f32x4 xs = unpk4(xo[pq]) + v;
;           u32x2 o = {pk2(xs[0], xs[1]), pk2(xs[2], xs[3])};
;           *(u32x2*)((bf16_t*)(p.ws + OFF_XB) + (size_t)tok * DM + col) = o;
;           const f32x4 xn = unpk4(o);
;           float ss = xn[0] * xn[0] + xn[1] * xn[1] + xn[2] * xn[2] + xn[3] * xn[3];
; #pragma unroll
;           for (int o2 = 16; o2 > 0; o2 >>= 1) ss += __shfl_xor(ss, o2);
;           if ((tid & 31) == 0) ((float*)(p.ws + (MODE == MODE_OUT ? OFF_SSB : OFF_SSA)))[(size_t)tok * 8 + nt * 2 + ai] = ss;
	ds_read_b128 v[2:5], v135
	ds_read_b128 v[6:9], v135 offset:8448
	ds_read_b128 v[10:13], v135 offset:16896
	ds_read_b128 v[14:17], v135 offset:25344
	ds_read_b128 v[18:21], v135 offset:33792
	ds_read_b128 v[22:25], v135 offset:42240
	ds_read_b128 v[26:29], v135 offset:50688
	ds_read_b128 v[30:33], v135 offset:59136
	s_waitcnt vmcnt(55) lgkmcnt(7)
	v_lshlrev_b32_e32 v138, 16, v226
	v_and_b32_e32 v139, 0xffff0000, v226
	v_lshlrev_b32_e32 v140, 16, v227
	v_and_b32_e32 v141, 0xffff0000, v227
	v_pk_add_f32 v[2:3], v[2:3], v[138:139]
	v_pk_add_f32 v[4:5], v[4:5], v[140:141]
	v_cvt_pk_bf16_f32 v226, v2, v3
	v_cvt_pk_bf16_f32 v227, v4, v5
	v_add_u32_e32 v136, 0x40000, v132
	global_store_dwordx2 v136, v[226:227], s[6:7] offset:256
	v_and_b32_e32 v139, 0xffff0000, v226
	v_lshlrev_b32_e32 v138, 16, v226
	v_mul_f32_e32 v142, v139, v139
	v_lshlrev_b32_e32 v140, 16, v227
	v_fmac_f32_e32 v142, v138, v138
	v_and_b32_e32 v141, 0xffff0000, v227
	v_fmac_f32_e32 v142, v140, v140
	v_fmac_f32_e32 v142, v141, v141
	v_mov_b32_e32 v143, v142
	s_nop 1
	v_permlane16_swap_b32_e32 v143, v142
	v_add_f32_e32 v142, v142, v143
	s_nop 1
	v_mov_b32_dpp v143, v142 row_ror:8 row_mask:0xf bank_mask:0xf
	v_add_f32_e32 v142, v142, v143
	s_nop 1
	v_mov_b32_dpp v143, v142 row_ror:4 row_mask:0xf bank_mask:0xf
	v_add_f32_e32 v142, v142, v143
	s_nop 1
	v_mov_b32_dpp v143, v142 row_ror:2 row_mask:0xf bank_mask:0xf
	v_add_f32_e32 v142, v142, v143
	s_nop 1
	v_mov_b32_dpp v143, v142 row_ror:1 row_mask:0xf bank_mask:0xf
	v_add_f32_e32 v142, v142, v143
	v_add_u32_e32 v137, 0x1000, v133
	s_mov_b64 exec, s[10:11]
	global_store_dword v137, v142, s[8:9] offset:4
	s_mov_b64 exec, -1
	s_waitcnt vmcnt(56) lgkmcnt(6)
	v_lshlrev_b32_e32 v138, 16, v228
	v_and_b32_e32 v139, 0xffff0000, v228
	v_lshlrev_b32_e32 v140, 16, v229
	v_and_b32_e32 v141, 0xffff0000, v229
	v_pk_add_f32 v[6:7], v[6:7], v[138:139]
	v_pk_add_f32 v[8:9], v[8:9], v[140:141]
	v_cvt_pk_bf16_f32 v228, v6, v7
	v_cvt_pk_bf16_f32 v229, v8, v9
	v_add_u32_e32 v136, 0x48000, v132
	global_store_dwordx2 v136, v[228:229], s[6:7] offset:256
	v_and_b32_e32 v139, 0xffff0000, v228
	v_lshlrev_b32_e32 v138, 16, v228
	v_mul_f32_e32 v142, v139, v139
	v_lshlrev_b32_e32 v140, 16, v229
	v_fmac_f32_e32 v142, v138, v138
	v_and_b32_e32 v141, 0xffff0000, v229
	v_fmac_f32_e32 v142, v140, v140
	v_fmac_f32_e32 v142, v141, v141
	v_mov_b32_e32 v143, v142
	s_nop 1
	v_permlane16_swap_b32_e32 v143, v142
	v_add_f32_e32 v142, v142, v143
	s_nop 1
	v_mov_b32_dpp v143, v142 row_ror:8 row_mask:0xf bank_mask:0xf
	v_add_f32_e32 v142, v142, v143
	s_nop 1
	v_mov_b32_dpp v143, v142 row_ror:4 row_mask:0xf bank_mask:0xf
	v_add_f32_e32 v142, v142, v143
	s_nop 1
	v_mov_b32_dpp v143, v142 row_ror:2 row_mask:0xf bank_mask:0xf
	v_add_f32_e32 v142, v142, v143
	s_nop 1
	v_mov_b32_dpp v143, v142 row_ror:1 row_mask:0xf bank_mask:0xf
	v_add_f32_e32 v142, v142, v143
	v_add_u32_e32 v137, 0x1200, v133
	s_mov_b64 exec, s[10:11]
	global_store_dword v137, v142, s[8:9] offset:4
	s_mov_b64 exec, -1
	s_waitcnt vmcnt(57) lgkmcnt(5)
	v_lshlrev_b32_e32 v138, 16, v230
	v_and_b32_e32 v139, 0xffff0000, v230
	v_lshlrev_b32_e32 v140, 16, v231
	v_and_b32_e32 v141, 0xffff0000, v231
	v_pk_add_f32 v[10:11], v[10:11], v[138:139]
	v_pk_add_f32 v[12:13], v[12:13], v[140:141]
	v_cvt_pk_bf16_f32 v230, v10, v11
	v_cvt_pk_bf16_f32 v231, v12, v13
	v_add_u32_e32 v136, 0x50000, v132
	global_store_dwordx2 v136, v[230:231], s[6:7] offset:256
	v_and_b32_e32 v139, 0xffff0000, v230
	v_lshlrev_b32_e32 v138, 16, v230
	v_mul_f32_e32 v142, v139, v139
	v_lshlrev_b32_e32 v140, 16, v231
	v_fmac_f32_e32 v142, v138, v138
	v_and_b32_e32 v141, 0xffff0000, v231
	v_fmac_f32_e32 v142, v140, v140
	v_fmac_f32_e32 v142, v141, v141
	v_mov_b32_e32 v143, v142
	s_nop 1
	v_permlane16_swap_b32_e32 v143, v142
	v_add_f32_e32 v142, v142, v143
	s_nop 1
	v_mov_b32_dpp v143, v142 row_ror:8 row_mask:0xf bank_mask:0xf
	v_add_f32_e32 v142, v142, v143
	s_nop 1
	v_mov_b32_dpp v143, v142 row_ror:4 row_mask:0xf bank_mask:0xf
	v_add_f32_e32 v142, v142, v143
	s_nop 1
	v_mov_b32_dpp v143, v142 row_ror:2 row_mask:0xf bank_mask:0xf
	v_add_f32_e32 v142, v142, v143
	s_nop 1
	v_mov_b32_dpp v143, v142 row_ror:1 row_mask:0xf bank_mask:0xf
	v_add_f32_e32 v142, v142, v143
	v_add_u32_e32 v137, 0x1400, v133
	s_mov_b64 exec, s[10:11]
	global_store_dword v137, v142, s[8:9] offset:4
	s_mov_b64 exec, -1
	s_waitcnt vmcnt(58) lgkmcnt(4)
	v_lshlrev_b32_e32 v138, 16, v232
	v_and_b32_e32 v139, 0xffff0000, v232
	v_lshlrev_b32_e32 v140, 16, v233
	v_and_b32_e32 v141, 0xffff0000, v233
	v_pk_add_f32 v[14:15], v[14:15], v[138:139]
	v_pk_add_f32 v[16:17], v[16:17], v[140:141]
	v_cvt_pk_bf16_f32 v232, v14, v15
	v_cvt_pk_bf16_f32 v233, v16, v17
	v_add_u32_e32 v136, 0x58000, v132
	global_store_dwordx2 v136, v[232:233], s[6:7] offset:256
	v_and_b32_e32 v139, 0xffff0000, v232
	v_lshlrev_b32_e32 v138, 16, v232
	v_mul_f32_e32 v142, v139, v139
	v_lshlrev_b32_e32 v140, 16, v233
	v_fmac_f32_e32 v142, v138, v138
	v_and_b32_e32 v141, 0xffff0000, v233
	v_fmac_f32_e32 v142, v140, v140
	v_fmac_f32_e32 v142, v141, v141
	v_mov_b32_e32 v143, v142
	s_nop 1
	v_permlane16_swap_b32_e32 v143, v142
	v_add_f32_e32 v142, v142, v143
	s_nop 1
	v_mov_b32_dpp v143, v142 row_ror:8 row_mask:0xf bank_mask:0xf
	v_add_f32_e32 v142, v142, v143
	s_nop 1
	v_mov_b32_dpp v143, v142 row_ror:4 row_mask:0xf bank_mask:0xf
	v_add_f32_e32 v142, v142, v143
	s_nop 1
	v_mov_b32_dpp v143, v142 row_ror:2 row_mask:0xf bank_mask:0xf
	v_add_f32_e32 v142, v142, v143
	s_nop 1
	v_mov_b32_dpp v143, v142 row_ror:1 row_mask:0xf bank_mask:0xf
	v_add_f32_e32 v142, v142, v143
	v_add_u32_e32 v137, 0x1600, v133
	s_mov_b64 exec, s[10:11]
	global_store_dword v137, v142, s[8:9] offset:4
	s_mov_b64 exec, -1
	s_waitcnt vmcnt(59) lgkmcnt(3)
; DI unsigned pk2(float a, float b) { f32x2 v = {a, b}; bf2_t r = __builtin_convertvector(v, bf2_t); return __builtin_bit_cast(unsigned, r); }
; DI f32x4 unpk4(u32x2 u) { f32x4 r = {__uint_as_float(u[0] << 16), __uint_as_float(u[0] & 0xffff0000u), __uint_as_float(u[1] << 16), __uint_as_float(u[1] & 0xffff0000u)}; return r; }
; template <int MODE>
; DI void gemm_tile(const Params& p, const bf16_t* __restrict__ A, const bf16_t* __restrict__ Bt, int K, int brow, int bcol, int mp, int nt, bool vt, char* smem) {
;     ...
;           const int tok = m0 + bj * 128 + y, col = n0 + ai * 128 + x4;
;           const f32x4 xs = unpk4(xo[pq]) + v;
;           u32x2 o = {pk2(xs[0], xs[1]), pk2(xs[2], xs[3])};
;           *(u32x2*)((bf16_t*)(p.ws + OFF_XB) + (size_t)tok * DM + col) = o;
;           const f32x4 xn = unpk4(o);
;           float ss = xn[0] * xn[0] + xn[1] * xn[1] + xn[2] * xn[2] + xn[3] * xn[3];
; #pragma unroll
;           for (int o2 = 16; o2 > 0; o2 >>= 1) ss += __shfl_xor(ss, o2);
;           if ((tid & 31) == 0) ((float*)(p.ws + (MODE == MODE_OUT ? OFF_SSB : OFF_SSA)))[(size_t)tok * 8 + nt * 2 + ai] = ss;
	v_lshlrev_b32_e32 v138, 16, v234
	v_and_b32_e32 v139, 0xffff0000, v234
	v_lshlrev_b32_e32 v140, 16, v235
	v_and_b32_e32 v141, 0xffff0000, v235
	v_pk_add_f32 v[18:19], v[18:19], v[138:139]
	v_pk_add_f32 v[20:21], v[20:21], v[140:141]
	v_cvt_pk_bf16_f32 v234, v18, v19
	v_cvt_pk_bf16_f32 v235, v20, v21
	v_add_u32_e32 v136, 0x60000, v132
	global_store_dwordx2 v136, v[234:235], s[6:7] offset:256
	v_and_b32_e32 v139, 0xffff0000, v234
	v_lshlrev_b32_e32 v138, 16, v234
	v_mul_f32_e32 v142, v139, v139
	v_lshlrev_b32_e32 v140, 16, v235
	v_fmac_f32_e32 v142, v138, v138
	v_and_b32_e32 v141, 0xffff0000, v235
	v_fmac_f32_e32 v142, v140, v140
	v_fmac_f32_e32 v142, v141, v141
	v_mov_b32_e32 v143, v142
	s_nop 1
	v_permlane16_swap_b32_e32 v143, v142
	v_add_f32_e32 v142, v142, v143
	s_nop 1
	v_mov_b32_dpp v143, v142 row_ror:8 row_mask:0xf bank_mask:0xf
	v_add_f32_e32 v142, v142, v143
	s_nop 1
	v_mov_b32_dpp v143, v142 row_ror:4 row_mask:0xf bank_mask:0xf
	v_add_f32_e32 v142, v142, v143
	s_nop 1
	v_mov_b32_dpp v143, v142 row_ror:2 row_mask:0xf bank_mask:0xf
	v_add_f32_e32 v142, v142, v143
	s_nop 1
	v_mov_b32_dpp v143, v142 row_ror:1 row_mask:0xf bank_mask:0xf
	v_add_f32_e32 v142, v142, v143
	v_add_u32_e32 v137, 0x1800, v133
	s_mov_b64 exec, s[10:11]
	global_store_dword v137, v142, s[8:9] offset:4
	s_mov_b64 exec, -1
	s_waitcnt vmcnt(60) lgkmcnt(2)
	v_lshlrev_b32_e32 v138, 16, v236
	v_and_b32_e32 v139, 0xffff0000, v236
	v_lshlrev_b32_e32 v140, 16, v237
	v_and_b32_e32 v141, 0xffff0000, v237
	v_pk_add_f32 v[22:23], v[22:23], v[138:139]
	v_pk_add_f32 v[24:25], v[24:25], v[140:141]
	v_cvt_pk_bf16_f32 v236, v22, v23
	v_cvt_pk_bf16_f32 v237, v24, v25
	v_add_u32_e32 v136, 0x68000, v132
	global_store_dwordx2 v136, v[236:237], s[6:7] offset:256
	v_and_b32_e32 v139, 0xffff0000, v236
	v_lshlrev_b32_e32 v138, 16, v236
	v_mul_f32_e32 v142, v139, v139
	v_lshlrev_b32_e32 v140, 16, v237
	v_fmac_f32_e32 v142, v138, v138
	v_and_b32_e32 v141, 0xffff0000, v237
	v_fmac_f32_e32 v142, v140, v140
	v_fmac_f32_e32 v142, v141, v141
	v_mov_b32_e32 v143, v142
	s_nop 1
	v_permlane16_swap_b32_e32 v143, v142
	v_add_f32_e32 v142, v142, v143
	s_nop 1
	v_mov_b32_dpp v143, v142 row_ror:8 row_mask:0xf bank_mask:0xf
	v_add_f32_e32 v142, v142, v143
	s_nop 1
	v_mov_b32_dpp v143, v142 row_ror:4 row_mask:0xf bank_mask:0xf
	v_add_f32_e32 v142, v142, v143
	s_nop 1
	v_mov_b32_dpp v143, v142 row_ror:2 row_mask:0xf bank_mask:0xf
	v_add_f32_e32 v142, v142, v143
	s_nop 1
	v_mov_b32_dpp v143, v142 row_ror:1 row_mask:0xf bank_mask:0xf
	v_add_f32_e32 v142, v142, v143
	v_add_u32_e32 v137, 0x1a00, v133
	s_mov_b64 exec, s[10:11]
	global_store_dword v137, v142, s[8:9] offset:4
	s_mov_b64 exec, -1
	s_waitcnt vmcnt(61) lgkmcnt(1)
	v_lshlrev_b32_e32 v138, 16, v238
	v_and_b32_e32 v139, 0xffff0000, v238
	v_lshlrev_b32_e32 v140, 16, v239
	v_and_b32_e32 v141, 0xffff0000, v239
	v_pk_add_f32 v[26:27], v[26:27], v[138:139]
	v_pk_add_f32 v[28:29], v[28:29], v[140:141]
	v_cvt_pk_bf16_f32 v238, v26, v27
	v_cvt_pk_bf16_f32 v239, v28, v29
	v_add_u32_e32 v136, 0x70000, v132
	global_store_dwordx2 v136, v[238:239], s[6:7] offset:256
	v_and_b32_e32 v139, 0xffff0000, v238
	v_lshlrev_b32_e32 v138, 16, v238
	v_mul_f32_e32 v142, v139, v139
	v_lshlrev_b32_e32 v140, 16, v239
	v_fmac_f32_e32 v142, v138, v138
	v_and_b32_e32 v141, 0xffff0000, v239
	v_fmac_f32_e32 v142, v140, v140
	v_fmac_f32_e32 v142, v141, v141
	v_mov_b32_e32 v143, v142
	s_nop 1
	v_permlane16_swap_b32_e32 v143, v142
	v_add_f32_e32 v142, v142, v143
	s_nop 1
	v_mov_b32_dpp v143, v142 row_ror:8 row_mask:0xf bank_mask:0xf
	v_add_f32_e32 v142, v142, v143
	s_nop 1
	v_mov_b32_dpp v143, v142 row_ror:4 row_mask:0xf bank_mask:0xf
	v_add_f32_e32 v142, v142, v143
	s_nop 1
	v_mov_b32_dpp v143, v142 row_ror:2 row_mask:0xf bank_mask:0xf
	v_add_f32_e32 v142, v142, v143
	s_nop 1
	v_mov_b32_dpp v143, v142 row_ror:1 row_mask:0xf bank_mask:0xf
	v_add_f32_e32 v142, v142, v143
	v_add_u32_e32 v137, 0x1c00, v133
	s_mov_b64 exec, s[10:11]
	global_store_dword v137, v142, s[8:9] offset:4
	s_mov_b64 exec, -1
	s_waitcnt vmcnt(62) lgkmcnt(0)
	v_lshlrev_b32_e32 v138, 16, v240
	v_and_b32_e32 v139, 0xffff0000, v240
	v_lshlrev_b32_e32 v140, 16, v241
	v_and_b32_e32 v141, 0xffff0000, v241
	v_pk_add_f32 v[30:31], v[30:31], v[138:139]
	v_pk_add_f32 v[32:33], v[32:33], v[140:141]
	v_cvt_pk_bf16_f32 v240, v30, v31
	v_cvt_pk_bf16_f32 v241, v32, v33
	v_add_u32_e32 v136, 0x78000, v132
	global_store_dwordx2 v136, v[240:241], s[6:7] offset:256
	v_and_b32_e32 v139, 0xffff0000, v240
	v_lshlrev_b32_e32 v138, 16, v240
	v_mul_f32_e32 v142, v139, v139
	v_lshlrev_b32_e32 v140, 16, v241
	v_fmac_f32_e32 v142, v138, v138
	v_and_b32_e32 v141, 0xffff0000, v241
	v_fmac_f32_e32 v142, v140, v140
	v_fmac_f32_e32 v142, v141, v141
	v_mov_b32_e32 v143, v142
	s_nop 1
	v_permlane16_swap_b32_e32 v143, v142
	v_add_f32_e32 v142, v142, v143
	s_nop 1
	v_mov_b32_dpp v143, v142 row_ror:8 row_mask:0xf bank_mask:0xf
	v_add_f32_e32 v142, v142, v143
	s_nop 1
	v_mov_b32_dpp v143, v142 row_ror:4 row_mask:0xf bank_mask:0xf
	v_add_f32_e32 v142, v142, v143
	s_nop 1
	v_mov_b32_dpp v143, v142 row_ror:2 row_mask:0xf bank_mask:0xf
	v_add_f32_e32 v142, v142, v143
	s_nop 1
	v_mov_b32_dpp v143, v142 row_ror:1 row_mask:0xf bank_mask:0xf
	v_add_f32_e32 v142, v142, v143
	v_add_u32_e32 v137, 0x1e00, v133
	s_mov_b64 exec, s[10:11]
	global_store_dword v137, v142, s[8:9] offset:4
	s_mov_b64 exec, -1
	s_branch .LBB0_522

; __global__ void __launch_bounds__(512, 2) mega(Params p) {
;   __shared__ __attribute__((aligned(16))) char smem[163328];
	.amdhsa_kernel _Z4mega6Params
		.amdhsa_group_segment_fixed_size 163584
		.amdhsa_private_segment_fixed_size 0
		.amdhsa_kernarg_size 440
		.amdhsa_user_sgpr_count 2
		.amdhsa_user_sgpr_dispatch_ptr 0
		.amdhsa_user_sgpr_queue_ptr 0
		.amdhsa_user_sgpr_kernarg_segment_ptr 1
		.amdhsa_user_sgpr_dispatch_id 0
		.amdhsa_user_sgpr_kernarg_preload_length 0
		.amdhsa_user_sgpr_kernarg_preload_offset 0
		.amdhsa_user_sgpr_private_segment_size 0
		.amdhsa_uses_dynamic_stack 0
		.amdhsa_enable_private_segment 0
		.amdhsa_system_sgpr_workgroup_id_x 1
		.amdhsa_system_sgpr_workgroup_id_y 0
		.amdhsa_system_sgpr_workgroup_id_z 0
		.amdhsa_system_sgpr_workgroup_info 0
		.amdhsa_system_vgpr_workitem_id 2
		.amdhsa_next_free_vgpr 252
		.amdhsa_next_free_sgpr 100
		.amdhsa_accum_offset 252
		.amdhsa_reserve_vcc 1
		.amdhsa_float_round_mode_32 0
		.amdhsa_float_round_mode_16_64 0
		.amdhsa_float_denorm_mode_32 3
		.amdhsa_float_denorm_mode_16_64 3
		.amdhsa_dx10_clamp 1
		.amdhsa_ieee_mode 1
		.amdhsa_fp16_overflow 0
		.amdhsa_tg_split 0
		.amdhsa_exception_fp_ieee_invalid_op 0
		.amdhsa_exception_fp_denorm_src 0
		.amdhsa_exception_fp_ieee_div_zero 0
		.amdhsa_exception_fp_ieee_overflow 0
		.amdhsa_exception_fp_ieee_underflow 0
		.amdhsa_exception_fp_ieee_inexact 0
		.amdhsa_exception_int_div_zero 0
	.end_amdhsa_kernel

; __global__ void __launch_bounds__(512, 2) mega(Params p) {
;   __shared__ __attribute__((aligned(16))) char smem[163328];
amdhsa.kernels:
  - .agpr_count:     0
    .args:
      - .offset:         0
        .size:           184
        .value_kind:     by_value
      - .offset:         184
        .size:           4
        .value_kind:     hidden_block_count_x
      - .offset:         188
        .size:           4
        .value_kind:     hidden_block_count_y
      - .offset:         192
        .size:           4
        .value_kind:     hidden_block_count_z
      - .offset:         196
        .size:           2
        .value_kind:     hidden_group_size_x
      - .offset:         198
        .size:           2
        .value_kind:     hidden_group_size_y
      - .offset:         200
        .size:           2
        .value_kind:     hidden_group_size_z
      - .offset:         202
        .size:           2
        .value_kind:     hidden_remainder_x
      - .offset:         204
        .size:           2
        .value_kind:     hidden_remainder_y
      - .offset:         206
        .size:           2
        .value_kind:     hidden_remainder_z
      - .offset:         224
        .size:           8
        .value_kind:     hidden_global_offset_x
      - .offset:         232
        .size:           8
        .value_kind:     hidden_global_offset_y
      - .offset:         240
        .size:           8
        .value_kind:     hidden_global_offset_z
      - .offset:         248
        .size:           2
        .value_kind:     hidden_grid_dims
      - .offset:         272
        .size:           8
        .value_kind:     hidden_multigrid_sync_arg
    .group_segment_fixed_size: 163584
    .kernarg_segment_align: 8
    .kernarg_segment_size: 440
    .language:       OpenCL C
    .language_version:
      - 2
      - 0
    .max_flat_workgroup_size: 512
    .name:           _Z4mega6Params
    .private_segment_fixed_size: 0
    .sgpr_count:     106
    .sgpr_spill_count: 248
    .symbol:         _Z4mega6Params.kd
    .uniform_work_group_size: 1
    .uses_dynamic_stack: false
    .vgpr_count:     252
    .vgpr_spill_count: 0
    .wavefront_size: 64
